# one static s_setprio 1 for waves 4-7 (younger half) for the whole kernel, all per-segment s_setprio toggles in the GEMM K-loops deleted; on top of v34
# speedup vs baseline: 1.0018x; 1.0018x over previous
;     __device__ bool tile(int i, Unit& u) const {
;         const long L = (long)i * G + c; if (L >= nwg) return false;
;         int wgid = (int)L; { const int q = nwg / NXCD, r = nwg % NXCD, xcd = wgid % NXCD, off = wgid / NXCD; wgid = (xcd < r ? xcd * (q + 1) : r * (q + 1) + (xcd - r) * q) + off; }
;         const int nig = WGM * nN, gid = wgid / nig, fm = gid * WGM, gsz = (nM - fm) < WGM ? (nM - fm) : WGM;
;         u.pm = fm + ((wgid % nig) % gsz); u.pn = (wgid % nig) / gsz; return true;
;     }
; __global__ void __launch_bounds__(512) mk_fwd(Params p0) {
;     ...
;             pg8::Gemm g{XB, (const bf16_t*)(wb + WO_IN), DM, DM, DM};
;             small_proj(p, l, G, bx);
;             SchedPlain S; S.o.init(MP / 256, INW / 256, G, bx); S.tA = 256L * DM * 2; S.tB = 256L * DM * 2;
;             EpiProj E{PROJ, ssq + (2 * l) * MPAD, p.gate_bias + l * 2048};
;             pg8::gemm_phase(lds, g, S, E);
.LBB0_140:
	v_writelane_b32 v248, s18, 44
	s_nop 1
	v_writelane_b32 v248, s19, 45
	v_writelane_b32 v248, s30, 46
	s_nop 1
	v_writelane_b32 v248, s31, 47
	v_writelane_b32 v248, s28, 48
	s_nop 1
	v_writelane_b32 v248, s29, 49
	s_or_b64 exec, exec, s[0:1]
	s_not_b32 s0, s81
	s_add_i32 s20, s92, s0
	s_cmpk_lt_i32 s20, 0x68
	s_cselect_b64 s[0:1], -1, 0
	v_writelane_b32 v248, s0, 50
	s_cmpk_lt_i32 s81, 0x680
	s_movk_i32 s15, 0xd1
	v_writelane_b32 v248, s1, 51
	s_cselect_b64 s[0:1], -1, 0
	v_writelane_b32 v248, s0, 52
	s_ashr_i32 s3, s81, 31
	s_ashr_i32 s5, s92, 31
	v_writelane_b32 v248, s1, 53
	s_lshr_b32 s0, s3, 29
	v_writelane_b32 v248, s36, 54
	s_add_i32 s0, s81, s0
	s_ashr_i32 s7, s0, 3
	v_writelane_b32 v247, s46, 0
	v_writelane_b32 v247, s47, 1
	s_and_b32 s0, s0, -8
	v_writelane_b32 v247, s48, 2
	s_sub_i32 s8, s81, s0
	v_writelane_b32 v247, s49, 3
	v_writelane_b32 v247, s50, 4
	s_cmp_lg_u64 s[38:39], 0
	v_writelane_b32 v247, s51, 5
	s_cselect_b64 s[0:1], -1, 0
	v_writelane_b32 v247, s0, 6
	s_and_b32 s9, s92, 7
	v_mov_b64_e32 v[194:195], 0x200
	v_writelane_b32 v247, s1, 7
	s_ashr_i32 s0, s92, 3
	s_mul_i32 s0, s0, s8
	s_add_i32 s10, s0, s7
	s_cmp_lt_i32 s92, 17
	s_cselect_b64 s[0:1], -1, 0
	s_add_i32 s11, s6, 0xffffff80
	s_cmp_lt_i32 s20, 32
	s_cselect_b64 s[12:13], -1, 0
	v_writelane_b32 v247, s12, 8
	s_cmpk_lt_i32 s81, 0x200
	v_writelane_b32 v248, s37, 55
	v_writelane_b32 v247, s13, 9
	s_cselect_b64 s[12:13], -1, 0
	s_lshl_b32 s4, s8, 6
	v_writelane_b32 v247, s12, 10
	s_cmpk_lt_i32 s20, 0x58
	v_writelane_b32 v248, s38, 56
	v_writelane_b32 v247, s13, 11
	s_cselect_b64 s[12:13], -1, 0
	v_writelane_b32 v247, s12, 12
	s_cmpk_lt_i32 s81, 0xb00
	v_writelane_b32 v248, s39, 57
	v_writelane_b32 v247, s13, 13
	s_cselect_b64 s[12:13], -1, 0
	v_writelane_b32 v247, s12, 14
	s_add_u32 s2, s92, s81
	v_writelane_b32 v248, s40, 58
	v_writelane_b32 v247, s13, 15
	v_writelane_b32 v247, s3, 16
	v_writelane_b32 v247, s5, 17
	s_addc_u32 s3, s5, s3
	s_ashr_i32 s5, s2, 31
	s_lshr_b32 s5, s5, 29
	s_add_i32 s5, s2, s5
	s_ashr_i32 s12, s5, 3
	s_and_b32 s5, s5, -8
	s_sub_i32 s13, s2, s5
	s_lshl_b32 s14, s13, 6
	s_cmp_lt_i32 s8, 0
	s_mul_i32 s5, s8, 0x41
	s_cselect_b32 s15, s15, 0xd0
	s_mul_i32 s15, s8, s15
	s_cselect_b32 s16, s5, s4
	s_movk_i32 s4, 0x161
	s_cselect_b32 s17, s4, 0x160
	s_add_i32 s15, s15, s7
	s_mul_hi_i32 s4, s15, 0x4ec4ec4f
	s_lshr_b32 s5, s4, 31
	s_ashr_i32 s4, s4, 5
	s_add_i32 s4, s4, s5
	s_mul_i32 s5, s4, 0x68
	s_sub_i32 s5, s15, s5
	s_lshl_b32 s18, s4, 3
	s_bfe_i32 s4, s5, 0x80000
	s_bfe_u32 s4, s4, 0x3000c
	s_add_i32 s15, s5, s4
	s_bfe_i32 s4, s15, 0x80000
	s_and_b32 s15, s15, 0xf8
	s_sub_i32 s5, s5, s15
	s_sext_i32_i16 s19, s4
	s_sext_i32_i8 s5, s5
	s_add_i32 s22, s18, s5
	s_ashr_i32 s5, s19, 3
	s_lshr_b32 s4, s19, 3
	v_writelane_b32 v247, s5, 18
	s_mov_b32 s18, s22
	s_ashr_i32 s23, s22, 31
	v_writelane_b32 v247, s18, 19
	s_bfe_i64 s[4:5], s[4:5], 0x100000
	s_lshl_b64 s[4:5], s[4:5], 19
	v_writelane_b32 v247, s19, 20
	s_lshl_b64 s[18:19], s[22:23], 19
	v_writelane_b32 v247, s18, 21
	s_cmp_eq_u32 s9, 0
	s_cselect_b32 s10, s10, s81
	v_writelane_b32 v247, s19, 22
	v_writelane_b32 v247, s4, 23
	s_cmpk_lt_i32 s10, 0x110
	v_cmp_lt_i64_e64 s[2:3], s[2:3], v[194:195]
	v_writelane_b32 v247, s5, 24
	s_cselect_b64 s[4:5], -1, 0
	v_writelane_b32 v247, s4, 25
	s_cmp_gt_i32 s10, 15
	v_writelane_b32 v248, s41, 59
	v_writelane_b32 v247, s5, 26
	s_cselect_b64 s[4:5], -1, 0
	s_or_b64 s[0:1], s[0:1], s[4:5]
	v_writelane_b32 v247, s0, 27
	v_writelane_b32 v248, s42, 60
	v_writelane_b32 v248, s43, 61
	v_writelane_b32 v247, s1, 28
	s_lshl_b32 s0, s10, 3
	s_add_i32 s1, s0, 0xffffff80
	s_cmp_gt_i32 s92, 16
	v_writelane_b32 v247, s2, 29
	s_cselect_b32 s0, s1, s0
	s_cselect_b32 s29, s11, s6
	v_writelane_b32 v247, s3, 30
	v_writelane_b32 v247, s0, 31
	s_add_i32 s0, s16, s7
	s_ashr_i32 s1, s0, 31
	s_lshr_b32 s1, s1, 27
	s_add_i32 s1, s0, s1
	s_ashr_i32 s2, s1, 5
	s_andn2_b32 s1, s1, 31
	s_sub_i32 s4, s0, s1
	s_bfe_i32 s0, s4, 0x80000
	s_bfe_u32 s0, s0, 0x3000c
	s_add_i32 s1, s4, s0
	s_bfe_i32 s0, s1, 0x80000
	s_and_b32 s1, s1, 0xf8
	s_sub_i32 s1, s4, s1
	s_lshl_b32 s3, s2, 3
	s_sext_i32_i8 s1, s1
	s_add_i32 s16, s3, s1
	s_mul_i32 s1, s8, s17
	s_sext_i32_i16 s2, s0
	s_add_i32 s1, s1, s7
	s_lshr_b32 s0, s2, 3
	s_ashr_i32 s11, s2, 3
	s_mul_hi_i32 s2, s1, 0x2e8ba2e9
	s_lshr_b32 s5, s2, 31
	s_ashr_i32 s2, s2, 5
	s_add_i32 s2, s2, s5
	s_lshl_b32 s5, s2, 3
	s_mulk_i32 s2, 0xb0
	s_sub_i32 s1, s1, s2
	s_bfe_u32 s2, s1, 0x3001c
	s_add_i32 s6, s1, s2
	s_sext_i32_i16 s7, s6
	s_and_b32 s6, s6, 0xfff8
	s_sub_i32 s1, s1, s6
	s_sext_i32_i16 s1, s1
	s_add_i32 s18, s5, s1
	s_ashr_i32 s1, s7, 3
	v_writelane_b32 v247, s1, 32
	s_sub_i32 s1, 0x80, s3
	s_lshr_b32 s2, s7, 3
	s_min_i32 s5, s1, 8
	s_cmp_lt_i32 s13, 0
	s_mulk_i32 s13, 0x41
	s_cselect_b32 s1, s13, s14
	s_add_i32 s1, s1, s12
	s_ashr_i32 s6, s1, 31
	s_lshr_b32 s6, s6, 27
	s_add_i32 s6, s1, s6
	s_ashr_i32 s17, s16, 31
	s_abs_i32 s9, s92
	s_ashr_i32 s7, s6, 5
	s_andn2_b32 s6, s6, 31
	s_waitcnt lgkmcnt(0)
; #define LAS __attribute__((address_space(3)))
; __device__ __forceinline__ void convert_weights_idle(const Params& p, LAS unsigned char* lds, int first, int last, int nwg, int G, int bx) {
;     int tid = threadIdx.x; asm volatile("" : "+v"(tid));
;     const int rem = nwg % G, wid = __builtin_amdgcn_readfirstlane(tid >> 6);
;     if (bx >= rem) convert_weights(p, lds, first, last, (bx - rem) * 8 + wid, (G - rem) * 8);
; }
	v_cvt_f32_u32_e32 v0, s9
	s_lshl_b64 s[12:13], s[16:17], 19
	s_sub_i32 s6, s1, s6
	s_bfe_i64 s[0:1], s[0:1], 0x100000
	v_writelane_b32 v247, s12, 33
	v_rcp_iflag_f32_e32 v0, v0
	s_ashr_i32 s19, s18, 31
	v_writelane_b32 v247, s13, 34
	s_lshl_b64 s[12:13], s[0:1], 18
	v_writelane_b32 v247, s12, 35
	s_lshl_b64 s[0:1], s[0:1], 19
	v_mul_f32_e32 v0, 0x4f7ffffe, v0
	v_writelane_b32 v247, s13, 36
	v_writelane_b32 v247, s0, 37
	v_cvt_u32_f32_e32 v0, v0
	s_lshl_b32 s7, s7, 3
	v_writelane_b32 v247, s1, 38
	s_mov_b32 s0, s18
	v_writelane_b32 v247, s0, 39
	s_sub_i32 s8, 0x80, s7
	s_min_i32 s8, s8, 8
	v_writelane_b32 v247, s1, 40
	s_lshl_b64 s[0:1], s[18:19], 19
	v_writelane_b32 v247, s0, 41
	s_mov_b32 s93, 0
	v_writelane_b32 v248, s44, 62
	v_writelane_b32 v247, s1, 42
	s_bfe_i64 s[0:1], s[2:3], 0x100000
	s_lshl_b64 s[0:1], s[0:1], 19
	v_writelane_b32 v247, s0, 43
	s_mul_hi_i32 s2, s16, 0x160000
	s_movk_i32 s31, 0x80
	v_writelane_b32 v247, s1, 44
	s_sub_i32 s0, 0, s9
	v_readfirstlane_b32 s1, v0
	s_mul_i32 s0, s0, s1
	s_mul_hi_u32 s0, s1, s0
	s_add_i32 s1, s1, s0
	s_mul_hi_u32 s0, s1, 0x680
	s_mul_i32 s0, s0, s9
	s_sub_i32 s0, 0x680, s0
	s_sub_i32 s1, s0, s9
	s_cmp_ge_u32 s0, s9
	s_cselect_b32 s0, s1, s0
	s_sub_i32 s1, s0, s9
	s_cmp_ge_u32 s0, s9
	s_cselect_b32 s0, s1, s0
	s_cmp_ge_i32 s81, s0
	s_cselect_b64 s[12:13], -1, 0
	s_abs_i32 s1, s5
	v_cvt_f32_u32_e32 v0, s1
	v_writelane_b32 v247, s12, 45
	v_mov_b32_e32 v97, 0
	v_mov_b32_e32 v223, 0x358637bd
	v_rcp_iflag_f32_e32 v0, v0
	v_writelane_b32 v247, s13, 46
	v_writelane_b32 v247, s2, 47
	s_sub_i32 s2, s81, s0
	v_mul_f32_e32 v0, 0x4f7ffffe, v0
	v_cvt_u32_f32_e32 v0, v0
	s_lshl_b32 s2, s2, 3
	s_sub_i32 s0, s92, s0
	v_writelane_b32 v247, s2, 48
	s_lshl_b32 s0, s0, 3
	v_writelane_b32 v247, s0, 49
	s_ashr_i32 s0, s4, 31
	s_abs_i32 s2, s4
	s_sub_i32 s4, 0, s1
	v_readfirstlane_b32 s5, v0
	s_mul_i32 s4, s4, s5
	s_mul_hi_u32 s4, s5, s4
	s_add_i32 s5, s5, s4
	s_mul_hi_u32 s4, s2, s5
	s_mul_i32 s4, s4, s1
	s_sub_i32 s2, s2, s4
	s_sub_i32 s4, s2, s1
	s_cmp_ge_u32 s2, s1
	s_cselect_b32 s2, s4, s2
	s_sub_i32 s4, s2, s1
	s_cmp_ge_u32 s2, s1
	s_cselect_b32 s1, s4, s2
	s_abs_i32 s2, s8
	v_cvt_f32_u32_e32 v0, s2
	s_mov_b32 s4, s16
	v_writelane_b32 v247, s4, 50
	s_xor_b32 s1, s1, s0
	v_rcp_iflag_f32_e32 v0, v0
	v_writelane_b32 v247, s5, 51
	s_mul_i32 s4, s16, 0x160000
	v_writelane_b32 v247, s4, 52
	v_mul_f32_e32 v0, 0x4f7ffffe, v0
	v_cvt_u32_f32_e32 v0, v0
	s_mul_hi_i32 s4, s11, 0x160000
	v_writelane_b32 v247, s4, 53
	v_writelane_b32 v247, s11, 54
	s_mul_i32 s4, s11, 0x160000
	s_sub_i32 s0, s1, s0
	v_writelane_b32 v247, s4, 55
	s_add_i32 s0, s3, s0
	s_sub_i32 s3, 0, s2
	v_readfirstlane_b32 s4, v0
	s_mul_i32 s3, s3, s4
	s_mul_hi_u32 s3, s4, s3
	s_abs_i32 s1, s6
	s_add_i32 s4, s4, s3
	s_mul_hi_u32 s3, s1, s4
	s_mul_i32 s3, s3, s2
	s_sub_i32 s1, s1, s3
	v_writelane_b32 v247, s0, 56
	s_ashr_i32 s0, s6, 31
	s_sub_i32 s3, s1, s2
	s_cmp_ge_u32 s1, s2
	s_cselect_b32 s1, s3, s1
	s_sub_i32 s3, s1, s2
	s_cmp_ge_u32 s1, s2
	s_cselect_b32 s1, s3, s1
	s_xor_b32 s1, s1, s0
	s_sub_i32 s0, s1, s0
	s_add_i32 s0, s7, s0
	v_writelane_b32 v247, s0, 57
	s_lshl_b32 s37, s92, 5
	s_lshl_b32 s0, s81, 5
	s_sub_i32 s0, s37, s0
	s_add_i32 s1, s0, -16
	v_writelane_b32 v247, s1, 58
	s_sub_i32 s0, s0, 32
	v_writelane_b32 v247, s0, 59
	s_add_i32 s0, s10, 48
	v_writelane_b32 v247, s0, 60
	v_writelane_b32 v247, s10, 61
	s_add_i32 s0, s10, -16
	v_writelane_b32 v247, s0, 62
	s_lshl_b32 s0, s20, 6
	v_writelane_b32 v247, s0, 63
	s_lshl_b32 s0, s92, 6
	v_writelane_b32 v246, s0, 0
	v_writelane_b32 v246, s20, 1
	s_lshl_b32 s0, s20, 5
	v_writelane_b32 v246, s0, 2
	s_add_i32 s0, 0, 0x23fc0
	v_writelane_b32 v246, s0, 3
	s_add_i32 s0, 0, 0x23fc4
	v_writelane_b32 v246, s0, 4
	v_writelane_b32 v246, s33, 5
	v_writelane_b32 v246, s29, 6
	v_writelane_b32 v246, s37, 7
	v_writelane_b32 v246, s81, 8
	v_mov_b32_e32 v224, 1
	v_mbcnt_hi_u32_b32 v225, -1, v68
	v_mov_b64_e32 v[196:197], 0x680
	v_mov_b64_e32 v[198:199], 0x67f
	v_mov_b32_e32 v226, 0xf149f2ca
	v_mov_b32_e32 v227, 0x1a00
	v_bfrev_b32_e32 v228, 32
	v_mov_b64_e32 v[200:201], 0x1ff
	v_mov_b64_e32 v[202:203], 0xb00
	v_mov_b64_e32 v[204:205], 0xaff
	s_movk_i32 s89, 0x1a00
	s_mov_b32 s35, 0x7838000
	s_mov_b32 s26, 0xb80000
	s_mov_b32 s88, 0xb88000
	s_mov_b32 s97, 0
	s_mov_b64 s[38:39], 0x200
	s_mov_b64 s[94:95], -1
	s_mov_b64 s[4:5], 0x80
	s_mov_b32 s6, 0x3e6d3388
	s_mov_b32 s24, 0x3f07dc22
	s_mov_b32 s28, 0x3f35f0e3
	s_mov_b32 s30, 0xbe11a98e
	s_mov_b32 s34, 0x3e027906
	s_mov_b32 s36, 0xbf38aa3b
	v_writelane_b32 v246, s92, 9
	s_barrier
	v_writelane_b32 v248, s45, 63
	v_writelane_b32 v246, s93, 10
	v_readfirstlane_b32 s32, v222
	s_nop 3
	s_lshr_b32 s32, s32, 6
	s_cmp_ge_u32 s32, 4
	s_cbranch_scc0 .Lmy_prio_done
	s_setprio 1
.Lmy_prio_done:
	s_branch .LBB0_144
.LBB0_141:
	s_or_b64 exec, exec, s[8:9]
	s_waitcnt vmcnt(0)

; #define PG8_STAGE(bufoff, gbase, voff) do { _Pragma("unroll") for (int _i = 0; _i < 2; ++_i) \
;         __builtin_amdgcn_global_load_lds((const unsigned*)((const char*)(gbase) + (voff)[_i]), (LAS unsigned*)(lds + (bufoff) + ldsw + _i * 8192), 16, 0, 0); } while (0)
; #define PG8_LDA(dst, b, h) do { _Pragma("unroll") for (int m = 0; m < 4; ++m) _Pragma("unroll") for (int k = 0; k < 2; ++k) dst[m][k] = *(const LAS bf16x8*)(lds + PG8_SA(b, h) + aoff + m * 2048 + k * 1024); } while (0)
; #define PG8_LDB(dst, b, h) do { _Pragma("unroll") for (int n = 0; n < 2; ++n) _Pragma("unroll") for (int k = 0; k < 2; ++k) dst[n][k] = *(const LAS bf16x8*)(lds + PG8_SB(b, h) + boff + n * 2048 + k * 1024); } while (0)
; #define PG8_MMA(ai, bj, At, Bt) do { __builtin_amdgcn_s_setprio(1); _Pragma("unroll") for (int m = 0; m < 4; ++m) _Pragma("unroll") for (int n = 0; n < 2; ++n) _Pragma("unroll") for (int k = 0; k < 2; ++k) \
;         acc[ai][bj][m][n] = __builtin_amdgcn_mfma_f32_16x16x32_bf16(Bt[n][k], At[m][k], acc[ai][bj][m][n], 0, 0, 0); __builtin_amdgcn_s_setprio(0); } while (0)
; #define PG8_WAIT_V(n) asm volatile("s_waitcnt vmcnt(" #n ")" ::: "memory")
; #define PG8_WAIT_L(n) asm volatile("s_waitcnt lgkmcnt(" #n ")" ::: "memory")
; #define PG8_BAR __builtin_amdgcn_s_barrier()
; #define PG8_SCHED __builtin_amdgcn_sched_barrier(0)
; template <class Epi, class Sched>
; __device__ __forceinline__ void gemm_phase(LAS unsigned char* lds, const Gemm g, const Sched& S, const Epi& E) {
;     ...
;         for (int t = 0; t < nt; t += 2) {
;             const bool last = (t == nt - 2);
;             const char* a1 = cA + (size_t)(t + 1) * kstep;
;             const char* a2 = last ? nA : cA + (size_t)(t + 2) * kstep; const char* b2 = last ? nB : cB + (size_t)(t + 2) * kstep;
;             const char* a3 = a2 + kstep; const char* b3 = b2 + kstep;
;             PG8_LDB(B0, 0, 0); PG8_LDB(B1, 0, 1); PG8_SCHED; PG8_LDA(At, 0, 0); PG8_STAGE(PG8_SA(1, 1), a1 + hstepA, voffA);
;             PG8_WAIT_V(8); PG8_WAIT_L(0); PG8_BAR; PG8_MMA(0, 0, At, B0); PG8_MMA(0, 1, At, B1); PG8_BAR; PG8_SCHED;
;             PG8_LDA(At, 0, 1); PG8_STAGE(PG8_SB(0, 0), b2, voffB); PG8_STAGE(PG8_SB(0, 1), b2 + hstepB, voffB); PG8_STAGE(PG8_SA(0, 0), a2, voffA);
;             PG8_WAIT_V(8); PG8_WAIT_L(0); PG8_BAR; PG8_MMA(1, 0, At, B0); PG8_MMA(1, 1, At, B1); PG8_BAR; PG8_SCHED;
.LBB0_174:
	s_add_u32 s20, s0, 0xfffc0080
	s_addc_u32 s21, s1, -1
	s_add_i32 s56, 0, 0x10000
	s_cmp_eq_u32 s55, 12
	s_cselect_b32 s23, s15, s21
	s_cselect_b32 s22, s42, s20
	s_cselect_b32 s21, s13, s54
	s_cselect_b32 s20, s43, s51
	s_add_i32 s58, 0, 0x14000
	v_add_u32_e32 v52, s56, v164
	v_add_u32_e32 v160, s58, v164
	ds_read_b128 v[32:35], v52
	ds_read_b128 v[40:43], v52 offset:1024
	ds_read_b128 v[44:47], v52 offset:2048
	ds_read_b128 v[52:55], v52 offset:3072
	ds_read_b128 v[156:159], v160
	ds_read_b128 v[166:169], v160 offset:1024
	ds_read_b128 v[170:173], v160 offset:2048
	ds_read_b128 v[174:177], v160 offset:3072
	v_lshl_add_u64 v[160:161], s[0:1], 0, v[154:155]
	s_add_i32 m0, s25, 0xc000
	ds_read_b128 v[178:181], v165
	ds_read_b128 v[182:185], v165 offset:1024
	ds_read_b128 v[186:189], v165 offset:2048
	ds_read_b128 v[190:193], v165 offset:3072
	ds_read_b128 v[206:209], v165 offset:4096
	ds_read_b128 v[210:213], v165 offset:5120
	ds_read_b128 v[214:217], v165 offset:6144
	ds_read_b128 v[218:221], v165 offset:7168
	global_load_lds_dwordx4 v[160:161], off
	v_lshl_add_u64 v[160:161], s[0:1], 0, v[152:153]
	s_add_i32 m0, s25, 0xe000
	s_nop 0
	global_load_lds_dwordx4 v[160:161], off
	s_waitcnt vmcnt(8)
	s_waitcnt lgkmcnt(0)
	s_barrier
	s_waitcnt lgkmcnt(0)
	v_mfma_f32_16x16x32_bf16 v[142:145], v[32:35], v[178:181], v[142:145]
	v_mfma_f32_16x16x32_bf16 v[138:141], v[44:47], v[178:181], v[138:141]
	v_mfma_f32_16x16x32_bf16 v[126:129], v[32:35], v[186:189], v[126:129]
	v_mfma_f32_16x16x32_bf16 v[122:125], v[44:47], v[186:189], v[122:125]
	v_mfma_f32_16x16x32_bf16 v[110:113], v[32:35], v[206:209], v[110:113]
	v_mfma_f32_16x16x32_bf16 v[106:109], v[44:47], v[206:209], v[106:109]
	v_mfma_f32_16x16x32_bf16 v[92:95], v[32:35], v[214:217], v[92:95]
	v_mfma_f32_16x16x32_bf16 v[88:91], v[44:47], v[214:217], v[88:91]
	v_mfma_f32_16x16x32_bf16 v[142:145], v[40:43], v[182:185], v[142:145]
	v_mfma_f32_16x16x32_bf16 v[138:141], v[52:55], v[182:185], v[138:141]
	v_mfma_f32_16x16x32_bf16 v[126:129], v[40:43], v[190:193], v[126:129]
	v_mfma_f32_16x16x32_bf16 v[122:125], v[52:55], v[190:193], v[122:125]
	v_mfma_f32_16x16x32_bf16 v[110:113], v[40:43], v[210:213], v[110:113]
	v_mfma_f32_16x16x32_bf16 v[106:109], v[52:55], v[210:213], v[106:109]
	v_mfma_f32_16x16x32_bf16 v[92:95], v[40:43], v[218:221], v[92:95]
	v_mfma_f32_16x16x32_bf16 v[88:91], v[52:55], v[218:221], v[88:91]
	v_mfma_f32_16x16x32_bf16 v[134:137], v[156:159], v[178:181], v[134:137]
	v_mfma_f32_16x16x32_bf16 v[130:133], v[170:173], v[178:181], v[130:133]
	v_mfma_f32_16x16x32_bf16 v[118:121], v[156:159], v[186:189], v[118:121]
	v_mfma_f32_16x16x32_bf16 v[114:117], v[170:173], v[186:189], v[114:117]
	v_mfma_f32_16x16x32_bf16 v[102:105], v[156:159], v[206:209], v[102:105]
	v_mfma_f32_16x16x32_bf16 v[98:101], v[170:173], v[206:209], v[98:101]
	v_mfma_f32_16x16x32_bf16 v[84:87], v[156:159], v[214:217], v[84:87]
	v_mfma_f32_16x16x32_bf16 v[80:83], v[170:173], v[214:217], v[80:83]
	v_mfma_f32_16x16x32_bf16 v[134:137], v[166:169], v[182:185], v[134:137]
	v_mfma_f32_16x16x32_bf16 v[130:133], v[174:177], v[182:185], v[130:133]
	v_mfma_f32_16x16x32_bf16 v[118:121], v[166:169], v[190:193], v[118:121]
	v_mfma_f32_16x16x32_bf16 v[114:117], v[174:177], v[190:193], v[114:117]
	v_mfma_f32_16x16x32_bf16 v[102:105], v[166:169], v[210:213], v[102:105]
	v_mfma_f32_16x16x32_bf16 v[98:101], v[174:177], v[210:213], v[98:101]
	v_mfma_f32_16x16x32_bf16 v[84:87], v[166:169], v[218:221], v[84:87]
	v_mfma_f32_16x16x32_bf16 v[80:83], v[174:177], v[218:221], v[80:83]
	s_barrier
	s_add_i32 s56, s56, s7
	v_lshl_add_u64 v[160:161], s[20:21], 0, v[96:97]
	s_mov_b32 m0, s56
	ds_read_b128 v[178:181], v165 offset:16384
	ds_read_b128 v[182:185], v165 offset:17408
	ds_read_b128 v[186:189], v165 offset:18432
	ds_read_b128 v[190:193], v165 offset:19456
	ds_read_b128 v[206:209], v165 offset:20480
	ds_read_b128 v[210:213], v165 offset:21504
	ds_read_b128 v[214:217], v165 offset:22528
	ds_read_b128 v[218:221], v165 offset:23552
	global_load_lds_dwordx4 v[160:161], off
	s_add_i32 m0, s56, 0x2000
	s_add_u32 s56, s20, 0x40000
	v_lshl_add_u64 v[230:231], s[20:21], 0, v[146:147]
	s_addc_u32 s57, s21, 0
	s_add_i32 s58, s58, s7
	global_load_lds_dwordx4 v[230:231], off
	v_lshl_add_u64 v[232:233], s[56:57], 0, v[96:97]
	s_mov_b32 m0, s58
	v_lshl_add_u64 v[234:235], s[22:23], 0, v[148:149]
	global_load_lds_dwordx4 v[232:233], off
	v_lshl_add_u64 v[232:233], s[56:57], 0, v[146:147]
	s_add_i32 m0, s58, 0x2000
	s_nop 0
	global_load_lds_dwordx4 v[232:233], off
	v_lshl_add_u64 v[232:233], s[22:23], 0, v[150:151]
	s_mov_b32 m0, s25
	s_nop 0
	global_load_lds_dwordx4 v[232:233], off
	s_mov_b32 m0, s27
	s_nop 0
	global_load_lds_dwordx4 v[234:235], off
	s_waitcnt vmcnt(8)
	s_waitcnt lgkmcnt(0)
	s_barrier
; #define PG8_STAGE(bufoff, gbase, voff) do { _Pragma("unroll") for (int _i = 0; _i < 2; ++_i) \
;         __builtin_amdgcn_global_load_lds((const unsigned*)((const char*)(gbase) + (voff)[_i]), (LAS unsigned*)(lds + (bufoff) + ldsw + _i * 8192), 16, 0, 0); } while (0)
; #define PG8_LDA(dst, b, h) do { _Pragma("unroll") for (int m = 0; m < 4; ++m) _Pragma("unroll") for (int k = 0; k < 2; ++k) dst[m][k] = *(const LAS bf16x8*)(lds + PG8_SA(b, h) + aoff + m * 2048 + k * 1024); } while (0)
; #define PG8_LDB(dst, b, h) do { _Pragma("unroll") for (int n = 0; n < 2; ++n) _Pragma("unroll") for (int k = 0; k < 2; ++k) dst[n][k] = *(const LAS bf16x8*)(lds + PG8_SB(b, h) + boff + n * 2048 + k * 1024); } while (0)
; #define PG8_MMA(ai, bj, At, Bt) do { __builtin_amdgcn_s_setprio(1); _Pragma("unroll") for (int m = 0; m < 4; ++m) _Pragma("unroll") for (int n = 0; n < 2; ++n) _Pragma("unroll") for (int k = 0; k < 2; ++k) \
;         acc[ai][bj][m][n] = __builtin_amdgcn_mfma_f32_16x16x32_bf16(Bt[n][k], At[m][k], acc[ai][bj][m][n], 0, 0, 0); __builtin_amdgcn_s_setprio(0); } while (0)
; #define PG8_WAIT_V(n) asm volatile("s_waitcnt vmcnt(" #n ")" ::: "memory")
; #define PG8_WAIT_L(n) asm volatile("s_waitcnt lgkmcnt(" #n ")" ::: "memory")
; #define PG8_BAR __builtin_amdgcn_s_barrier()
; #define PG8_SCHED __builtin_amdgcn_sched_barrier(0)
; template <class Epi, class Sched>
; __device__ __forceinline__ void gemm_phase(LAS unsigned char* lds, const Gemm g, const Sched& S, const Epi& E) {
;     ...
;             PG8_LDA(At, 0, 1); PG8_STAGE(PG8_SB(0, 0), b2, voffB); PG8_STAGE(PG8_SB(0, 1), b2 + hstepB, voffB); PG8_STAGE(PG8_SA(0, 0), a2, voffA);
;             PG8_WAIT_V(8); PG8_WAIT_L(0); PG8_BAR; PG8_MMA(1, 0, At, B0); PG8_MMA(1, 1, At, B1); PG8_BAR; PG8_SCHED;
;             PG8_LDB(B0, 1, 0); PG8_LDB(B1, 1, 1); PG8_SCHED; PG8_LDA(At, 1, 0); PG8_STAGE(PG8_SA(0, 1), a2 + hstepA, voffA);
;             PG8_WAIT_V(8); PG8_WAIT_L(0); PG8_BAR; PG8_MMA(0, 0, At, B0); PG8_MMA(0, 1, At, B1); PG8_BAR; PG8_SCHED;
;             PG8_LDA(At, 1, 1); PG8_STAGE(PG8_SB(1, 0), b3, voffB); PG8_STAGE(PG8_SB(1, 1), b3 + hstepB, voffB); PG8_STAGE(PG8_SA(1, 0), a3, voffA);
	s_waitcnt lgkmcnt(0)
	v_mfma_f32_16x16x32_bf16 v[76:79], v[32:35], v[178:181], v[76:79]
	v_mfma_f32_16x16x32_bf16 v[72:75], v[44:47], v[178:181], v[72:75]
	v_mfma_f32_16x16x32_bf16 v[60:63], v[32:35], v[186:189], v[60:63]
	v_mfma_f32_16x16x32_bf16 v[56:59], v[44:47], v[186:189], v[56:59]
	v_mfma_f32_16x16x32_bf16 v[28:31], v[32:35], v[206:209], v[28:31]
	v_mfma_f32_16x16x32_bf16 v[24:27], v[44:47], v[206:209], v[24:27]
	v_mfma_f32_16x16x32_bf16 v[12:15], v[32:35], v[214:217], v[12:15]
	v_mfma_f32_16x16x32_bf16 v[8:11], v[44:47], v[214:217], v[8:11]
	v_mfma_f32_16x16x32_bf16 v[76:79], v[40:43], v[182:185], v[76:79]
	v_mfma_f32_16x16x32_bf16 v[72:75], v[52:55], v[182:185], v[72:75]
	v_mfma_f32_16x16x32_bf16 v[60:63], v[40:43], v[190:193], v[60:63]
	v_mfma_f32_16x16x32_bf16 v[56:59], v[52:55], v[190:193], v[56:59]
	v_mfma_f32_16x16x32_bf16 v[28:31], v[40:43], v[210:213], v[28:31]
	v_mfma_f32_16x16x32_bf16 v[24:27], v[52:55], v[210:213], v[24:27]
	v_mfma_f32_16x16x32_bf16 v[12:15], v[40:43], v[218:221], v[12:15]
	v_mfma_f32_16x16x32_bf16 v[8:11], v[52:55], v[218:221], v[8:11]
	v_mfma_f32_16x16x32_bf16 v[36:39], v[170:173], v[186:189], v[36:39]
	v_mfma_f32_16x16x32_bf16 v[20:23], v[156:159], v[206:209], v[20:23]
	v_mfma_f32_16x16x32_bf16 v[16:19], v[170:173], v[206:209], v[16:19]
	v_mfma_f32_16x16x32_bf16 v[4:7], v[156:159], v[214:217], v[4:7]
	v_mfma_f32_16x16x32_bf16 v[0:3], v[170:173], v[214:217], v[0:3]
	v_mfma_f32_16x16x32_bf16 v[32:35], v[156:159], v[178:181], v[68:71]
	v_mfma_f32_16x16x32_bf16 v[40:43], v[170:173], v[178:181], v[64:67]
	v_mfma_f32_16x16x32_bf16 v[44:47], v[156:159], v[186:189], v[48:51]
	v_mfma_f32_16x16x32_bf16 v[36:39], v[174:177], v[190:193], v[36:39]
	v_mfma_f32_16x16x32_bf16 v[20:23], v[166:169], v[210:213], v[20:23]
	v_mfma_f32_16x16x32_bf16 v[16:19], v[174:177], v[210:213], v[16:19]
	v_mfma_f32_16x16x32_bf16 v[4:7], v[166:169], v[218:221], v[4:7]
	v_mfma_f32_16x16x32_bf16 v[0:3], v[174:177], v[218:221], v[0:3]
	v_mfma_f32_16x16x32_bf16 v[32:35], v[166:169], v[182:185], v[32:35]
	v_mfma_f32_16x16x32_bf16 v[40:43], v[174:177], v[182:185], v[40:43]
	v_mfma_f32_16x16x32_bf16 v[44:47], v[166:169], v[190:193], v[44:47]
	s_barrier
	s_add_i32 s56, 0, 0x18000
	s_add_i32 s57, 0, 0x1c000
	v_add_u32_e32 v68, s56, v164
	v_add_u32_e32 v174, s57, v164
	ds_read_b128 v[48:51], v68
	ds_read_b128 v[52:55], v68 offset:1024
	ds_read_b128 v[64:67], v68 offset:2048
	ds_read_b128 v[68:71], v68 offset:3072
	ds_read_b128 v[156:159], v174
	ds_read_b128 v[166:169], v174 offset:1024
	ds_read_b128 v[170:173], v174 offset:2048
	ds_read_b128 v[174:177], v174 offset:3072
	s_add_u32 s22, s22, 0x40000
	s_addc_u32 s23, s23, 0
	s_mov_b32 m0, s29
	v_lshl_add_u64 v[236:237], s[22:23], 0, v[150:151]
	ds_read_b128 v[178:181], v165 offset:32768
	ds_read_b128 v[182:185], v165 offset:33792
	ds_read_b128 v[186:189], v165 offset:34816
	ds_read_b128 v[190:193], v165 offset:35840
	ds_read_b128 v[206:209], v165 offset:36864
	ds_read_b128 v[210:213], v165 offset:37888
	ds_read_b128 v[214:217], v165 offset:38912
	ds_read_b128 v[218:221], v165 offset:39936
	global_load_lds_dwordx4 v[236:237], off
	v_lshl_add_u64 v[236:237], s[22:23], 0, v[148:149]
	s_mov_b32 m0, s31
	s_nop 0
	global_load_lds_dwordx4 v[236:237], off
	s_waitcnt vmcnt(8)
	s_waitcnt lgkmcnt(0)
	s_barrier
	s_waitcnt lgkmcnt(0)
	v_mfma_f32_16x16x32_bf16 v[142:145], v[48:51], v[178:181], v[142:145]
	v_mfma_f32_16x16x32_bf16 v[138:141], v[64:67], v[178:181], v[138:141]
	v_mfma_f32_16x16x32_bf16 v[126:129], v[48:51], v[186:189], v[126:129]
	v_mfma_f32_16x16x32_bf16 v[122:125], v[64:67], v[186:189], v[122:125]
	v_mfma_f32_16x16x32_bf16 v[110:113], v[48:51], v[206:209], v[110:113]
	v_mfma_f32_16x16x32_bf16 v[106:109], v[64:67], v[206:209], v[106:109]
	v_mfma_f32_16x16x32_bf16 v[92:95], v[48:51], v[214:217], v[92:95]
	v_mfma_f32_16x16x32_bf16 v[88:91], v[64:67], v[214:217], v[88:91]
	v_mfma_f32_16x16x32_bf16 v[142:145], v[52:55], v[182:185], v[142:145]
	v_mfma_f32_16x16x32_bf16 v[138:141], v[68:71], v[182:185], v[138:141]
	v_mfma_f32_16x16x32_bf16 v[126:129], v[52:55], v[190:193], v[126:129]
	v_mfma_f32_16x16x32_bf16 v[122:125], v[68:71], v[190:193], v[122:125]
	v_mfma_f32_16x16x32_bf16 v[110:113], v[52:55], v[210:213], v[110:113]
	v_mfma_f32_16x16x32_bf16 v[106:109], v[68:71], v[210:213], v[106:109]
	v_mfma_f32_16x16x32_bf16 v[92:95], v[52:55], v[218:221], v[92:95]
	v_mfma_f32_16x16x32_bf16 v[88:91], v[68:71], v[218:221], v[88:91]
	v_mfma_f32_16x16x32_bf16 v[134:137], v[156:159], v[178:181], v[134:137]
	v_mfma_f32_16x16x32_bf16 v[130:133], v[170:173], v[178:181], v[130:133]
	v_mfma_f32_16x16x32_bf16 v[118:121], v[156:159], v[186:189], v[118:121]
	v_mfma_f32_16x16x32_bf16 v[114:117], v[170:173], v[186:189], v[114:117]
	v_mfma_f32_16x16x32_bf16 v[102:105], v[156:159], v[206:209], v[102:105]
	v_mfma_f32_16x16x32_bf16 v[98:101], v[170:173], v[206:209], v[98:101]
	v_mfma_f32_16x16x32_bf16 v[84:87], v[156:159], v[214:217], v[84:87]
	v_mfma_f32_16x16x32_bf16 v[80:83], v[170:173], v[214:217], v[80:83]
	v_mfma_f32_16x16x32_bf16 v[134:137], v[166:169], v[182:185], v[134:137]
	v_mfma_f32_16x16x32_bf16 v[130:133], v[174:177], v[182:185], v[130:133]
	v_mfma_f32_16x16x32_bf16 v[118:121], v[166:169], v[190:193], v[118:121]
	v_mfma_f32_16x16x32_bf16 v[114:117], v[174:177], v[190:193], v[114:117]
	v_mfma_f32_16x16x32_bf16 v[102:105], v[166:169], v[210:213], v[102:105]
	v_mfma_f32_16x16x32_bf16 v[98:101], v[174:177], v[210:213], v[98:101]
	v_mfma_f32_16x16x32_bf16 v[84:87], v[166:169], v[218:221], v[84:87]
	v_mfma_f32_16x16x32_bf16 v[80:83], v[174:177], v[218:221], v[80:83]
	s_barrier
; #define PG8_STAGE(bufoff, gbase, voff) do { _Pragma("unroll") for (int _i = 0; _i < 2; ++_i) \
;         __builtin_amdgcn_global_load_lds((const unsigned*)((const char*)(gbase) + (voff)[_i]), (LAS unsigned*)(lds + (bufoff) + ldsw + _i * 8192), 16, 0, 0); } while (0)
; #define PG8_LDA(dst, b, h) do { _Pragma("unroll") for (int m = 0; m < 4; ++m) _Pragma("unroll") for (int k = 0; k < 2; ++k) dst[m][k] = *(const LAS bf16x8*)(lds + PG8_SA(b, h) + aoff + m * 2048 + k * 1024); } while (0)
; #define PG8_MMA(ai, bj, At, Bt) do { __builtin_amdgcn_s_setprio(1); _Pragma("unroll") for (int m = 0; m < 4; ++m) _Pragma("unroll") for (int n = 0; n < 2; ++n) _Pragma("unroll") for (int k = 0; k < 2; ++k) \
;         acc[ai][bj][m][n] = __builtin_amdgcn_mfma_f32_16x16x32_bf16(Bt[n][k], At[m][k], acc[ai][bj][m][n], 0, 0, 0); __builtin_amdgcn_s_setprio(0); } while (0)
; #define PG8_WAIT_V(n) asm volatile("s_waitcnt vmcnt(" #n ")" ::: "memory")
; #define PG8_WAIT_L(n) asm volatile("s_waitcnt lgkmcnt(" #n ")" ::: "memory")
; #define PG8_BAR __builtin_amdgcn_s_barrier()
; #define PG8_SCHED __builtin_amdgcn_sched_barrier(0)
; template <class Epi, class Sched>
; __device__ __forceinline__ void gemm_phase(LAS unsigned char* lds, const Gemm g, const Sched& S, const Epi& E) {
;     ...
;             PG8_LDA(At, 1, 1); PG8_STAGE(PG8_SB(1, 0), b3, voffB); PG8_STAGE(PG8_SB(1, 1), b3 + hstepB, voffB); PG8_STAGE(PG8_SA(1, 0), a3, voffA);
;             PG8_WAIT_V(8); PG8_WAIT_L(0); PG8_BAR; PG8_MMA(1, 0, At, B0); PG8_MMA(1, 1, At, B1); PG8_BAR; PG8_SCHED;
;         }
;         if (wr == 0) PG8_BAR;
	s_add_i32 s22, s56, s7
	v_lshl_add_u64 v[160:161], v[160:161], 0, s[4:5]
	s_mov_b32 m0, s22
	ds_read_b128 v[178:181], v165 offset:49152
	ds_read_b128 v[182:185], v165 offset:50176
	ds_read_b128 v[186:189], v165 offset:51200
	ds_read_b128 v[190:193], v165 offset:52224
	ds_read_b128 v[206:209], v165 offset:53248
	ds_read_b128 v[210:213], v165 offset:54272
	ds_read_b128 v[214:217], v165 offset:55296
	ds_read_b128 v[218:221], v165 offset:56320
	global_load_lds_dwordx4 v[160:161], off
	s_add_i32 m0, s22, 0x2000
	s_add_u32 s20, s20, 0x40080
	v_lshl_add_u64 v[160:161], v[230:231], 0, s[4:5]
	s_addc_u32 s21, s21, 0
	s_add_i32 s22, s57, s7
	global_load_lds_dwordx4 v[160:161], off
	v_lshl_add_u64 v[160:161], s[20:21], 0, v[96:97]
	s_mov_b32 m0, s22
	s_nop 0
	global_load_lds_dwordx4 v[160:161], off
	v_lshl_add_u64 v[160:161], s[20:21], 0, v[146:147]
	s_add_i32 m0, s22, 0x2000
	s_nop 0
	global_load_lds_dwordx4 v[160:161], off
	v_lshl_add_u64 v[160:161], v[232:233], 0, s[4:5]
	s_mov_b32 m0, s44
	s_nop 0
	global_load_lds_dwordx4 v[160:161], off
	v_lshl_add_u64 v[160:161], v[234:235], 0, s[4:5]
	s_mov_b32 m0, s45
	s_nop 0
	global_load_lds_dwordx4 v[160:161], off
	s_waitcnt vmcnt(8)
	s_waitcnt lgkmcnt(0)
	s_barrier
	s_waitcnt lgkmcnt(0)
	v_mfma_f32_16x16x32_bf16 v[76:79], v[48:51], v[178:181], v[76:79]
	v_mfma_f32_16x16x32_bf16 v[72:75], v[64:67], v[178:181], v[72:75]
	v_mfma_f32_16x16x32_bf16 v[60:63], v[48:51], v[186:189], v[60:63]
	v_mfma_f32_16x16x32_bf16 v[56:59], v[64:67], v[186:189], v[56:59]
	v_mfma_f32_16x16x32_bf16 v[28:31], v[48:51], v[206:209], v[28:31]
	v_mfma_f32_16x16x32_bf16 v[24:27], v[64:67], v[206:209], v[24:27]
	v_mfma_f32_16x16x32_bf16 v[12:15], v[48:51], v[214:217], v[12:15]
	v_mfma_f32_16x16x32_bf16 v[8:11], v[64:67], v[214:217], v[8:11]
	v_mfma_f32_16x16x32_bf16 v[76:79], v[52:55], v[182:185], v[76:79]
	v_mfma_f32_16x16x32_bf16 v[72:75], v[68:71], v[182:185], v[72:75]
	v_mfma_f32_16x16x32_bf16 v[60:63], v[52:55], v[190:193], v[60:63]
	v_mfma_f32_16x16x32_bf16 v[56:59], v[68:71], v[190:193], v[56:59]
	v_mfma_f32_16x16x32_bf16 v[28:31], v[52:55], v[210:213], v[28:31]
	v_mfma_f32_16x16x32_bf16 v[24:27], v[68:71], v[210:213], v[24:27]
	v_mfma_f32_16x16x32_bf16 v[12:15], v[52:55], v[218:221], v[12:15]
	v_mfma_f32_16x16x32_bf16 v[8:11], v[68:71], v[218:221], v[8:11]
	v_mfma_f32_16x16x32_bf16 v[32:35], v[156:159], v[178:181], v[32:35]
	v_mfma_f32_16x16x32_bf16 v[68:71], v[166:169], v[182:185], v[32:35]
	v_mfma_f32_16x16x32_bf16 v[32:35], v[170:173], v[178:181], v[40:43]
	v_mfma_f32_16x16x32_bf16 v[64:67], v[174:177], v[182:185], v[32:35]
	v_mfma_f32_16x16x32_bf16 v[32:35], v[156:159], v[186:189], v[44:47]
	v_mfma_f32_16x16x32_bf16 v[48:51], v[166:169], v[190:193], v[32:35]
	v_mfma_f32_16x16x32_bf16 v[32:35], v[170:173], v[186:189], v[36:39]
	v_mfma_f32_16x16x32_bf16 v[20:23], v[156:159], v[206:209], v[20:23]
	v_mfma_f32_16x16x32_bf16 v[16:19], v[170:173], v[206:209], v[16:19]
	v_mfma_f32_16x16x32_bf16 v[4:7], v[156:159], v[214:217], v[4:7]
	v_mfma_f32_16x16x32_bf16 v[0:3], v[170:173], v[214:217], v[0:3]
	v_mfma_f32_16x16x32_bf16 v[36:39], v[174:177], v[190:193], v[32:35]
	v_mfma_f32_16x16x32_bf16 v[20:23], v[166:169], v[210:213], v[20:23]
	v_mfma_f32_16x16x32_bf16 v[16:19], v[174:177], v[210:213], v[16:19]
	v_mfma_f32_16x16x32_bf16 v[4:7], v[166:169], v[218:221], v[4:7]
	v_mfma_f32_16x16x32_bf16 v[0:3], v[174:177], v[218:221], v[0:3]
	s_barrier
	s_add_i32 s55, s55, 2
	s_add_u32 s51, s51, 0x100
	s_addc_u32 s54, s54, 0
	s_add_u32 s0, s0, 0x100
	s_addc_u32 s1, s1, 0
	s_cmp_gt_u32 s55, 13
	s_cbranch_scc0 .LBB0_174
	s_and_b64 vcc, exec, s[10:11]
	s_cbranch_vccz .LBB0_177
	s_barrier

; #define PG8_STAGE(bufoff, gbase, voff) do { _Pragma("unroll") for (int _i = 0; _i < 2; ++_i) \
;         __builtin_amdgcn_global_load_lds((const unsigned*)((const char*)(gbase) + (voff)[_i]), (LAS unsigned*)(lds + (bufoff) + ldsw + _i * 8192), 16, 0, 0); } while (0)
; #define PG8_LDA(dst, b, h) do { _Pragma("unroll") for (int m = 0; m < 4; ++m) _Pragma("unroll") for (int k = 0; k < 2; ++k) dst[m][k] = *(const LAS bf16x8*)(lds + PG8_SA(b, h) + aoff + m * 2048 + k * 1024); } while (0)
; #define PG8_LDB(dst, b, h) do { _Pragma("unroll") for (int n = 0; n < 2; ++n) _Pragma("unroll") for (int k = 0; k < 2; ++k) dst[n][k] = *(const LAS bf16x8*)(lds + PG8_SB(b, h) + boff + n * 2048 + k * 1024); } while (0)
; #define PG8_MMA(ai, bj, At, Bt) do { __builtin_amdgcn_s_setprio(1); _Pragma("unroll") for (int m = 0; m < 4; ++m) _Pragma("unroll") for (int n = 0; n < 2; ++n) _Pragma("unroll") for (int k = 0; k < 2; ++k) \
;         acc[ai][bj][m][n] = __builtin_amdgcn_mfma_f32_16x16x32_bf16(Bt[n][k], At[m][k], acc[ai][bj][m][n], 0, 0, 0); __builtin_amdgcn_s_setprio(0); } while (0)
; #define PG8_WAIT_V(n) asm volatile("s_waitcnt vmcnt(" #n ")" ::: "memory")
; #define PG8_WAIT_L(n) asm volatile("s_waitcnt lgkmcnt(" #n ")" ::: "memory")
; #define PG8_BAR __builtin_amdgcn_s_barrier()
; #define PG8_SCHED __builtin_amdgcn_sched_barrier(0)
; template <class Epi, class Sched>
; __device__ __forceinline__ void gemm_phase(LAS unsigned char* lds, const Gemm g, const Sched& S, const Epi& E) {
;     ...
;         for (int t = 0; t < nt; t += 2) {
;             const bool last = (t == nt - 2);
;             const char* a1 = cA + (size_t)(t + 1) * kstep;
;             const char* a2 = last ? nA : cA + (size_t)(t + 2) * kstep; const char* b2 = last ? nB : cB + (size_t)(t + 2) * kstep;
;             const char* a3 = a2 + kstep; const char* b3 = b2 + kstep;
;             PG8_LDB(B0, 0, 0); PG8_LDB(B1, 0, 1); PG8_SCHED; PG8_LDA(At, 0, 0); PG8_STAGE(PG8_SA(1, 1), a1 + hstepA, voffA);
;             PG8_WAIT_V(8); PG8_WAIT_L(0); PG8_BAR; PG8_MMA(0, 0, At, B0); PG8_MMA(0, 1, At, B1); PG8_BAR; PG8_SCHED;
;             PG8_LDA(At, 0, 1); PG8_STAGE(PG8_SB(0, 0), b2, voffB); PG8_STAGE(PG8_SB(0, 1), b2 + hstepB, voffB); PG8_STAGE(PG8_SA(0, 0), a2, voffA);
;             PG8_WAIT_V(8); PG8_WAIT_L(0); PG8_BAR; PG8_MMA(1, 0, At, B0); PG8_MMA(1, 1, At, B1); PG8_BAR; PG8_SCHED;
.LBB0_727:
	s_add_u32 s18, s16, 0xfffc0080
	s_addc_u32 s19, s17, -1
	s_add_i32 s77, 0, 0x10000
	s_cmp_eq_u32 s76, 4
	s_cselect_b32 s21, s11, s19
	s_cselect_b32 s20, s72, s18
	v_add_u32_e32 v96, s77, v218
	s_cselect_b32 s19, s9, s75
	s_cselect_b32 s18, s73, s74
	s_add_i32 s80, 0, 0x14000
	ds_read_b128 v[132:135], v96
	ds_read_b128 v[136:139], v96 offset:1024
	ds_read_b128 v[140:143], v96 offset:2048
	ds_read_b128 v[144:147], v96 offset:3072
	v_add_u32_e32 v96, s80, v218
	ds_read_b128 v[148:151], v96
	ds_read_b128 v[152:155], v96 offset:1024
	ds_read_b128 v[156:159], v96 offset:2048
	ds_read_b128 v[160:163], v96 offset:3072
	v_lshl_add_u64 v[98:99], s[16:17], 0, v[214:215]
	s_add_i32 m0, s25, 0xc000
	ds_read_b128 v[164:167], v219
	ds_read_b128 v[168:171], v219 offset:1024
	ds_read_b128 v[172:175], v219 offset:2048
	ds_read_b128 v[176:179], v219 offset:3072
	ds_read_b128 v[180:183], v219 offset:4096
	ds_read_b128 v[184:187], v219 offset:5120
	ds_read_b128 v[188:191], v219 offset:6144
	ds_read_b128 v[230:233], v219 offset:7168
	global_load_lds_dwordx4 v[98:99], off
	v_lshl_add_u64 v[98:99], s[16:17], 0, v[212:213]
	s_add_i32 m0, s25, 0xe000
	s_nop 0
	global_load_lds_dwordx4 v[98:99], off
	s_waitcnt vmcnt(8)
	s_waitcnt lgkmcnt(0)
	s_barrier
	s_waitcnt lgkmcnt(0)
	v_mfma_f32_16x16x32_bf16 v[128:131], v[132:135], v[164:167], v[128:131]
	v_mfma_f32_16x16x32_bf16 v[124:127], v[140:143], v[164:167], v[124:127]
	v_mfma_f32_16x16x32_bf16 v[120:123], v[132:135], v[172:175], v[120:123]
	v_mfma_f32_16x16x32_bf16 v[116:119], v[140:143], v[172:175], v[116:119]
	v_mfma_f32_16x16x32_bf16 v[112:115], v[132:135], v[180:183], v[112:115]
	v_mfma_f32_16x16x32_bf16 v[108:111], v[140:143], v[180:183], v[108:111]
	v_mfma_f32_16x16x32_bf16 v[104:107], v[132:135], v[188:191], v[104:107]
	v_mfma_f32_16x16x32_bf16 v[98:101], v[140:143], v[188:191], v[100:103]
	v_mfma_f32_16x16x32_bf16 v[128:131], v[136:139], v[168:171], v[128:131]
	v_mfma_f32_16x16x32_bf16 v[124:127], v[144:147], v[168:171], v[124:127]
	v_mfma_f32_16x16x32_bf16 v[120:123], v[136:139], v[176:179], v[120:123]
	v_mfma_f32_16x16x32_bf16 v[116:119], v[144:147], v[176:179], v[116:119]
	v_mfma_f32_16x16x32_bf16 v[112:115], v[136:139], v[184:187], v[112:115]
	v_mfma_f32_16x16x32_bf16 v[108:111], v[144:147], v[184:187], v[108:111]
	v_mfma_f32_16x16x32_bf16 v[104:107], v[136:139], v[230:233], v[104:107]
	v_mfma_f32_16x16x32_bf16 v[98:101], v[144:147], v[230:233], v[98:101]
	v_mfma_f32_16x16x32_bf16 v[92:95], v[148:151], v[164:167], v[92:95]
	v_mfma_f32_16x16x32_bf16 v[88:91], v[156:159], v[164:167], v[88:91]
	v_mfma_f32_16x16x32_bf16 v[84:87], v[148:151], v[172:175], v[84:87]
	v_mfma_f32_16x16x32_bf16 v[80:83], v[156:159], v[172:175], v[80:83]
	v_mfma_f32_16x16x32_bf16 v[76:79], v[148:151], v[180:183], v[76:79]
	v_mfma_f32_16x16x32_bf16 v[72:75], v[156:159], v[180:183], v[72:75]
	v_mfma_f32_16x16x32_bf16 v[68:71], v[148:151], v[188:191], v[68:71]
	v_mfma_f32_16x16x32_bf16 v[64:67], v[156:159], v[188:191], v[64:67]
	v_mfma_f32_16x16x32_bf16 v[92:95], v[152:155], v[168:171], v[92:95]
	v_mfma_f32_16x16x32_bf16 v[88:91], v[160:163], v[168:171], v[88:91]
	v_mfma_f32_16x16x32_bf16 v[84:87], v[152:155], v[176:179], v[84:87]
	v_mfma_f32_16x16x32_bf16 v[80:83], v[160:163], v[176:179], v[80:83]
	v_mfma_f32_16x16x32_bf16 v[76:79], v[152:155], v[184:187], v[76:79]
	v_mfma_f32_16x16x32_bf16 v[72:75], v[160:163], v[184:187], v[72:75]
	v_mfma_f32_16x16x32_bf16 v[68:71], v[152:155], v[230:233], v[68:71]
	v_mfma_f32_16x16x32_bf16 v[64:67], v[160:163], v[230:233], v[64:67]
	s_barrier
	s_add_i32 s77, s77, s7
	v_lshl_add_u64 v[220:221], s[18:19], 0, v[208:209]
	s_mov_b32 m0, s77
	ds_read_b128 v[164:167], v219 offset:16384
	ds_read_b128 v[168:171], v219 offset:17408
	ds_read_b128 v[172:175], v219 offset:18432
	ds_read_b128 v[176:179], v219 offset:19456
	ds_read_b128 v[180:183], v219 offset:20480
	ds_read_b128 v[184:187], v219 offset:21504
	ds_read_b128 v[188:191], v219 offset:22528
	ds_read_b128 v[230:233], v219 offset:23552
	global_load_lds_dwordx4 v[220:221], off
	s_add_i32 m0, s77, 0x2000
	s_add_u32 s78, s18, 0x20000
	v_lshl_add_u64 v[234:235], s[18:19], 0, v[192:193]
	s_addc_u32 s79, s19, 0
	s_add_i32 s77, s80, s7
	global_load_lds_dwordx4 v[234:235], off
	v_lshl_add_u64 v[102:103], s[78:79], 0, v[208:209]
	s_mov_b32 m0, s77
	v_lshl_add_u64 v[236:237], s[20:21], 0, v[210:211]
	global_load_lds_dwordx4 v[102:103], off
	v_lshl_add_u64 v[102:103], s[78:79], 0, v[192:193]
	s_add_i32 m0, s77, 0x2000
	v_lshl_add_u64 v[238:239], s[20:21], 0, v[206:207]
	global_load_lds_dwordx4 v[102:103], off
	s_mov_b32 m0, s25
	s_nop 0
	global_load_lds_dwordx4 v[236:237], off
	s_mov_b32 m0, s27
	s_nop 0
	global_load_lds_dwordx4 v[238:239], off
	s_waitcnt vmcnt(8)
	s_waitcnt lgkmcnt(0)
	s_barrier
; #define PG8_STAGE(bufoff, gbase, voff) do { _Pragma("unroll") for (int _i = 0; _i < 2; ++_i) \
;         __builtin_amdgcn_global_load_lds((const unsigned*)((const char*)(gbase) + (voff)[_i]), (LAS unsigned*)(lds + (bufoff) + ldsw + _i * 8192), 16, 0, 0); } while (0)
; #define PG8_LDA(dst, b, h) do { _Pragma("unroll") for (int m = 0; m < 4; ++m) _Pragma("unroll") for (int k = 0; k < 2; ++k) dst[m][k] = *(const LAS bf16x8*)(lds + PG8_SA(b, h) + aoff + m * 2048 + k * 1024); } while (0)
; #define PG8_LDB(dst, b, h) do { _Pragma("unroll") for (int n = 0; n < 2; ++n) _Pragma("unroll") for (int k = 0; k < 2; ++k) dst[n][k] = *(const LAS bf16x8*)(lds + PG8_SB(b, h) + boff + n * 2048 + k * 1024); } while (0)
; #define PG8_MMA(ai, bj, At, Bt) do { __builtin_amdgcn_s_setprio(1); _Pragma("unroll") for (int m = 0; m < 4; ++m) _Pragma("unroll") for (int n = 0; n < 2; ++n) _Pragma("unroll") for (int k = 0; k < 2; ++k) \
;         acc[ai][bj][m][n] = __builtin_amdgcn_mfma_f32_16x16x32_bf16(Bt[n][k], At[m][k], acc[ai][bj][m][n], 0, 0, 0); __builtin_amdgcn_s_setprio(0); } while (0)
; #define PG8_WAIT_V(n) asm volatile("s_waitcnt vmcnt(" #n ")" ::: "memory")
; #define PG8_WAIT_L(n) asm volatile("s_waitcnt lgkmcnt(" #n ")" ::: "memory")
; #define PG8_BAR __builtin_amdgcn_s_barrier()
; #define PG8_SCHED __builtin_amdgcn_sched_barrier(0)
; template <class Epi, class Sched>
; __device__ __forceinline__ void gemm_phase(LAS unsigned char* lds, const Gemm g, const Sched& S, const Epi& E) {
;     ...
;             PG8_LDA(At, 0, 1); PG8_STAGE(PG8_SB(0, 0), b2, voffB); PG8_STAGE(PG8_SB(0, 1), b2 + hstepB, voffB); PG8_STAGE(PG8_SA(0, 0), a2, voffA);
;             PG8_WAIT_V(8); PG8_WAIT_L(0); PG8_BAR; PG8_MMA(1, 0, At, B0); PG8_MMA(1, 1, At, B1); PG8_BAR; PG8_SCHED;
;             PG8_LDB(B0, 1, 0); PG8_LDB(B1, 1, 1); PG8_SCHED; PG8_LDA(At, 1, 0); PG8_STAGE(PG8_SA(0, 1), a2 + hstepA, voffA);
;             PG8_WAIT_V(8); PG8_WAIT_L(0); PG8_BAR; PG8_MMA(0, 0, At, B0); PG8_MMA(0, 1, At, B1); PG8_BAR; PG8_SCHED;
;             PG8_LDA(At, 1, 1); PG8_STAGE(PG8_SB(1, 0), b3, voffB); PG8_STAGE(PG8_SB(1, 1), b3 + hstepB, voffB); PG8_STAGE(PG8_SA(1, 0), a3, voffA);
	s_waitcnt lgkmcnt(0)
	v_mfma_f32_16x16x32_bf16 v[60:63], v[132:135], v[164:167], v[60:63]
	v_mfma_f32_16x16x32_bf16 v[56:59], v[140:143], v[164:167], v[56:59]
	v_mfma_f32_16x16x32_bf16 v[52:55], v[132:135], v[172:175], v[52:55]
	v_mfma_f32_16x16x32_bf16 v[48:51], v[140:143], v[172:175], v[48:51]
	v_mfma_f32_16x16x32_bf16 v[44:47], v[132:135], v[180:183], v[44:47]
	v_mfma_f32_16x16x32_bf16 v[40:43], v[140:143], v[180:183], v[40:43]
	v_mfma_f32_16x16x32_bf16 v[36:39], v[132:135], v[188:191], v[36:39]
	v_mfma_f32_16x16x32_bf16 v[32:35], v[140:143], v[188:191], v[32:35]
	v_mfma_f32_16x16x32_bf16 v[60:63], v[136:139], v[168:171], v[60:63]
	v_mfma_f32_16x16x32_bf16 v[56:59], v[144:147], v[168:171], v[56:59]
	v_mfma_f32_16x16x32_bf16 v[52:55], v[136:139], v[176:179], v[52:55]
	v_mfma_f32_16x16x32_bf16 v[48:51], v[144:147], v[176:179], v[48:51]
	v_mfma_f32_16x16x32_bf16 v[44:47], v[136:139], v[184:187], v[44:47]
	v_mfma_f32_16x16x32_bf16 v[40:43], v[144:147], v[184:187], v[40:43]
	v_mfma_f32_16x16x32_bf16 v[36:39], v[136:139], v[230:233], v[36:39]
	v_mfma_f32_16x16x32_bf16 v[32:35], v[144:147], v[230:233], v[32:35]
	v_mfma_f32_16x16x32_bf16 v[28:31], v[148:151], v[164:167], v[28:31]
	v_mfma_f32_16x16x32_bf16 v[24:27], v[156:159], v[164:167], v[24:27]
	v_mfma_f32_16x16x32_bf16 v[20:23], v[148:151], v[172:175], v[20:23]
	v_mfma_f32_16x16x32_bf16 v[16:19], v[156:159], v[172:175], v[16:19]
	v_mfma_f32_16x16x32_bf16 v[12:15], v[148:151], v[180:183], v[12:15]
	v_mfma_f32_16x16x32_bf16 v[8:11], v[156:159], v[180:183], v[8:11]
	v_mfma_f32_16x16x32_bf16 v[4:7], v[148:151], v[188:191], v[4:7]
	v_mfma_f32_16x16x32_bf16 v[0:3], v[156:159], v[188:191], v[0:3]
	v_mfma_f32_16x16x32_bf16 v[28:31], v[152:155], v[168:171], v[28:31]
	v_mfma_f32_16x16x32_bf16 v[24:27], v[160:163], v[168:171], v[24:27]
	v_mfma_f32_16x16x32_bf16 v[20:23], v[152:155], v[176:179], v[20:23]
	v_mfma_f32_16x16x32_bf16 v[16:19], v[160:163], v[176:179], v[16:19]
	v_mfma_f32_16x16x32_bf16 v[12:15], v[152:155], v[184:187], v[12:15]
	v_mfma_f32_16x16x32_bf16 v[8:11], v[160:163], v[184:187], v[8:11]
	v_mfma_f32_16x16x32_bf16 v[4:7], v[152:155], v[230:233], v[4:7]
	v_mfma_f32_16x16x32_bf16 v[0:3], v[160:163], v[230:233], v[0:3]
	s_barrier
	s_add_i32 s77, 0, 0x18000
	v_add_u32_e32 v96, s77, v218
	s_add_i32 s78, 0, 0x1c000
	ds_read_b128 v[132:135], v96
	ds_read_b128 v[136:139], v96 offset:1024
	ds_read_b128 v[140:143], v96 offset:2048
	ds_read_b128 v[144:147], v96 offset:3072
	v_add_u32_e32 v96, s78, v218
	ds_read_b128 v[148:151], v96
	ds_read_b128 v[152:155], v96 offset:1024
	ds_read_b128 v[156:159], v96 offset:2048
	ds_read_b128 v[160:163], v96 offset:3072
	s_add_u32 s20, s20, 0x40000
	s_addc_u32 s21, s21, 0
	s_mov_b32 m0, s29
	v_lshl_add_u64 v[102:103], s[20:21], 0, v[210:211]
	ds_read_b128 v[164:167], v219 offset:32768
	ds_read_b128 v[168:171], v219 offset:33792
	ds_read_b128 v[172:175], v219 offset:34816
	ds_read_b128 v[176:179], v219 offset:35840
	ds_read_b128 v[180:183], v219 offset:36864
	ds_read_b128 v[184:187], v219 offset:37888
	ds_read_b128 v[188:191], v219 offset:38912
	ds_read_b128 v[230:233], v219 offset:39936
	global_load_lds_dwordx4 v[102:103], off
	v_lshl_add_u64 v[102:103], s[20:21], 0, v[206:207]
	s_mov_b32 m0, s31
	s_nop 0
	global_load_lds_dwordx4 v[102:103], off
	s_waitcnt vmcnt(8)
	s_waitcnt lgkmcnt(0)
	s_barrier
	s_waitcnt lgkmcnt(0)
	v_mfma_f32_16x16x32_bf16 v[128:131], v[132:135], v[164:167], v[128:131]
	v_mfma_f32_16x16x32_bf16 v[124:127], v[140:143], v[164:167], v[124:127]
	v_mfma_f32_16x16x32_bf16 v[120:123], v[132:135], v[172:175], v[120:123]
	v_mfma_f32_16x16x32_bf16 v[116:119], v[140:143], v[172:175], v[116:119]
	v_mfma_f32_16x16x32_bf16 v[112:115], v[132:135], v[180:183], v[112:115]
	v_mfma_f32_16x16x32_bf16 v[108:111], v[140:143], v[180:183], v[108:111]
	v_mfma_f32_16x16x32_bf16 v[102:105], v[132:135], v[188:191], v[104:107]
	v_mfma_f32_16x16x32_bf16 v[98:101], v[140:143], v[188:191], v[98:101]
	v_mfma_f32_16x16x32_bf16 v[128:131], v[136:139], v[168:171], v[128:131]
	v_mfma_f32_16x16x32_bf16 v[124:127], v[144:147], v[168:171], v[124:127]
	v_mfma_f32_16x16x32_bf16 v[120:123], v[136:139], v[176:179], v[120:123]
	v_mfma_f32_16x16x32_bf16 v[116:119], v[144:147], v[176:179], v[116:119]
	v_mfma_f32_16x16x32_bf16 v[112:115], v[136:139], v[184:187], v[112:115]
	v_mfma_f32_16x16x32_bf16 v[108:111], v[144:147], v[184:187], v[108:111]
	v_mfma_f32_16x16x32_bf16 v[104:107], v[136:139], v[230:233], v[102:105]
	v_mfma_f32_16x16x32_bf16 v[100:103], v[144:147], v[230:233], v[98:101]
	v_mfma_f32_16x16x32_bf16 v[92:95], v[148:151], v[164:167], v[92:95]
	v_mfma_f32_16x16x32_bf16 v[88:91], v[156:159], v[164:167], v[88:91]
	v_mfma_f32_16x16x32_bf16 v[84:87], v[148:151], v[172:175], v[84:87]
	v_mfma_f32_16x16x32_bf16 v[80:83], v[156:159], v[172:175], v[80:83]
	v_mfma_f32_16x16x32_bf16 v[76:79], v[148:151], v[180:183], v[76:79]
	v_mfma_f32_16x16x32_bf16 v[72:75], v[156:159], v[180:183], v[72:75]
	v_mfma_f32_16x16x32_bf16 v[68:71], v[148:151], v[188:191], v[68:71]
	v_mfma_f32_16x16x32_bf16 v[64:67], v[156:159], v[188:191], v[64:67]
	v_mfma_f32_16x16x32_bf16 v[92:95], v[152:155], v[168:171], v[92:95]
	v_mfma_f32_16x16x32_bf16 v[88:91], v[160:163], v[168:171], v[88:91]
	v_mfma_f32_16x16x32_bf16 v[84:87], v[152:155], v[176:179], v[84:87]
	v_mfma_f32_16x16x32_bf16 v[80:83], v[160:163], v[176:179], v[80:83]
	v_mfma_f32_16x16x32_bf16 v[76:79], v[152:155], v[184:187], v[76:79]
	v_mfma_f32_16x16x32_bf16 v[72:75], v[160:163], v[184:187], v[72:75]
	v_mfma_f32_16x16x32_bf16 v[68:71], v[152:155], v[230:233], v[68:71]
	v_mfma_f32_16x16x32_bf16 v[64:67], v[160:163], v[230:233], v[64:67]
	s_barrier
; #define PG8_STAGE(bufoff, gbase, voff) do { _Pragma("unroll") for (int _i = 0; _i < 2; ++_i) \
;         __builtin_amdgcn_global_load_lds((const unsigned*)((const char*)(gbase) + (voff)[_i]), (LAS unsigned*)(lds + (bufoff) + ldsw + _i * 8192), 16, 0, 0); } while (0)
; #define PG8_LDA(dst, b, h) do { _Pragma("unroll") for (int m = 0; m < 4; ++m) _Pragma("unroll") for (int k = 0; k < 2; ++k) dst[m][k] = *(const LAS bf16x8*)(lds + PG8_SA(b, h) + aoff + m * 2048 + k * 1024); } while (0)
; #define PG8_MMA(ai, bj, At, Bt) do { __builtin_amdgcn_s_setprio(1); _Pragma("unroll") for (int m = 0; m < 4; ++m) _Pragma("unroll") for (int n = 0; n < 2; ++n) _Pragma("unroll") for (int k = 0; k < 2; ++k) \
;         acc[ai][bj][m][n] = __builtin_amdgcn_mfma_f32_16x16x32_bf16(Bt[n][k], At[m][k], acc[ai][bj][m][n], 0, 0, 0); __builtin_amdgcn_s_setprio(0); } while (0)
; #define PG8_WAIT_V(n) asm volatile("s_waitcnt vmcnt(" #n ")" ::: "memory")
; #define PG8_WAIT_L(n) asm volatile("s_waitcnt lgkmcnt(" #n ")" ::: "memory")
; #define PG8_BAR __builtin_amdgcn_s_barrier()
; #define PG8_SCHED __builtin_amdgcn_sched_barrier(0)
; template <class Epi, class Sched>
; __device__ __forceinline__ void gemm_phase(LAS unsigned char* lds, const Gemm g, const Sched& S, const Epi& E) {
;     ...
;             PG8_LDA(At, 1, 1); PG8_STAGE(PG8_SB(1, 0), b3, voffB); PG8_STAGE(PG8_SB(1, 1), b3 + hstepB, voffB); PG8_STAGE(PG8_SA(1, 0), a3, voffA);
;             PG8_WAIT_V(8); PG8_WAIT_L(0); PG8_BAR; PG8_MMA(1, 0, At, B0); PG8_MMA(1, 1, At, B1); PG8_BAR; PG8_SCHED;
;         }
;         if (wr == 0) PG8_BAR;
	s_add_i32 s20, s77, s7
	v_lshl_add_u64 v[98:99], v[220:221], 0, s[4:5]
	s_mov_b32 m0, s20
	ds_read_b128 v[164:167], v219 offset:49152
	ds_read_b128 v[168:171], v219 offset:50176
	ds_read_b128 v[172:175], v219 offset:51200
	ds_read_b128 v[176:179], v219 offset:52224
	ds_read_b128 v[180:183], v219 offset:53248
	ds_read_b128 v[184:187], v219 offset:54272
	ds_read_b128 v[188:191], v219 offset:55296
	ds_read_b128 v[230:233], v219 offset:56320
	global_load_lds_dwordx4 v[98:99], off
	s_add_i32 m0, s20, 0x2000
	s_add_u32 s18, s18, 0x20080
	v_lshl_add_u64 v[98:99], v[234:235], 0, s[4:5]
	s_addc_u32 s19, s19, 0
	s_add_i32 s20, s78, s7
	global_load_lds_dwordx4 v[98:99], off
	v_lshl_add_u64 v[98:99], s[18:19], 0, v[208:209]
	s_mov_b32 m0, s20
	s_nop 0
	global_load_lds_dwordx4 v[98:99], off
	v_lshl_add_u64 v[98:99], s[18:19], 0, v[192:193]
	s_add_i32 m0, s20, 0x2000
	s_nop 0
	global_load_lds_dwordx4 v[98:99], off
	v_lshl_add_u64 v[98:99], v[236:237], 0, s[4:5]
	s_mov_b32 m0, s40
	s_nop 0
	global_load_lds_dwordx4 v[98:99], off
	v_lshl_add_u64 v[98:99], v[238:239], 0, s[4:5]
	s_mov_b32 m0, s41
	s_nop 0
	global_load_lds_dwordx4 v[98:99], off
	s_waitcnt vmcnt(8)
	s_waitcnt lgkmcnt(0)
	s_barrier
	s_waitcnt lgkmcnt(0)
	v_mfma_f32_16x16x32_bf16 v[60:63], v[132:135], v[164:167], v[60:63]
	v_mfma_f32_16x16x32_bf16 v[56:59], v[140:143], v[164:167], v[56:59]
	v_mfma_f32_16x16x32_bf16 v[52:55], v[132:135], v[172:175], v[52:55]
	v_mfma_f32_16x16x32_bf16 v[48:51], v[140:143], v[172:175], v[48:51]
	v_mfma_f32_16x16x32_bf16 v[44:47], v[132:135], v[180:183], v[44:47]
	v_mfma_f32_16x16x32_bf16 v[40:43], v[140:143], v[180:183], v[40:43]
	v_mfma_f32_16x16x32_bf16 v[36:39], v[132:135], v[188:191], v[36:39]
	v_mfma_f32_16x16x32_bf16 v[32:35], v[140:143], v[188:191], v[32:35]
	v_mfma_f32_16x16x32_bf16 v[60:63], v[136:139], v[168:171], v[60:63]
	v_mfma_f32_16x16x32_bf16 v[56:59], v[144:147], v[168:171], v[56:59]
	v_mfma_f32_16x16x32_bf16 v[52:55], v[136:139], v[176:179], v[52:55]
	v_mfma_f32_16x16x32_bf16 v[48:51], v[144:147], v[176:179], v[48:51]
	v_mfma_f32_16x16x32_bf16 v[44:47], v[136:139], v[184:187], v[44:47]
	v_mfma_f32_16x16x32_bf16 v[40:43], v[144:147], v[184:187], v[40:43]
	v_mfma_f32_16x16x32_bf16 v[36:39], v[136:139], v[230:233], v[36:39]
	v_mfma_f32_16x16x32_bf16 v[32:35], v[144:147], v[230:233], v[32:35]
	v_mfma_f32_16x16x32_bf16 v[28:31], v[148:151], v[164:167], v[28:31]
	v_mfma_f32_16x16x32_bf16 v[24:27], v[156:159], v[164:167], v[24:27]
	v_mfma_f32_16x16x32_bf16 v[20:23], v[148:151], v[172:175], v[20:23]
	v_mfma_f32_16x16x32_bf16 v[16:19], v[156:159], v[172:175], v[16:19]
	v_mfma_f32_16x16x32_bf16 v[12:15], v[148:151], v[180:183], v[12:15]
	v_mfma_f32_16x16x32_bf16 v[8:11], v[156:159], v[180:183], v[8:11]
	v_mfma_f32_16x16x32_bf16 v[4:7], v[148:151], v[188:191], v[4:7]
	v_mfma_f32_16x16x32_bf16 v[0:3], v[156:159], v[188:191], v[0:3]
	v_mfma_f32_16x16x32_bf16 v[28:31], v[152:155], v[168:171], v[28:31]
	v_mfma_f32_16x16x32_bf16 v[24:27], v[160:163], v[168:171], v[24:27]
	v_mfma_f32_16x16x32_bf16 v[20:23], v[152:155], v[176:179], v[20:23]
	v_mfma_f32_16x16x32_bf16 v[16:19], v[160:163], v[176:179], v[16:19]
	v_mfma_f32_16x16x32_bf16 v[12:15], v[152:155], v[184:187], v[12:15]
	v_mfma_f32_16x16x32_bf16 v[8:11], v[160:163], v[184:187], v[8:11]
	v_mfma_f32_16x16x32_bf16 v[4:7], v[152:155], v[230:233], v[4:7]
	v_mfma_f32_16x16x32_bf16 v[0:3], v[160:163], v[230:233], v[0:3]
	s_barrier
	s_add_i32 s76, s76, 2
	s_add_u32 s74, s74, 0x100
	s_addc_u32 s75, s75, 0
	s_add_u32 s16, s16, 0x100
	s_addc_u32 s17, s17, 0
	s_cmp_gt_u32 s76, 5
	s_cbranch_scc0 .LBB0_727
	s_and_b64 vcc, exec, s[2:3]
	s_cbranch_vccz .LBB0_730
	s_barrier

; #define PG8_STAGE(bufoff, gbase, voff) do { _Pragma("unroll") for (int _i = 0; _i < 2; ++_i) \
;         __builtin_amdgcn_global_load_lds((const unsigned*)((const char*)(gbase) + (voff)[_i]), (LAS unsigned*)(lds + (bufoff) + ldsw + _i * 8192), 16, 0, 0); } while (0)
; #define PG8_LDA(dst, b, h) do { _Pragma("unroll") for (int m = 0; m < 4; ++m) _Pragma("unroll") for (int k = 0; k < 2; ++k) dst[m][k] = *(const LAS bf16x8*)(lds + PG8_SA(b, h) + aoff + m * 2048 + k * 1024); } while (0)
; #define PG8_LDB(dst, b, h) do { _Pragma("unroll") for (int n = 0; n < 2; ++n) _Pragma("unroll") for (int k = 0; k < 2; ++k) dst[n][k] = *(const LAS bf16x8*)(lds + PG8_SB(b, h) + boff + n * 2048 + k * 1024); } while (0)
; #define PG8_MMA(ai, bj, At, Bt) do { __builtin_amdgcn_s_setprio(1); _Pragma("unroll") for (int m = 0; m < 4; ++m) _Pragma("unroll") for (int n = 0; n < 2; ++n) _Pragma("unroll") for (int k = 0; k < 2; ++k) \
;         acc[ai][bj][m][n] = __builtin_amdgcn_mfma_f32_16x16x32_bf16(Bt[n][k], At[m][k], acc[ai][bj][m][n], 0, 0, 0); __builtin_amdgcn_s_setprio(0); } while (0)
; #define PG8_WAIT_V(n) asm volatile("s_waitcnt vmcnt(" #n ")" ::: "memory")
; #define PG8_WAIT_L(n) asm volatile("s_waitcnt lgkmcnt(" #n ")" ::: "memory")
; #define PG8_BAR __builtin_amdgcn_s_barrier()
; #define PG8_SCHED __builtin_amdgcn_sched_barrier(0)
; template <class Epi, class Sched>
; __device__ __forceinline__ void gemm_phase(LAS unsigned char* lds, const Gemm g, const Sched& S, const Epi& E) {
;     ...
;         for (int t = 0; t < nt; t += 2) {
;             const bool last = (t == nt - 2);
;             const char* a1 = cA + (size_t)(t + 1) * kstep;
;             const char* a2 = last ? nA : cA + (size_t)(t + 2) * kstep; const char* b2 = last ? nB : cB + (size_t)(t + 2) * kstep;
;             const char* a3 = a2 + kstep; const char* b3 = b2 + kstep;
;             PG8_LDB(B0, 0, 0); PG8_LDB(B1, 0, 1); PG8_SCHED; PG8_LDA(At, 0, 0); PG8_STAGE(PG8_SA(1, 1), a1 + hstepA, voffA);
;             PG8_WAIT_V(8); PG8_WAIT_L(0); PG8_BAR; PG8_MMA(0, 0, At, B0); PG8_MMA(0, 1, At, B1); PG8_BAR; PG8_SCHED;
;             PG8_LDA(At, 0, 1); PG8_STAGE(PG8_SB(0, 0), b2, voffB); PG8_STAGE(PG8_SB(0, 1), b2 + hstepB, voffB); PG8_STAGE(PG8_SA(0, 0), a2, voffA);
;             PG8_WAIT_V(8); PG8_WAIT_L(0); PG8_BAR; PG8_MMA(1, 0, At, B0); PG8_MMA(1, 1, At, B1); PG8_BAR; PG8_SCHED;
.LBB0_879:
	s_add_u32 s20, s0, 0xfffc0080
	s_addc_u32 s21, s1, -1
	s_add_i32 s58, 0, 0x10000
	s_cmp_eq_u32 s57, 12
	s_cselect_b32 s23, s15, s21
	s_cselect_b32 s22, s49, s20
	v_add_u32_e32 v96, s58, v231
	s_cselect_b32 s21, s13, s56
	s_cselect_b32 s20, s50, s51
	s_add_i32 s60, 0, 0x14000
	ds_read_b128 v[118:121], v96
	ds_read_b128 v[126:129], v96 offset:1024
	ds_read_b128 v[134:137], v96 offset:2048
	ds_read_b128 v[138:141], v96 offset:3072
	v_add_u32_e32 v96, s60, v231
	ds_read_b128 v[146:149], v96
	ds_read_b128 v[150:153], v96 offset:1024
	ds_read_b128 v[154:157], v96 offset:2048
	ds_read_b128 v[158:161], v96 offset:3072
	v_lshl_add_u64 v[218:219], s[0:1], 0, v[216:217]
	s_add_i32 m0, s25, 0xc000
	ds_read_b128 v[162:165], v232
	ds_read_b128 v[166:169], v232 offset:1024
	ds_read_b128 v[170:173], v232 offset:2048
	ds_read_b128 v[174:177], v232 offset:3072
	ds_read_b128 v[178:181], v232 offset:4096
	ds_read_b128 v[182:185], v232 offset:5120
	ds_read_b128 v[186:189], v232 offset:6144
	ds_read_b128 v[190:193], v232 offset:7168
	global_load_lds_dwordx4 v[218:219], off
	v_lshl_add_u64 v[218:219], s[0:1], 0, v[214:215]
	s_add_i32 m0, s25, 0xe000
	s_nop 0
	global_load_lds_dwordx4 v[218:219], off
	s_waitcnt vmcnt(8)
	s_waitcnt lgkmcnt(0)
	s_barrier
	s_waitcnt lgkmcnt(0)
	v_mfma_f32_16x16x32_bf16 v[142:145], v[118:121], v[162:165], v[142:145]
	v_mfma_f32_16x16x32_bf16 v[130:133], v[134:137], v[162:165], v[130:133]
	v_mfma_f32_16x16x32_bf16 v[110:113], v[118:121], v[170:173], v[110:113]
	v_mfma_f32_16x16x32_bf16 v[106:109], v[134:137], v[170:173], v[106:109]
	v_mfma_f32_16x16x32_bf16 v[92:95], v[118:121], v[178:181], v[92:95]
	v_mfma_f32_16x16x32_bf16 v[88:91], v[134:137], v[178:181], v[88:91]
	v_mfma_f32_16x16x32_bf16 v[76:79], v[118:121], v[186:189], v[76:79]
	v_mfma_f32_16x16x32_bf16 v[72:75], v[134:137], v[186:189], v[72:75]
	v_mfma_f32_16x16x32_bf16 v[142:145], v[126:129], v[166:169], v[142:145]
	v_mfma_f32_16x16x32_bf16 v[130:133], v[138:141], v[166:169], v[130:133]
	v_mfma_f32_16x16x32_bf16 v[110:113], v[126:129], v[174:177], v[110:113]
	v_mfma_f32_16x16x32_bf16 v[106:109], v[138:141], v[174:177], v[106:109]
	v_mfma_f32_16x16x32_bf16 v[92:95], v[126:129], v[182:185], v[92:95]
	v_mfma_f32_16x16x32_bf16 v[88:91], v[138:141], v[182:185], v[88:91]
	v_mfma_f32_16x16x32_bf16 v[76:79], v[126:129], v[190:193], v[76:79]
	v_mfma_f32_16x16x32_bf16 v[72:75], v[138:141], v[190:193], v[72:75]
	v_mfma_f32_16x16x32_bf16 v[122:125], v[146:149], v[162:165], v[122:125]
	v_mfma_f32_16x16x32_bf16 v[114:117], v[154:157], v[162:165], v[114:117]
	v_mfma_f32_16x16x32_bf16 v[102:105], v[146:149], v[170:173], v[102:105]
	v_mfma_f32_16x16x32_bf16 v[98:101], v[154:157], v[170:173], v[98:101]
	v_mfma_f32_16x16x32_bf16 v[84:87], v[146:149], v[178:181], v[84:87]
	v_mfma_f32_16x16x32_bf16 v[80:83], v[154:157], v[178:181], v[80:83]
	v_mfma_f32_16x16x32_bf16 v[68:71], v[146:149], v[186:189], v[68:71]
	v_mfma_f32_16x16x32_bf16 v[64:67], v[154:157], v[186:189], v[64:67]
	v_mfma_f32_16x16x32_bf16 v[122:125], v[150:153], v[166:169], v[122:125]
	v_mfma_f32_16x16x32_bf16 v[114:117], v[158:161], v[166:169], v[114:117]
	v_mfma_f32_16x16x32_bf16 v[102:105], v[150:153], v[174:177], v[102:105]
	v_mfma_f32_16x16x32_bf16 v[98:101], v[158:161], v[174:177], v[98:101]
	v_mfma_f32_16x16x32_bf16 v[84:87], v[150:153], v[182:185], v[84:87]
	v_mfma_f32_16x16x32_bf16 v[80:83], v[158:161], v[182:185], v[80:83]
	v_mfma_f32_16x16x32_bf16 v[68:71], v[150:153], v[190:193], v[68:71]
	v_mfma_f32_16x16x32_bf16 v[64:67], v[158:161], v[190:193], v[64:67]
	s_barrier
	s_add_i32 s58, s58, s7
	v_lshl_add_u64 v[218:219], s[20:21], 0, v[210:211]
	s_mov_b32 m0, s58
	ds_read_b128 v[162:165], v232 offset:16384
	ds_read_b128 v[166:169], v232 offset:17408
	ds_read_b128 v[170:173], v232 offset:18432
	ds_read_b128 v[174:177], v232 offset:19456
	ds_read_b128 v[178:181], v232 offset:20480
	ds_read_b128 v[182:185], v232 offset:21504
	ds_read_b128 v[186:189], v232 offset:22528
	ds_read_b128 v[190:193], v232 offset:23552
	global_load_lds_dwordx4 v[218:219], off
	s_add_i32 m0, s58, 0x2000
	s_add_u32 s58, s20, 0x40000
	v_lshl_add_u64 v[220:221], s[20:21], 0, v[206:207]
	s_addc_u32 s59, s21, 0
	s_add_i32 s60, s60, s7
	global_load_lds_dwordx4 v[220:221], off
	v_lshl_add_u64 v[234:235], s[58:59], 0, v[210:211]
	s_mov_b32 m0, s60
	v_lshl_add_u64 v[236:237], s[22:23], 0, v[208:209]
	global_load_lds_dwordx4 v[234:235], off
	v_lshl_add_u64 v[234:235], s[58:59], 0, v[206:207]
	s_add_i32 m0, s60, 0x2000
	s_nop 0
	global_load_lds_dwordx4 v[234:235], off
	v_lshl_add_u64 v[234:235], s[22:23], 0, v[212:213]
	s_mov_b32 m0, s25
	s_nop 0
	global_load_lds_dwordx4 v[234:235], off
	s_mov_b32 m0, s27
	s_nop 0
	global_load_lds_dwordx4 v[236:237], off
	s_waitcnt vmcnt(8)
	s_waitcnt lgkmcnt(0)
	s_barrier
; #define PG8_STAGE(bufoff, gbase, voff) do { _Pragma("unroll") for (int _i = 0; _i < 2; ++_i) \
;         __builtin_amdgcn_global_load_lds((const unsigned*)((const char*)(gbase) + (voff)[_i]), (LAS unsigned*)(lds + (bufoff) + ldsw + _i * 8192), 16, 0, 0); } while (0)
; #define PG8_LDA(dst, b, h) do { _Pragma("unroll") for (int m = 0; m < 4; ++m) _Pragma("unroll") for (int k = 0; k < 2; ++k) dst[m][k] = *(const LAS bf16x8*)(lds + PG8_SA(b, h) + aoff + m * 2048 + k * 1024); } while (0)
; #define PG8_LDB(dst, b, h) do { _Pragma("unroll") for (int n = 0; n < 2; ++n) _Pragma("unroll") for (int k = 0; k < 2; ++k) dst[n][k] = *(const LAS bf16x8*)(lds + PG8_SB(b, h) + boff + n * 2048 + k * 1024); } while (0)
; #define PG8_MMA(ai, bj, At, Bt) do { __builtin_amdgcn_s_setprio(1); _Pragma("unroll") for (int m = 0; m < 4; ++m) _Pragma("unroll") for (int n = 0; n < 2; ++n) _Pragma("unroll") for (int k = 0; k < 2; ++k) \
;         acc[ai][bj][m][n] = __builtin_amdgcn_mfma_f32_16x16x32_bf16(Bt[n][k], At[m][k], acc[ai][bj][m][n], 0, 0, 0); __builtin_amdgcn_s_setprio(0); } while (0)
; #define PG8_WAIT_V(n) asm volatile("s_waitcnt vmcnt(" #n ")" ::: "memory")
; #define PG8_WAIT_L(n) asm volatile("s_waitcnt lgkmcnt(" #n ")" ::: "memory")
; #define PG8_BAR __builtin_amdgcn_s_barrier()
; #define PG8_SCHED __builtin_amdgcn_sched_barrier(0)
; template <class Epi, class Sched>
; __device__ __forceinline__ void gemm_phase(LAS unsigned char* lds, const Gemm g, const Sched& S, const Epi& E) {
;     ...
;             PG8_LDA(At, 0, 1); PG8_STAGE(PG8_SB(0, 0), b2, voffB); PG8_STAGE(PG8_SB(0, 1), b2 + hstepB, voffB); PG8_STAGE(PG8_SA(0, 0), a2, voffA);
;             PG8_WAIT_V(8); PG8_WAIT_L(0); PG8_BAR; PG8_MMA(1, 0, At, B0); PG8_MMA(1, 1, At, B1); PG8_BAR; PG8_SCHED;
;             PG8_LDB(B0, 1, 0); PG8_LDB(B1, 1, 1); PG8_SCHED; PG8_LDA(At, 1, 0); PG8_STAGE(PG8_SA(0, 1), a2 + hstepA, voffA);
;             PG8_WAIT_V(8); PG8_WAIT_L(0); PG8_BAR; PG8_MMA(0, 0, At, B0); PG8_MMA(0, 1, At, B1); PG8_BAR; PG8_SCHED;
;             PG8_LDA(At, 1, 1); PG8_STAGE(PG8_SB(1, 0), b3, voffB); PG8_STAGE(PG8_SB(1, 1), b3 + hstepB, voffB); PG8_STAGE(PG8_SA(1, 0), a3, voffA);
	s_waitcnt lgkmcnt(0)
	v_mfma_f32_16x16x32_bf16 v[60:63], v[118:121], v[162:165], v[60:63]
	v_mfma_f32_16x16x32_bf16 v[56:59], v[134:137], v[162:165], v[56:59]
	v_mfma_f32_16x16x32_bf16 v[44:47], v[118:121], v[170:173], v[44:47]
	v_mfma_f32_16x16x32_bf16 v[40:43], v[134:137], v[170:173], v[40:43]
	v_mfma_f32_16x16x32_bf16 v[28:31], v[118:121], v[178:181], v[28:31]
	v_mfma_f32_16x16x32_bf16 v[24:27], v[134:137], v[178:181], v[24:27]
	v_mfma_f32_16x16x32_bf16 v[12:15], v[118:121], v[186:189], v[12:15]
	v_mfma_f32_16x16x32_bf16 v[8:11], v[134:137], v[186:189], v[8:11]
	v_mfma_f32_16x16x32_bf16 v[60:63], v[126:129], v[166:169], v[60:63]
	v_mfma_f32_16x16x32_bf16 v[56:59], v[138:141], v[166:169], v[56:59]
	v_mfma_f32_16x16x32_bf16 v[44:47], v[126:129], v[174:177], v[44:47]
	v_mfma_f32_16x16x32_bf16 v[40:43], v[138:141], v[174:177], v[40:43]
	v_mfma_f32_16x16x32_bf16 v[28:31], v[126:129], v[182:185], v[28:31]
	v_mfma_f32_16x16x32_bf16 v[24:27], v[138:141], v[182:185], v[24:27]
	v_mfma_f32_16x16x32_bf16 v[12:15], v[126:129], v[190:193], v[12:15]
	v_mfma_f32_16x16x32_bf16 v[8:11], v[138:141], v[190:193], v[8:11]
	v_mfma_f32_16x16x32_bf16 v[52:55], v[146:149], v[162:165], v[52:55]
	v_mfma_f32_16x16x32_bf16 v[48:51], v[154:157], v[162:165], v[48:51]
	v_mfma_f32_16x16x32_bf16 v[36:39], v[146:149], v[170:173], v[36:39]
	v_mfma_f32_16x16x32_bf16 v[32:35], v[154:157], v[170:173], v[32:35]
	v_mfma_f32_16x16x32_bf16 v[20:23], v[146:149], v[178:181], v[20:23]
	v_mfma_f32_16x16x32_bf16 v[16:19], v[154:157], v[178:181], v[16:19]
	v_mfma_f32_16x16x32_bf16 v[4:7], v[146:149], v[186:189], v[4:7]
	v_mfma_f32_16x16x32_bf16 v[0:3], v[154:157], v[186:189], v[0:3]
	v_mfma_f32_16x16x32_bf16 v[52:55], v[150:153], v[166:169], v[52:55]
	v_mfma_f32_16x16x32_bf16 v[48:51], v[158:161], v[166:169], v[48:51]
	v_mfma_f32_16x16x32_bf16 v[36:39], v[150:153], v[174:177], v[36:39]
	v_mfma_f32_16x16x32_bf16 v[32:35], v[158:161], v[174:177], v[32:35]
	v_mfma_f32_16x16x32_bf16 v[20:23], v[150:153], v[182:185], v[20:23]
	v_mfma_f32_16x16x32_bf16 v[16:19], v[158:161], v[182:185], v[16:19]
	v_mfma_f32_16x16x32_bf16 v[4:7], v[150:153], v[190:193], v[4:7]
	v_mfma_f32_16x16x32_bf16 v[0:3], v[158:161], v[190:193], v[0:3]
	s_barrier
	s_add_i32 s58, 0, 0x18000
	v_add_u32_e32 v96, s58, v231
	s_add_i32 s59, 0, 0x1c000
	ds_read_b128 v[118:121], v96
	ds_read_b128 v[126:129], v96 offset:1024
	ds_read_b128 v[134:137], v96 offset:2048
	ds_read_b128 v[138:141], v96 offset:3072
	v_add_u32_e32 v96, s59, v231
	ds_read_b128 v[146:149], v96
	ds_read_b128 v[150:153], v96 offset:1024
	ds_read_b128 v[154:157], v96 offset:2048
	ds_read_b128 v[158:161], v96 offset:3072
	s_add_u32 s22, s22, 0x40000
	s_addc_u32 s23, s23, 0
	s_mov_b32 m0, s29
	v_lshl_add_u64 v[238:239], s[22:23], 0, v[212:213]
	ds_read_b128 v[162:165], v232 offset:32768
	ds_read_b128 v[166:169], v232 offset:33792
	ds_read_b128 v[170:173], v232 offset:34816
	ds_read_b128 v[174:177], v232 offset:35840
	ds_read_b128 v[178:181], v232 offset:36864
	ds_read_b128 v[182:185], v232 offset:37888
	ds_read_b128 v[186:189], v232 offset:38912
	ds_read_b128 v[190:193], v232 offset:39936
	global_load_lds_dwordx4 v[238:239], off
	v_lshl_add_u64 v[238:239], s[22:23], 0, v[208:209]
	s_mov_b32 m0, s31
	s_nop 0
	global_load_lds_dwordx4 v[238:239], off
	s_waitcnt vmcnt(8)
	s_waitcnt lgkmcnt(0)
	s_barrier
	s_waitcnt lgkmcnt(0)
	v_mfma_f32_16x16x32_bf16 v[142:145], v[118:121], v[162:165], v[142:145]
	v_mfma_f32_16x16x32_bf16 v[130:133], v[134:137], v[162:165], v[130:133]
	v_mfma_f32_16x16x32_bf16 v[110:113], v[118:121], v[170:173], v[110:113]
	v_mfma_f32_16x16x32_bf16 v[106:109], v[134:137], v[170:173], v[106:109]
	v_mfma_f32_16x16x32_bf16 v[92:95], v[118:121], v[178:181], v[92:95]
	v_mfma_f32_16x16x32_bf16 v[88:91], v[134:137], v[178:181], v[88:91]
	v_mfma_f32_16x16x32_bf16 v[76:79], v[118:121], v[186:189], v[76:79]
	v_mfma_f32_16x16x32_bf16 v[72:75], v[134:137], v[186:189], v[72:75]
	v_mfma_f32_16x16x32_bf16 v[142:145], v[126:129], v[166:169], v[142:145]
	v_mfma_f32_16x16x32_bf16 v[130:133], v[138:141], v[166:169], v[130:133]
	v_mfma_f32_16x16x32_bf16 v[110:113], v[126:129], v[174:177], v[110:113]
	v_mfma_f32_16x16x32_bf16 v[106:109], v[138:141], v[174:177], v[106:109]
	v_mfma_f32_16x16x32_bf16 v[92:95], v[126:129], v[182:185], v[92:95]
	v_mfma_f32_16x16x32_bf16 v[88:91], v[138:141], v[182:185], v[88:91]
	v_mfma_f32_16x16x32_bf16 v[76:79], v[126:129], v[190:193], v[76:79]
	v_mfma_f32_16x16x32_bf16 v[72:75], v[138:141], v[190:193], v[72:75]
	v_mfma_f32_16x16x32_bf16 v[122:125], v[146:149], v[162:165], v[122:125]
	v_mfma_f32_16x16x32_bf16 v[114:117], v[154:157], v[162:165], v[114:117]
	v_mfma_f32_16x16x32_bf16 v[102:105], v[146:149], v[170:173], v[102:105]
	v_mfma_f32_16x16x32_bf16 v[98:101], v[154:157], v[170:173], v[98:101]
	v_mfma_f32_16x16x32_bf16 v[84:87], v[146:149], v[178:181], v[84:87]
	v_mfma_f32_16x16x32_bf16 v[80:83], v[154:157], v[178:181], v[80:83]
	v_mfma_f32_16x16x32_bf16 v[68:71], v[146:149], v[186:189], v[68:71]
	v_mfma_f32_16x16x32_bf16 v[64:67], v[154:157], v[186:189], v[64:67]
	v_mfma_f32_16x16x32_bf16 v[122:125], v[150:153], v[166:169], v[122:125]
	v_mfma_f32_16x16x32_bf16 v[114:117], v[158:161], v[166:169], v[114:117]
	v_mfma_f32_16x16x32_bf16 v[102:105], v[150:153], v[174:177], v[102:105]
	v_mfma_f32_16x16x32_bf16 v[98:101], v[158:161], v[174:177], v[98:101]
	v_mfma_f32_16x16x32_bf16 v[84:87], v[150:153], v[182:185], v[84:87]
	v_mfma_f32_16x16x32_bf16 v[80:83], v[158:161], v[182:185], v[80:83]
	v_mfma_f32_16x16x32_bf16 v[68:71], v[150:153], v[190:193], v[68:71]
	v_mfma_f32_16x16x32_bf16 v[64:67], v[158:161], v[190:193], v[64:67]
	s_barrier
; #define PG8_STAGE(bufoff, gbase, voff) do { _Pragma("unroll") for (int _i = 0; _i < 2; ++_i) \
;         __builtin_amdgcn_global_load_lds((const unsigned*)((const char*)(gbase) + (voff)[_i]), (LAS unsigned*)(lds + (bufoff) + ldsw + _i * 8192), 16, 0, 0); } while (0)
; #define PG8_LDA(dst, b, h) do { _Pragma("unroll") for (int m = 0; m < 4; ++m) _Pragma("unroll") for (int k = 0; k < 2; ++k) dst[m][k] = *(const LAS bf16x8*)(lds + PG8_SA(b, h) + aoff + m * 2048 + k * 1024); } while (0)
; #define PG8_MMA(ai, bj, At, Bt) do { __builtin_amdgcn_s_setprio(1); _Pragma("unroll") for (int m = 0; m < 4; ++m) _Pragma("unroll") for (int n = 0; n < 2; ++n) _Pragma("unroll") for (int k = 0; k < 2; ++k) \
;         acc[ai][bj][m][n] = __builtin_amdgcn_mfma_f32_16x16x32_bf16(Bt[n][k], At[m][k], acc[ai][bj][m][n], 0, 0, 0); __builtin_amdgcn_s_setprio(0); } while (0)
; #define PG8_WAIT_V(n) asm volatile("s_waitcnt vmcnt(" #n ")" ::: "memory")
; #define PG8_WAIT_L(n) asm volatile("s_waitcnt lgkmcnt(" #n ")" ::: "memory")
; #define PG8_BAR __builtin_amdgcn_s_barrier()
; #define PG8_SCHED __builtin_amdgcn_sched_barrier(0)
; template <class Epi, class Sched>
; __device__ __forceinline__ void gemm_phase(LAS unsigned char* lds, const Gemm g, const Sched& S, const Epi& E) {
;     ...
;             PG8_LDA(At, 1, 1); PG8_STAGE(PG8_SB(1, 0), b3, voffB); PG8_STAGE(PG8_SB(1, 1), b3 + hstepB, voffB); PG8_STAGE(PG8_SA(1, 0), a3, voffA);
;             PG8_WAIT_V(8); PG8_WAIT_L(0); PG8_BAR; PG8_MMA(1, 0, At, B0); PG8_MMA(1, 1, At, B1); PG8_BAR; PG8_SCHED;
;         }
;         if (wr == 0) PG8_BAR;
	s_add_i32 s22, s58, s7
	v_lshl_add_u64 v[218:219], v[218:219], 0, s[4:5]
	s_mov_b32 m0, s22
	ds_read_b128 v[162:165], v232 offset:49152
	ds_read_b128 v[166:169], v232 offset:50176
	ds_read_b128 v[170:173], v232 offset:51200
	ds_read_b128 v[174:177], v232 offset:52224
	ds_read_b128 v[178:181], v232 offset:53248
	ds_read_b128 v[182:185], v232 offset:54272
	ds_read_b128 v[186:189], v232 offset:55296
	ds_read_b128 v[190:193], v232 offset:56320
	global_load_lds_dwordx4 v[218:219], off
	s_add_i32 m0, s22, 0x2000
	s_add_u32 s20, s20, 0x40080
	v_lshl_add_u64 v[218:219], v[220:221], 0, s[4:5]
	s_addc_u32 s21, s21, 0
	s_add_i32 s22, s59, s7
	global_load_lds_dwordx4 v[218:219], off
	v_lshl_add_u64 v[218:219], s[20:21], 0, v[210:211]
	s_mov_b32 m0, s22
	s_nop 0
	global_load_lds_dwordx4 v[218:219], off
	v_lshl_add_u64 v[218:219], s[20:21], 0, v[206:207]
	s_add_i32 m0, s22, 0x2000
	s_nop 0
	global_load_lds_dwordx4 v[218:219], off
	v_lshl_add_u64 v[218:219], v[234:235], 0, s[4:5]
	s_mov_b32 m0, s42
	s_nop 0
	global_load_lds_dwordx4 v[218:219], off
	v_lshl_add_u64 v[218:219], v[236:237], 0, s[4:5]
	s_mov_b32 m0, s43
	s_nop 0
	global_load_lds_dwordx4 v[218:219], off
	s_waitcnt vmcnt(8)
	s_waitcnt lgkmcnt(0)
	s_barrier
	s_waitcnt lgkmcnt(0)
	v_mfma_f32_16x16x32_bf16 v[60:63], v[118:121], v[162:165], v[60:63]
	v_mfma_f32_16x16x32_bf16 v[56:59], v[134:137], v[162:165], v[56:59]
	v_mfma_f32_16x16x32_bf16 v[44:47], v[118:121], v[170:173], v[44:47]
	v_mfma_f32_16x16x32_bf16 v[40:43], v[134:137], v[170:173], v[40:43]
	v_mfma_f32_16x16x32_bf16 v[28:31], v[118:121], v[178:181], v[28:31]
	v_mfma_f32_16x16x32_bf16 v[24:27], v[134:137], v[178:181], v[24:27]
	v_mfma_f32_16x16x32_bf16 v[12:15], v[118:121], v[186:189], v[12:15]
	v_mfma_f32_16x16x32_bf16 v[8:11], v[134:137], v[186:189], v[8:11]
	v_mfma_f32_16x16x32_bf16 v[60:63], v[126:129], v[166:169], v[60:63]
	v_mfma_f32_16x16x32_bf16 v[56:59], v[138:141], v[166:169], v[56:59]
	v_mfma_f32_16x16x32_bf16 v[44:47], v[126:129], v[174:177], v[44:47]
	v_mfma_f32_16x16x32_bf16 v[40:43], v[138:141], v[174:177], v[40:43]
	v_mfma_f32_16x16x32_bf16 v[28:31], v[126:129], v[182:185], v[28:31]
	v_mfma_f32_16x16x32_bf16 v[24:27], v[138:141], v[182:185], v[24:27]
	v_mfma_f32_16x16x32_bf16 v[12:15], v[126:129], v[190:193], v[12:15]
	v_mfma_f32_16x16x32_bf16 v[8:11], v[138:141], v[190:193], v[8:11]
	v_mfma_f32_16x16x32_bf16 v[52:55], v[146:149], v[162:165], v[52:55]
	v_mfma_f32_16x16x32_bf16 v[48:51], v[154:157], v[162:165], v[48:51]
	v_mfma_f32_16x16x32_bf16 v[36:39], v[146:149], v[170:173], v[36:39]
	v_mfma_f32_16x16x32_bf16 v[32:35], v[154:157], v[170:173], v[32:35]
	v_mfma_f32_16x16x32_bf16 v[20:23], v[146:149], v[178:181], v[20:23]
	v_mfma_f32_16x16x32_bf16 v[16:19], v[154:157], v[178:181], v[16:19]
	v_mfma_f32_16x16x32_bf16 v[4:7], v[146:149], v[186:189], v[4:7]
	v_mfma_f32_16x16x32_bf16 v[0:3], v[154:157], v[186:189], v[0:3]
	v_mfma_f32_16x16x32_bf16 v[52:55], v[150:153], v[166:169], v[52:55]
	v_mfma_f32_16x16x32_bf16 v[48:51], v[158:161], v[166:169], v[48:51]
	v_mfma_f32_16x16x32_bf16 v[36:39], v[150:153], v[174:177], v[36:39]
	v_mfma_f32_16x16x32_bf16 v[32:35], v[158:161], v[174:177], v[32:35]
	v_mfma_f32_16x16x32_bf16 v[20:23], v[150:153], v[182:185], v[20:23]
	v_mfma_f32_16x16x32_bf16 v[16:19], v[158:161], v[182:185], v[16:19]
	v_mfma_f32_16x16x32_bf16 v[4:7], v[150:153], v[190:193], v[4:7]
	v_mfma_f32_16x16x32_bf16 v[0:3], v[158:161], v[190:193], v[0:3]
	s_barrier
	s_add_i32 s57, s57, 2
	s_add_u32 s51, s51, 0x100
	s_addc_u32 s56, s56, 0
	s_add_u32 s0, s0, 0x100
	s_addc_u32 s1, s1, 0
	s_cmp_gt_u32 s57, 13
	s_cbranch_scc0 .LBB0_879
	s_and_b64 vcc, exec, s[10:11]
	s_cbranch_vccz .LBB0_882
	s_barrier

; #define PG8_STAGE(bufoff, gbase, voff) do { _Pragma("unroll") for (int _i = 0; _i < 2; ++_i) \
;         __builtin_amdgcn_global_load_lds((const unsigned*)((const char*)(gbase) + (voff)[_i]), (LAS unsigned*)(lds + (bufoff) + ldsw + _i * 8192), 16, 0, 0); } while (0)
; #define PG8_LDA(dst, b, h) do { _Pragma("unroll") for (int m = 0; m < 4; ++m) _Pragma("unroll") for (int k = 0; k < 2; ++k) dst[m][k] = *(const LAS bf16x8*)(lds + PG8_SA(b, h) + aoff + m * 2048 + k * 1024); } while (0)
; #define PG8_LDB(dst, b, h) do { _Pragma("unroll") for (int n = 0; n < 2; ++n) _Pragma("unroll") for (int k = 0; k < 2; ++k) dst[n][k] = *(const LAS bf16x8*)(lds + PG8_SB(b, h) + boff + n * 2048 + k * 1024); } while (0)
; #define PG8_MMA(ai, bj, At, Bt) do { __builtin_amdgcn_s_setprio(1); _Pragma("unroll") for (int m = 0; m < 4; ++m) _Pragma("unroll") for (int n = 0; n < 2; ++n) _Pragma("unroll") for (int k = 0; k < 2; ++k) \
;         acc[ai][bj][m][n] = __builtin_amdgcn_mfma_f32_16x16x32_bf16(Bt[n][k], At[m][k], acc[ai][bj][m][n], 0, 0, 0); __builtin_amdgcn_s_setprio(0); } while (0)
; #define PG8_WAIT_V(n) asm volatile("s_waitcnt vmcnt(" #n ")" ::: "memory")
; #define PG8_WAIT_L(n) asm volatile("s_waitcnt lgkmcnt(" #n ")" ::: "memory")
; #define PG8_BAR __builtin_amdgcn_s_barrier()
; #define PG8_SCHED __builtin_amdgcn_sched_barrier(0)
; template <class Epi, class Sched>
; __device__ __forceinline__ void gemm_phase(LAS unsigned char* lds, const Gemm g, const Sched& S, const Epi& E) {
;     ...
;         for (int t = 0; t < nt; t += 2) {
;             const bool last = (t == nt - 2);
;             const char* a1 = cA + (size_t)(t + 1) * kstep;
;             const char* a2 = last ? nA : cA + (size_t)(t + 2) * kstep; const char* b2 = last ? nB : cB + (size_t)(t + 2) * kstep;
;             const char* a3 = a2 + kstep; const char* b3 = b2 + kstep;
;             PG8_LDB(B0, 0, 0); PG8_LDB(B1, 0, 1); PG8_SCHED; PG8_LDA(At, 0, 0); PG8_STAGE(PG8_SA(1, 1), a1 + hstepA, voffA);
;             PG8_WAIT_V(8); PG8_WAIT_L(0); PG8_BAR; PG8_MMA(0, 0, At, B0); PG8_MMA(0, 1, At, B1); PG8_BAR; PG8_SCHED;
;             PG8_LDA(At, 0, 1); PG8_STAGE(PG8_SB(0, 0), b2, voffB); PG8_STAGE(PG8_SB(0, 1), b2 + hstepB, voffB); PG8_STAGE(PG8_SA(0, 0), a2, voffA);
;             PG8_WAIT_V(8); PG8_WAIT_L(0); PG8_BAR; PG8_MMA(1, 0, At, B0); PG8_MMA(1, 1, At, B1); PG8_BAR; PG8_SCHED;
.LBB0_924:
	s_add_u32 s20, s0, 0xfffc0080
	s_addc_u32 s21, s1, -1
	s_add_i32 s58, 0, 0x10000
	s_cmp_eq_u32 s57, 12
	s_cselect_b32 s23, s15, s21
	s_cselect_b32 s22, s49, s20
	s_cselect_b32 s21, s13, s56
	s_cselect_b32 s20, s50, s51
	s_add_i32 s60, 0, 0x14000
	v_add_u32_e32 v142, s58, v214
	v_add_u32_e32 v158, s60, v214
	ds_read_b128 v[130:133], v142
	ds_read_b128 v[134:137], v142 offset:1024
	ds_read_b128 v[138:141], v142 offset:2048
	ds_read_b128 v[142:145], v142 offset:3072
	ds_read_b128 v[146:149], v158
	ds_read_b128 v[150:153], v158 offset:1024
	ds_read_b128 v[154:157], v158 offset:2048
	ds_read_b128 v[158:161], v158 offset:3072
	v_lshl_add_u64 v[192:193], s[0:1], 0, v[186:187]
	s_add_i32 m0, s25, 0xc000
	ds_read_b128 v[162:165], v215
	ds_read_b128 v[166:169], v215 offset:1024
	ds_read_b128 v[170:173], v215 offset:2048
	ds_read_b128 v[174:177], v215 offset:3072
	ds_read_b128 v[188:191], v215 offset:4096
	ds_read_b128 v[206:209], v215 offset:5120
	ds_read_b128 v[216:219], v215 offset:6144
	ds_read_b128 v[230:233], v215 offset:7168
	global_load_lds_dwordx4 v[192:193], off
	v_lshl_add_u64 v[192:193], s[0:1], 0, v[184:185]
	s_add_i32 m0, s25, 0xe000
	s_nop 0
	global_load_lds_dwordx4 v[192:193], off
	s_waitcnt vmcnt(8)
	s_waitcnt lgkmcnt(0)
	s_barrier
	s_waitcnt lgkmcnt(0)
	v_mfma_f32_16x16x32_bf16 v[126:129], v[130:133], v[162:165], v[126:129]
	v_mfma_f32_16x16x32_bf16 v[122:125], v[138:141], v[162:165], v[122:125]
	v_mfma_f32_16x16x32_bf16 v[110:113], v[130:133], v[170:173], v[110:113]
	v_mfma_f32_16x16x32_bf16 v[106:109], v[138:141], v[170:173], v[106:109]
	v_mfma_f32_16x16x32_bf16 v[92:95], v[130:133], v[188:191], v[92:95]
	v_mfma_f32_16x16x32_bf16 v[88:91], v[138:141], v[188:191], v[88:91]
	v_mfma_f32_16x16x32_bf16 v[76:79], v[130:133], v[216:219], v[76:79]
	v_mfma_f32_16x16x32_bf16 v[72:75], v[138:141], v[216:219], v[72:75]
	v_mfma_f32_16x16x32_bf16 v[126:129], v[134:137], v[166:169], v[126:129]
	v_mfma_f32_16x16x32_bf16 v[122:125], v[142:145], v[166:169], v[122:125]
	v_mfma_f32_16x16x32_bf16 v[110:113], v[134:137], v[174:177], v[110:113]
	v_mfma_f32_16x16x32_bf16 v[106:109], v[142:145], v[174:177], v[106:109]
	v_mfma_f32_16x16x32_bf16 v[92:95], v[134:137], v[206:209], v[92:95]
	v_mfma_f32_16x16x32_bf16 v[88:91], v[142:145], v[206:209], v[88:91]
	v_mfma_f32_16x16x32_bf16 v[76:79], v[134:137], v[230:233], v[76:79]
	v_mfma_f32_16x16x32_bf16 v[72:75], v[142:145], v[230:233], v[72:75]
	v_mfma_f32_16x16x32_bf16 v[118:121], v[146:149], v[162:165], v[118:121]
	v_mfma_f32_16x16x32_bf16 v[114:117], v[154:157], v[162:165], v[114:117]
	v_mfma_f32_16x16x32_bf16 v[102:105], v[146:149], v[170:173], v[102:105]
	v_mfma_f32_16x16x32_bf16 v[98:101], v[154:157], v[170:173], v[98:101]
	v_mfma_f32_16x16x32_bf16 v[84:87], v[146:149], v[188:191], v[84:87]
	v_mfma_f32_16x16x32_bf16 v[80:83], v[154:157], v[188:191], v[80:83]
	v_mfma_f32_16x16x32_bf16 v[68:71], v[146:149], v[216:219], v[68:71]
	v_mfma_f32_16x16x32_bf16 v[64:67], v[154:157], v[216:219], v[64:67]
	v_mfma_f32_16x16x32_bf16 v[118:121], v[150:153], v[166:169], v[118:121]
	v_mfma_f32_16x16x32_bf16 v[114:117], v[158:161], v[166:169], v[114:117]
	v_mfma_f32_16x16x32_bf16 v[102:105], v[150:153], v[174:177], v[102:105]
	v_mfma_f32_16x16x32_bf16 v[98:101], v[158:161], v[174:177], v[98:101]
	v_mfma_f32_16x16x32_bf16 v[84:87], v[150:153], v[206:209], v[84:87]
	v_mfma_f32_16x16x32_bf16 v[80:83], v[158:161], v[206:209], v[80:83]
	v_mfma_f32_16x16x32_bf16 v[68:71], v[150:153], v[230:233], v[68:71]
	v_mfma_f32_16x16x32_bf16 v[64:67], v[158:161], v[230:233], v[64:67]
	s_barrier
	s_add_i32 s58, s58, s7
	v_lshl_add_u64 v[192:193], s[20:21], 0, v[96:97]
	s_mov_b32 m0, s58
	ds_read_b128 v[162:165], v215 offset:16384
	ds_read_b128 v[166:169], v215 offset:17408
	ds_read_b128 v[170:173], v215 offset:18432
	ds_read_b128 v[174:177], v215 offset:19456
	ds_read_b128 v[188:191], v215 offset:20480
	ds_read_b128 v[206:209], v215 offset:21504
	ds_read_b128 v[216:219], v215 offset:22528
	ds_read_b128 v[230:233], v215 offset:23552
	global_load_lds_dwordx4 v[192:193], off
	s_add_i32 m0, s58, 0x2000
	s_add_u32 s58, s20, 0x40000
	v_lshl_add_u64 v[210:211], s[20:21], 0, v[178:179]
	s_addc_u32 s59, s21, 0
	s_add_i32 s60, s60, s7
	global_load_lds_dwordx4 v[210:211], off
	v_lshl_add_u64 v[220:221], s[58:59], 0, v[96:97]
	s_mov_b32 m0, s60
	v_lshl_add_u64 v[234:235], s[22:23], 0, v[180:181]
	global_load_lds_dwordx4 v[220:221], off
	v_lshl_add_u64 v[220:221], s[58:59], 0, v[178:179]
	s_add_i32 m0, s60, 0x2000
	s_nop 0
	global_load_lds_dwordx4 v[220:221], off
	v_lshl_add_u64 v[220:221], s[22:23], 0, v[182:183]
	s_mov_b32 m0, s25
	s_nop 0
	global_load_lds_dwordx4 v[220:221], off
	s_mov_b32 m0, s27
	s_nop 0
	global_load_lds_dwordx4 v[234:235], off
	s_waitcnt vmcnt(8)
	s_waitcnt lgkmcnt(0)
	s_barrier
; #define PG8_STAGE(bufoff, gbase, voff) do { _Pragma("unroll") for (int _i = 0; _i < 2; ++_i) \
;         __builtin_amdgcn_global_load_lds((const unsigned*)((const char*)(gbase) + (voff)[_i]), (LAS unsigned*)(lds + (bufoff) + ldsw + _i * 8192), 16, 0, 0); } while (0)
; #define PG8_LDA(dst, b, h) do { _Pragma("unroll") for (int m = 0; m < 4; ++m) _Pragma("unroll") for (int k = 0; k < 2; ++k) dst[m][k] = *(const LAS bf16x8*)(lds + PG8_SA(b, h) + aoff + m * 2048 + k * 1024); } while (0)
; #define PG8_LDB(dst, b, h) do { _Pragma("unroll") for (int n = 0; n < 2; ++n) _Pragma("unroll") for (int k = 0; k < 2; ++k) dst[n][k] = *(const LAS bf16x8*)(lds + PG8_SB(b, h) + boff + n * 2048 + k * 1024); } while (0)
; #define PG8_MMA(ai, bj, At, Bt) do { __builtin_amdgcn_s_setprio(1); _Pragma("unroll") for (int m = 0; m < 4; ++m) _Pragma("unroll") for (int n = 0; n < 2; ++n) _Pragma("unroll") for (int k = 0; k < 2; ++k) \
;         acc[ai][bj][m][n] = __builtin_amdgcn_mfma_f32_16x16x32_bf16(Bt[n][k], At[m][k], acc[ai][bj][m][n], 0, 0, 0); __builtin_amdgcn_s_setprio(0); } while (0)
; #define PG8_WAIT_V(n) asm volatile("s_waitcnt vmcnt(" #n ")" ::: "memory")
; #define PG8_WAIT_L(n) asm volatile("s_waitcnt lgkmcnt(" #n ")" ::: "memory")
; #define PG8_BAR __builtin_amdgcn_s_barrier()
; #define PG8_SCHED __builtin_amdgcn_sched_barrier(0)
; template <class Epi, class Sched>
; __device__ __forceinline__ void gemm_phase(LAS unsigned char* lds, const Gemm g, const Sched& S, const Epi& E) {
;     ...
;             PG8_LDA(At, 0, 1); PG8_STAGE(PG8_SB(0, 0), b2, voffB); PG8_STAGE(PG8_SB(0, 1), b2 + hstepB, voffB); PG8_STAGE(PG8_SA(0, 0), a2, voffA);
;             PG8_WAIT_V(8); PG8_WAIT_L(0); PG8_BAR; PG8_MMA(1, 0, At, B0); PG8_MMA(1, 1, At, B1); PG8_BAR; PG8_SCHED;
;             PG8_LDB(B0, 1, 0); PG8_LDB(B1, 1, 1); PG8_SCHED; PG8_LDA(At, 1, 0); PG8_STAGE(PG8_SA(0, 1), a2 + hstepA, voffA);
;             PG8_WAIT_V(8); PG8_WAIT_L(0); PG8_BAR; PG8_MMA(0, 0, At, B0); PG8_MMA(0, 1, At, B1); PG8_BAR; PG8_SCHED;
;             PG8_LDA(At, 1, 1); PG8_STAGE(PG8_SB(1, 0), b3, voffB); PG8_STAGE(PG8_SB(1, 1), b3 + hstepB, voffB); PG8_STAGE(PG8_SA(1, 0), a3, voffA);
	s_waitcnt lgkmcnt(0)
	v_mfma_f32_16x16x32_bf16 v[60:63], v[130:133], v[162:165], v[60:63]
	v_mfma_f32_16x16x32_bf16 v[56:59], v[138:141], v[162:165], v[56:59]
	v_mfma_f32_16x16x32_bf16 v[44:47], v[130:133], v[170:173], v[44:47]
	v_mfma_f32_16x16x32_bf16 v[40:43], v[138:141], v[170:173], v[40:43]
	v_mfma_f32_16x16x32_bf16 v[28:31], v[130:133], v[188:191], v[28:31]
	v_mfma_f32_16x16x32_bf16 v[24:27], v[138:141], v[188:191], v[24:27]
	v_mfma_f32_16x16x32_bf16 v[12:15], v[130:133], v[216:219], v[12:15]
	v_mfma_f32_16x16x32_bf16 v[8:11], v[138:141], v[216:219], v[8:11]
	v_mfma_f32_16x16x32_bf16 v[60:63], v[134:137], v[166:169], v[60:63]
	v_mfma_f32_16x16x32_bf16 v[56:59], v[142:145], v[166:169], v[56:59]
	v_mfma_f32_16x16x32_bf16 v[44:47], v[134:137], v[174:177], v[44:47]
	v_mfma_f32_16x16x32_bf16 v[40:43], v[142:145], v[174:177], v[40:43]
	v_mfma_f32_16x16x32_bf16 v[28:31], v[134:137], v[206:209], v[28:31]
	v_mfma_f32_16x16x32_bf16 v[24:27], v[142:145], v[206:209], v[24:27]
	v_mfma_f32_16x16x32_bf16 v[12:15], v[134:137], v[230:233], v[12:15]
	v_mfma_f32_16x16x32_bf16 v[8:11], v[142:145], v[230:233], v[8:11]
	v_mfma_f32_16x16x32_bf16 v[52:55], v[146:149], v[162:165], v[52:55]
	v_mfma_f32_16x16x32_bf16 v[48:51], v[154:157], v[162:165], v[48:51]
	v_mfma_f32_16x16x32_bf16 v[36:39], v[146:149], v[170:173], v[36:39]
	v_mfma_f32_16x16x32_bf16 v[32:35], v[154:157], v[170:173], v[32:35]
	v_mfma_f32_16x16x32_bf16 v[20:23], v[146:149], v[188:191], v[20:23]
	v_mfma_f32_16x16x32_bf16 v[16:19], v[154:157], v[188:191], v[16:19]
	v_mfma_f32_16x16x32_bf16 v[4:7], v[146:149], v[216:219], v[4:7]
	v_mfma_f32_16x16x32_bf16 v[0:3], v[154:157], v[216:219], v[0:3]
	v_mfma_f32_16x16x32_bf16 v[52:55], v[150:153], v[166:169], v[52:55]
	v_mfma_f32_16x16x32_bf16 v[48:51], v[158:161], v[166:169], v[48:51]
	v_mfma_f32_16x16x32_bf16 v[36:39], v[150:153], v[174:177], v[36:39]
	v_mfma_f32_16x16x32_bf16 v[32:35], v[158:161], v[174:177], v[32:35]
	v_mfma_f32_16x16x32_bf16 v[20:23], v[150:153], v[206:209], v[20:23]
	v_mfma_f32_16x16x32_bf16 v[16:19], v[158:161], v[206:209], v[16:19]
	v_mfma_f32_16x16x32_bf16 v[4:7], v[150:153], v[230:233], v[4:7]
	v_mfma_f32_16x16x32_bf16 v[0:3], v[158:161], v[230:233], v[0:3]
	s_barrier
	s_add_i32 s58, 0, 0x18000
	s_add_i32 s59, 0, 0x1c000
	v_add_u32_e32 v142, s58, v214
	v_add_u32_e32 v158, s59, v214
	ds_read_b128 v[130:133], v142
	ds_read_b128 v[134:137], v142 offset:1024
	ds_read_b128 v[138:141], v142 offset:2048
	ds_read_b128 v[142:145], v142 offset:3072
	ds_read_b128 v[146:149], v158
	ds_read_b128 v[150:153], v158 offset:1024
	ds_read_b128 v[154:157], v158 offset:2048
	ds_read_b128 v[158:161], v158 offset:3072
	s_add_u32 s22, s22, 0x40000
	s_addc_u32 s23, s23, 0
	s_mov_b32 m0, s29
	v_lshl_add_u64 v[236:237], s[22:23], 0, v[182:183]
	ds_read_b128 v[162:165], v215 offset:32768
	ds_read_b128 v[166:169], v215 offset:33792
	ds_read_b128 v[170:173], v215 offset:34816
	ds_read_b128 v[174:177], v215 offset:35840
	ds_read_b128 v[188:191], v215 offset:36864
	ds_read_b128 v[206:209], v215 offset:37888
	ds_read_b128 v[216:219], v215 offset:38912
	ds_read_b128 v[230:233], v215 offset:39936
	global_load_lds_dwordx4 v[236:237], off
	v_lshl_add_u64 v[236:237], s[22:23], 0, v[180:181]
	s_mov_b32 m0, s31
	s_nop 0
	global_load_lds_dwordx4 v[236:237], off
	s_waitcnt vmcnt(8)
	s_waitcnt lgkmcnt(0)
	s_barrier
	s_waitcnt lgkmcnt(0)
	v_mfma_f32_16x16x32_bf16 v[126:129], v[130:133], v[162:165], v[126:129]
	v_mfma_f32_16x16x32_bf16 v[122:125], v[138:141], v[162:165], v[122:125]
	v_mfma_f32_16x16x32_bf16 v[110:113], v[130:133], v[170:173], v[110:113]
	v_mfma_f32_16x16x32_bf16 v[106:109], v[138:141], v[170:173], v[106:109]
	v_mfma_f32_16x16x32_bf16 v[92:95], v[130:133], v[188:191], v[92:95]
	v_mfma_f32_16x16x32_bf16 v[88:91], v[138:141], v[188:191], v[88:91]
	v_mfma_f32_16x16x32_bf16 v[76:79], v[130:133], v[216:219], v[76:79]
	v_mfma_f32_16x16x32_bf16 v[72:75], v[138:141], v[216:219], v[72:75]
	v_mfma_f32_16x16x32_bf16 v[126:129], v[134:137], v[166:169], v[126:129]
	v_mfma_f32_16x16x32_bf16 v[122:125], v[142:145], v[166:169], v[122:125]
	v_mfma_f32_16x16x32_bf16 v[110:113], v[134:137], v[174:177], v[110:113]
	v_mfma_f32_16x16x32_bf16 v[106:109], v[142:145], v[174:177], v[106:109]
	v_mfma_f32_16x16x32_bf16 v[92:95], v[134:137], v[206:209], v[92:95]
	v_mfma_f32_16x16x32_bf16 v[88:91], v[142:145], v[206:209], v[88:91]
	v_mfma_f32_16x16x32_bf16 v[76:79], v[134:137], v[230:233], v[76:79]
	v_mfma_f32_16x16x32_bf16 v[72:75], v[142:145], v[230:233], v[72:75]
	v_mfma_f32_16x16x32_bf16 v[118:121], v[146:149], v[162:165], v[118:121]
	v_mfma_f32_16x16x32_bf16 v[114:117], v[154:157], v[162:165], v[114:117]
	v_mfma_f32_16x16x32_bf16 v[102:105], v[146:149], v[170:173], v[102:105]
	v_mfma_f32_16x16x32_bf16 v[98:101], v[154:157], v[170:173], v[98:101]
	v_mfma_f32_16x16x32_bf16 v[84:87], v[146:149], v[188:191], v[84:87]
	v_mfma_f32_16x16x32_bf16 v[80:83], v[154:157], v[188:191], v[80:83]
	v_mfma_f32_16x16x32_bf16 v[68:71], v[146:149], v[216:219], v[68:71]
	v_mfma_f32_16x16x32_bf16 v[64:67], v[154:157], v[216:219], v[64:67]
	v_mfma_f32_16x16x32_bf16 v[118:121], v[150:153], v[166:169], v[118:121]
	v_mfma_f32_16x16x32_bf16 v[114:117], v[158:161], v[166:169], v[114:117]
	v_mfma_f32_16x16x32_bf16 v[102:105], v[150:153], v[174:177], v[102:105]
	v_mfma_f32_16x16x32_bf16 v[98:101], v[158:161], v[174:177], v[98:101]
	v_mfma_f32_16x16x32_bf16 v[84:87], v[150:153], v[206:209], v[84:87]
	v_mfma_f32_16x16x32_bf16 v[80:83], v[158:161], v[206:209], v[80:83]
	v_mfma_f32_16x16x32_bf16 v[68:71], v[150:153], v[230:233], v[68:71]
	v_mfma_f32_16x16x32_bf16 v[64:67], v[158:161], v[230:233], v[64:67]
	s_barrier
; #define PG8_STAGE(bufoff, gbase, voff) do { _Pragma("unroll") for (int _i = 0; _i < 2; ++_i) \
;         __builtin_amdgcn_global_load_lds((const unsigned*)((const char*)(gbase) + (voff)[_i]), (LAS unsigned*)(lds + (bufoff) + ldsw + _i * 8192), 16, 0, 0); } while (0)
; #define PG8_LDA(dst, b, h) do { _Pragma("unroll") for (int m = 0; m < 4; ++m) _Pragma("unroll") for (int k = 0; k < 2; ++k) dst[m][k] = *(const LAS bf16x8*)(lds + PG8_SA(b, h) + aoff + m * 2048 + k * 1024); } while (0)
; #define PG8_MMA(ai, bj, At, Bt) do { __builtin_amdgcn_s_setprio(1); _Pragma("unroll") for (int m = 0; m < 4; ++m) _Pragma("unroll") for (int n = 0; n < 2; ++n) _Pragma("unroll") for (int k = 0; k < 2; ++k) \
;         acc[ai][bj][m][n] = __builtin_amdgcn_mfma_f32_16x16x32_bf16(Bt[n][k], At[m][k], acc[ai][bj][m][n], 0, 0, 0); __builtin_amdgcn_s_setprio(0); } while (0)
; #define PG8_WAIT_V(n) asm volatile("s_waitcnt vmcnt(" #n ")" ::: "memory")
; #define PG8_WAIT_L(n) asm volatile("s_waitcnt lgkmcnt(" #n ")" ::: "memory")
; #define PG8_BAR __builtin_amdgcn_s_barrier()
; #define PG8_SCHED __builtin_amdgcn_sched_barrier(0)
; template <class Epi, class Sched>
; __device__ __forceinline__ void gemm_phase(LAS unsigned char* lds, const Gemm g, const Sched& S, const Epi& E) {
;     ...
;             PG8_LDA(At, 1, 1); PG8_STAGE(PG8_SB(1, 0), b3, voffB); PG8_STAGE(PG8_SB(1, 1), b3 + hstepB, voffB); PG8_STAGE(PG8_SA(1, 0), a3, voffA);
;             PG8_WAIT_V(8); PG8_WAIT_L(0); PG8_BAR; PG8_MMA(1, 0, At, B0); PG8_MMA(1, 1, At, B1); PG8_BAR; PG8_SCHED;
;         }
;         if (wr == 0) PG8_BAR;
	s_add_i32 s22, s58, s7
	v_lshl_add_u64 v[192:193], v[192:193], 0, s[4:5]
	s_mov_b32 m0, s22
	ds_read_b128 v[162:165], v215 offset:49152
	ds_read_b128 v[166:169], v215 offset:50176
	ds_read_b128 v[170:173], v215 offset:51200
	ds_read_b128 v[174:177], v215 offset:52224
	ds_read_b128 v[188:191], v215 offset:53248
	ds_read_b128 v[206:209], v215 offset:54272
	ds_read_b128 v[216:219], v215 offset:55296
	ds_read_b128 v[230:233], v215 offset:56320
	global_load_lds_dwordx4 v[192:193], off
	s_add_i32 m0, s22, 0x2000
	s_add_u32 s20, s20, 0x40080
	v_lshl_add_u64 v[192:193], v[210:211], 0, s[4:5]
	s_addc_u32 s21, s21, 0
	s_add_i32 s22, s59, s7
	global_load_lds_dwordx4 v[192:193], off
	v_lshl_add_u64 v[192:193], s[20:21], 0, v[96:97]
	s_mov_b32 m0, s22
	s_nop 0
	global_load_lds_dwordx4 v[192:193], off
	v_lshl_add_u64 v[192:193], s[20:21], 0, v[178:179]
	s_add_i32 m0, s22, 0x2000
	s_nop 0
	global_load_lds_dwordx4 v[192:193], off
	v_lshl_add_u64 v[192:193], v[220:221], 0, s[4:5]
	s_mov_b32 m0, s42
	s_nop 0
	global_load_lds_dwordx4 v[192:193], off
	v_lshl_add_u64 v[192:193], v[234:235], 0, s[4:5]
	s_mov_b32 m0, s43
	s_nop 0
	global_load_lds_dwordx4 v[192:193], off
	s_waitcnt vmcnt(8)
	s_waitcnt lgkmcnt(0)
	s_barrier
	s_waitcnt lgkmcnt(0)
	v_mfma_f32_16x16x32_bf16 v[60:63], v[130:133], v[162:165], v[60:63]
	v_mfma_f32_16x16x32_bf16 v[56:59], v[138:141], v[162:165], v[56:59]
	v_mfma_f32_16x16x32_bf16 v[44:47], v[130:133], v[170:173], v[44:47]
	v_mfma_f32_16x16x32_bf16 v[40:43], v[138:141], v[170:173], v[40:43]
	v_mfma_f32_16x16x32_bf16 v[28:31], v[130:133], v[188:191], v[28:31]
	v_mfma_f32_16x16x32_bf16 v[24:27], v[138:141], v[188:191], v[24:27]
	v_mfma_f32_16x16x32_bf16 v[12:15], v[130:133], v[216:219], v[12:15]
	v_mfma_f32_16x16x32_bf16 v[8:11], v[138:141], v[216:219], v[8:11]
	v_mfma_f32_16x16x32_bf16 v[60:63], v[134:137], v[166:169], v[60:63]
	v_mfma_f32_16x16x32_bf16 v[56:59], v[142:145], v[166:169], v[56:59]
	v_mfma_f32_16x16x32_bf16 v[44:47], v[134:137], v[174:177], v[44:47]
	v_mfma_f32_16x16x32_bf16 v[40:43], v[142:145], v[174:177], v[40:43]
	v_mfma_f32_16x16x32_bf16 v[28:31], v[134:137], v[206:209], v[28:31]
	v_mfma_f32_16x16x32_bf16 v[24:27], v[142:145], v[206:209], v[24:27]
	v_mfma_f32_16x16x32_bf16 v[12:15], v[134:137], v[230:233], v[12:15]
	v_mfma_f32_16x16x32_bf16 v[8:11], v[142:145], v[230:233], v[8:11]
	v_mfma_f32_16x16x32_bf16 v[52:55], v[146:149], v[162:165], v[52:55]
	v_mfma_f32_16x16x32_bf16 v[48:51], v[154:157], v[162:165], v[48:51]
	v_mfma_f32_16x16x32_bf16 v[36:39], v[146:149], v[170:173], v[36:39]
	v_mfma_f32_16x16x32_bf16 v[32:35], v[154:157], v[170:173], v[32:35]
	v_mfma_f32_16x16x32_bf16 v[20:23], v[146:149], v[188:191], v[20:23]
	v_mfma_f32_16x16x32_bf16 v[16:19], v[154:157], v[188:191], v[16:19]
	v_mfma_f32_16x16x32_bf16 v[4:7], v[146:149], v[216:219], v[4:7]
	v_mfma_f32_16x16x32_bf16 v[0:3], v[154:157], v[216:219], v[0:3]
	v_mfma_f32_16x16x32_bf16 v[52:55], v[150:153], v[166:169], v[52:55]
	v_mfma_f32_16x16x32_bf16 v[48:51], v[158:161], v[166:169], v[48:51]
	v_mfma_f32_16x16x32_bf16 v[36:39], v[150:153], v[174:177], v[36:39]
	v_mfma_f32_16x16x32_bf16 v[32:35], v[158:161], v[174:177], v[32:35]
	v_mfma_f32_16x16x32_bf16 v[20:23], v[150:153], v[206:209], v[20:23]
	v_mfma_f32_16x16x32_bf16 v[16:19], v[158:161], v[206:209], v[16:19]
	v_mfma_f32_16x16x32_bf16 v[4:7], v[150:153], v[230:233], v[4:7]
	v_mfma_f32_16x16x32_bf16 v[0:3], v[158:161], v[230:233], v[0:3]
	s_barrier
	s_add_i32 s57, s57, 2
	s_add_u32 s51, s51, 0x100
	s_addc_u32 s56, s56, 0
	s_add_u32 s0, s0, 0x100
	s_addc_u32 s1, s1, 0
	s_cmp_gt_u32 s57, 13
	s_cbranch_scc0 .LBB0_924
	s_and_b64 vcc, exec, s[10:11]
	s_cbranch_vccz .LBB0_927
	s_barrier

; #define PG8_STAGE(bufoff, gbase, voff) do { _Pragma("unroll") for (int _i = 0; _i < 2; ++_i) \
;         __builtin_amdgcn_global_load_lds((const unsigned*)((const char*)(gbase) + (voff)[_i]), (LAS unsigned*)(lds + (bufoff) + ldsw + _i * 8192), 16, 0, 0); } while (0)
; #define PG8_LDA(dst, b, h) do { _Pragma("unroll") for (int m = 0; m < 4; ++m) _Pragma("unroll") for (int k = 0; k < 2; ++k) dst[m][k] = *(const LAS bf16x8*)(lds + PG8_SA(b, h) + aoff + m * 2048 + k * 1024); } while (0)
; #define PG8_LDB(dst, b, h) do { _Pragma("unroll") for (int n = 0; n < 2; ++n) _Pragma("unroll") for (int k = 0; k < 2; ++k) dst[n][k] = *(const LAS bf16x8*)(lds + PG8_SB(b, h) + boff + n * 2048 + k * 1024); } while (0)
; #define PG8_MMA(ai, bj, At, Bt) do { __builtin_amdgcn_s_setprio(1); _Pragma("unroll") for (int m = 0; m < 4; ++m) _Pragma("unroll") for (int n = 0; n < 2; ++n) _Pragma("unroll") for (int k = 0; k < 2; ++k) \
;         acc[ai][bj][m][n] = __builtin_amdgcn_mfma_f32_16x16x32_bf16(Bt[n][k], At[m][k], acc[ai][bj][m][n], 0, 0, 0); __builtin_amdgcn_s_setprio(0); } while (0)
; #define PG8_WAIT_V(n) asm volatile("s_waitcnt vmcnt(" #n ")" ::: "memory")
; #define PG8_WAIT_L(n) asm volatile("s_waitcnt lgkmcnt(" #n ")" ::: "memory")
; #define PG8_BAR __builtin_amdgcn_s_barrier()
; #define PG8_SCHED __builtin_amdgcn_sched_barrier(0)
; template <class Epi, class Sched>
; __device__ __forceinline__ void gemm_phase(LAS unsigned char* lds, const Gemm g, const Sched& S, const Epi& E) {
;     ...
;         for (int t = 0; t < nt; t += 2) {
;             const bool last = (t == nt - 2);
;             const char* a1 = cA + (size_t)(t + 1) * kstep;
;             const char* a2 = last ? nA : cA + (size_t)(t + 2) * kstep; const char* b2 = last ? nB : cB + (size_t)(t + 2) * kstep;
;             const char* a3 = a2 + kstep; const char* b3 = b2 + kstep;
;             PG8_LDB(B0, 0, 0); PG8_LDB(B1, 0, 1); PG8_SCHED; PG8_LDA(At, 0, 0); PG8_STAGE(PG8_SA(1, 1), a1 + hstepA, voffA);
;             PG8_WAIT_V(8); PG8_WAIT_L(0); PG8_BAR; PG8_MMA(0, 0, At, B0); PG8_MMA(0, 1, At, B1); PG8_BAR; PG8_SCHED;
;             PG8_LDA(At, 0, 1); PG8_STAGE(PG8_SB(0, 0), b2, voffB); PG8_STAGE(PG8_SB(0, 1), b2 + hstepB, voffB); PG8_STAGE(PG8_SA(0, 0), a2, voffA);
;             PG8_WAIT_V(8); PG8_WAIT_L(0); PG8_BAR; PG8_MMA(1, 0, At, B0); PG8_MMA(1, 1, At, B1); PG8_BAR; PG8_SCHED;
.LBB0_1025:
	s_add_u32 s18, s14, 0xfffc0080
	s_addc_u32 s19, s15, -1
	s_add_i32 s51, 0, 0x10000
	s_cmp_eq_u32 s50, 12
	s_cselect_b32 s21, s9, s19
	s_cselect_b32 s20, s17, s18
	s_cselect_b32 s19, s3, s49
	s_cselect_b32 s18, s23, s48
	s_add_i32 s54, 0, 0x14000
	v_add_u32_e32 v92, s51, v231
	v_add_u32_e32 v110, s54, v231
	ds_read_b128 v[80:83], v92
	ds_read_b128 v[84:87], v92 offset:1024
	ds_read_b128 v[88:91], v92 offset:2048
	ds_read_b128 v[92:95], v92 offset:3072
	ds_read_b128 v[98:101], v110
	ds_read_b128 v[102:105], v110 offset:1024
	ds_read_b128 v[106:109], v110 offset:2048
	ds_read_b128 v[110:113], v110 offset:3072
	v_lshl_add_u64 v[126:127], s[14:15], 0, v[180:181]
	s_add_i32 m0, s25, 0xc000
	ds_read_b128 v[164:167], v232
	ds_read_b128 v[168:171], v232 offset:1024
	ds_read_b128 v[182:185], v232 offset:2048
	ds_read_b128 v[186:189], v232 offset:3072
	ds_read_b128 v[190:193], v232 offset:4096
	ds_read_b128 v[206:209], v232 offset:5120
	ds_read_b128 v[210:213], v232 offset:6144
	ds_read_b128 v[214:217], v232 offset:7168
	global_load_lds_dwordx4 v[126:127], off
	v_lshl_add_u64 v[126:127], s[14:15], 0, v[178:179]
	s_add_i32 m0, s25, 0xe000
	s_nop 0
	global_load_lds_dwordx4 v[126:127], off
	s_waitcnt vmcnt(8)
	s_waitcnt lgkmcnt(0)
	s_barrier
	s_waitcnt lgkmcnt(0)
	v_mfma_f32_16x16x32_bf16 v[160:163], v[80:83], v[164:167], v[160:163]
	v_mfma_f32_16x16x32_bf16 v[60:63], v[88:91], v[164:167], v[60:63]
	v_mfma_f32_16x16x32_bf16 v[144:147], v[80:83], v[182:185], v[144:147]
	v_mfma_f32_16x16x32_bf16 v[52:55], v[88:91], v[182:185], v[52:55]
	v_mfma_f32_16x16x32_bf16 v[140:143], v[80:83], v[190:193], v[140:143]
	v_mfma_f32_16x16x32_bf16 v[36:39], v[88:91], v[190:193], v[36:39]
	v_mfma_f32_16x16x32_bf16 v[152:155], v[80:83], v[210:213], v[152:155]
	v_mfma_f32_16x16x32_bf16 v[48:51], v[88:91], v[210:213], v[48:51]
	v_mfma_f32_16x16x32_bf16 v[160:163], v[84:87], v[168:171], v[160:163]
	v_mfma_f32_16x16x32_bf16 v[60:63], v[92:95], v[168:171], v[60:63]
	v_mfma_f32_16x16x32_bf16 v[144:147], v[84:87], v[186:189], v[144:147]
	v_mfma_f32_16x16x32_bf16 v[52:55], v[92:95], v[186:189], v[52:55]
	v_mfma_f32_16x16x32_bf16 v[140:143], v[84:87], v[206:209], v[140:143]
	v_mfma_f32_16x16x32_bf16 v[36:39], v[92:95], v[206:209], v[36:39]
	v_mfma_f32_16x16x32_bf16 v[152:155], v[84:87], v[214:217], v[152:155]
	v_mfma_f32_16x16x32_bf16 v[48:51], v[92:95], v[214:217], v[48:51]
	v_mfma_f32_16x16x32_bf16 v[156:159], v[98:101], v[164:167], v[156:159]
	v_mfma_f32_16x16x32_bf16 v[56:59], v[106:109], v[164:167], v[56:59]
	v_mfma_f32_16x16x32_bf16 v[118:121], v[98:101], v[182:185], v[118:121]
	v_mfma_f32_16x16x32_bf16 v[40:43], v[106:109], v[182:185], v[40:43]
	v_mfma_f32_16x16x32_bf16 v[114:117], v[98:101], v[190:193], v[114:117]
	v_mfma_f32_16x16x32_bf16 v[32:35], v[106:109], v[190:193], v[32:35]
	v_mfma_f32_16x16x32_bf16 v[148:151], v[98:101], v[210:213], v[148:151]
	v_mfma_f32_16x16x32_bf16 v[44:47], v[106:109], v[210:213], v[44:47]
	v_mfma_f32_16x16x32_bf16 v[156:159], v[102:105], v[168:171], v[156:159]
	v_mfma_f32_16x16x32_bf16 v[56:59], v[110:113], v[168:171], v[56:59]
	v_mfma_f32_16x16x32_bf16 v[118:121], v[102:105], v[186:189], v[118:121]
	v_mfma_f32_16x16x32_bf16 v[40:43], v[110:113], v[186:189], v[40:43]
	v_mfma_f32_16x16x32_bf16 v[114:117], v[102:105], v[206:209], v[114:117]
	v_mfma_f32_16x16x32_bf16 v[32:35], v[110:113], v[206:209], v[32:35]
	v_mfma_f32_16x16x32_bf16 v[148:151], v[102:105], v[214:217], v[148:151]
	v_mfma_f32_16x16x32_bf16 v[44:47], v[110:113], v[214:217], v[44:47]
	s_barrier
	s_add_i32 s51, s51, s29
	v_lshl_add_u64 v[238:239], s[18:19], 0, v[96:97]
	s_mov_b32 m0, s51
	ds_read_b128 v[164:167], v232 offset:16384
	ds_read_b128 v[168:171], v232 offset:17408
	ds_read_b128 v[182:185], v232 offset:18432
	ds_read_b128 v[186:189], v232 offset:19456
	ds_read_b128 v[190:193], v232 offset:20480
	ds_read_b128 v[206:209], v232 offset:21504
	ds_read_b128 v[210:213], v232 offset:22528
	ds_read_b128 v[214:217], v232 offset:23552
	global_load_lds_dwordx4 v[238:239], off
	s_add_i32 m0, s51, 0x2000
	s_add_u32 s52, s18, 0x40000
	v_lshl_add_u64 v[240:241], s[18:19], 0, v[172:173]
	s_addc_u32 s53, s19, 0
	s_add_i32 s51, s54, s29
	global_load_lds_dwordx4 v[240:241], off
	v_lshl_add_u64 v[126:127], s[52:53], 0, v[96:97]
	s_mov_b32 m0, s51
	v_lshl_add_u64 v[242:243], s[20:21], 0, v[176:177]
	global_load_lds_dwordx4 v[126:127], off
	v_lshl_add_u64 v[126:127], s[52:53], 0, v[172:173]
	s_add_i32 m0, s51, 0x2000
	v_lshl_add_u64 v[244:245], s[20:21], 0, v[174:175]
	global_load_lds_dwordx4 v[126:127], off
	s_mov_b32 m0, s25
	s_nop 0
	global_load_lds_dwordx4 v[242:243], off
	s_mov_b32 m0, s27
	s_nop 0
	global_load_lds_dwordx4 v[244:245], off
	s_waitcnt vmcnt(8)
	s_waitcnt lgkmcnt(0)
	s_barrier
; #define PG8_STAGE(bufoff, gbase, voff) do { _Pragma("unroll") for (int _i = 0; _i < 2; ++_i) \
;         __builtin_amdgcn_global_load_lds((const unsigned*)((const char*)(gbase) + (voff)[_i]), (LAS unsigned*)(lds + (bufoff) + ldsw + _i * 8192), 16, 0, 0); } while (0)
; #define PG8_LDA(dst, b, h) do { _Pragma("unroll") for (int m = 0; m < 4; ++m) _Pragma("unroll") for (int k = 0; k < 2; ++k) dst[m][k] = *(const LAS bf16x8*)(lds + PG8_SA(b, h) + aoff + m * 2048 + k * 1024); } while (0)
; #define PG8_LDB(dst, b, h) do { _Pragma("unroll") for (int n = 0; n < 2; ++n) _Pragma("unroll") for (int k = 0; k < 2; ++k) dst[n][k] = *(const LAS bf16x8*)(lds + PG8_SB(b, h) + boff + n * 2048 + k * 1024); } while (0)
; #define PG8_MMA(ai, bj, At, Bt) do { __builtin_amdgcn_s_setprio(1); _Pragma("unroll") for (int m = 0; m < 4; ++m) _Pragma("unroll") for (int n = 0; n < 2; ++n) _Pragma("unroll") for (int k = 0; k < 2; ++k) \
;         acc[ai][bj][m][n] = __builtin_amdgcn_mfma_f32_16x16x32_bf16(Bt[n][k], At[m][k], acc[ai][bj][m][n], 0, 0, 0); __builtin_amdgcn_s_setprio(0); } while (0)
; #define PG8_WAIT_V(n) asm volatile("s_waitcnt vmcnt(" #n ")" ::: "memory")
; #define PG8_WAIT_L(n) asm volatile("s_waitcnt lgkmcnt(" #n ")" ::: "memory")
; #define PG8_BAR __builtin_amdgcn_s_barrier()
; #define PG8_SCHED __builtin_amdgcn_sched_barrier(0)
; template <class Epi, class Sched>
; __device__ __forceinline__ void gemm_phase(LAS unsigned char* lds, const Gemm g, const Sched& S, const Epi& E) {
;     ...
;             PG8_LDA(At, 0, 1); PG8_STAGE(PG8_SB(0, 0), b2, voffB); PG8_STAGE(PG8_SB(0, 1), b2 + hstepB, voffB); PG8_STAGE(PG8_SA(0, 0), a2, voffA);
;             PG8_WAIT_V(8); PG8_WAIT_L(0); PG8_BAR; PG8_MMA(1, 0, At, B0); PG8_MMA(1, 1, At, B1); PG8_BAR; PG8_SCHED;
;             PG8_LDB(B0, 1, 0); PG8_LDB(B1, 1, 1); PG8_SCHED; PG8_LDA(At, 1, 0); PG8_STAGE(PG8_SA(0, 1), a2 + hstepA, voffA);
;             PG8_WAIT_V(8); PG8_WAIT_L(0); PG8_BAR; PG8_MMA(0, 0, At, B0); PG8_MMA(0, 1, At, B1); PG8_BAR; PG8_SCHED;
;             PG8_LDA(At, 1, 1); PG8_STAGE(PG8_SB(1, 0), b3, voffB); PG8_STAGE(PG8_SB(1, 1), b3 + hstepB, voffB); PG8_STAGE(PG8_SA(1, 0), a3, voffA);
	s_waitcnt lgkmcnt(0)
	v_mfma_f32_16x16x32_bf16 v[136:139], v[80:83], v[164:167], v[136:139]
	v_mfma_f32_16x16x32_bf16 v[28:31], v[88:91], v[164:167], v[28:31]
	v_mfma_f32_16x16x32_bf16 v[76:79], v[80:83], v[182:185], v[76:79]
	v_mfma_f32_16x16x32_bf16 v[12:15], v[88:91], v[182:185], v[12:15]
	v_mfma_f32_16x16x32_bf16 v[68:71], v[80:83], v[190:193], v[68:71]
	v_mfma_f32_16x16x32_bf16 v[4:7], v[88:91], v[190:193], v[4:7]
	v_mfma_f32_16x16x32_bf16 v[16:19], v[88:91], v[210:213], v[16:19]
	v_mfma_f32_16x16x32_bf16 v[136:139], v[84:87], v[168:171], v[136:139]
	v_mfma_f32_16x16x32_bf16 v[28:31], v[92:95], v[168:171], v[28:31]
	v_mfma_f32_16x16x32_bf16 v[76:79], v[84:87], v[186:189], v[76:79]
	v_mfma_f32_16x16x32_bf16 v[12:15], v[92:95], v[186:189], v[12:15]
	v_mfma_f32_16x16x32_bf16 v[68:71], v[84:87], v[206:209], v[68:71]
	v_mfma_f32_16x16x32_bf16 v[4:7], v[92:95], v[206:209], v[4:7]
	v_mfma_f32_16x16x32_bf16 v[80:83], v[80:83], v[210:213], v[122:125]
	v_mfma_f32_16x16x32_bf16 v[16:19], v[92:95], v[214:217], v[16:19]
	v_mfma_f32_16x16x32_bf16 v[80:83], v[84:87], v[214:217], v[80:83]
	v_mfma_f32_16x16x32_bf16 v[24:27], v[106:109], v[164:167], v[24:27]
	v_mfma_f32_16x16x32_bf16 v[72:75], v[98:101], v[182:185], v[72:75]
	v_mfma_f32_16x16x32_bf16 v[8:11], v[106:109], v[182:185], v[8:11]
	v_mfma_f32_16x16x32_bf16 v[64:67], v[98:101], v[190:193], v[64:67]
	v_mfma_f32_16x16x32_bf16 v[0:3], v[106:109], v[190:193], v[0:3]
	v_mfma_f32_16x16x32_bf16 v[20:23], v[106:109], v[210:213], v[20:23]
	v_mfma_f32_16x16x32_bf16 v[84:87], v[98:101], v[164:167], v[132:135]
	v_mfma_f32_16x16x32_bf16 v[24:27], v[110:113], v[168:171], v[24:27]
	v_mfma_f32_16x16x32_bf16 v[72:75], v[102:105], v[186:189], v[72:75]
	v_mfma_f32_16x16x32_bf16 v[8:11], v[110:113], v[186:189], v[8:11]
	v_mfma_f32_16x16x32_bf16 v[64:67], v[102:105], v[206:209], v[64:67]
	v_mfma_f32_16x16x32_bf16 v[0:3], v[110:113], v[206:209], v[0:3]
	v_mfma_f32_16x16x32_bf16 v[88:91], v[98:101], v[210:213], v[128:131]
	v_mfma_f32_16x16x32_bf16 v[20:23], v[110:113], v[214:217], v[20:23]
	v_mfma_f32_16x16x32_bf16 v[84:87], v[102:105], v[168:171], v[84:87]
	v_mfma_f32_16x16x32_bf16 v[88:91], v[102:105], v[214:217], v[88:91]
	s_barrier
	s_add_i32 s51, 0, 0x18000
	s_add_i32 s52, 0, 0x1c000
	v_add_u32_e32 v106, s51, v231
	v_add_u32_e32 v122, s52, v231
	ds_read_b128 v[92:95], v106
	ds_read_b128 v[98:101], v106 offset:1024
	ds_read_b128 v[102:105], v106 offset:2048
	ds_read_b128 v[106:109], v106 offset:3072
	ds_read_b128 v[110:113], v122
	ds_read_b128 v[126:129], v122 offset:1024
	ds_read_b128 v[164:167], v122 offset:2048
	ds_read_b128 v[168:171], v122 offset:3072
	s_add_u32 s20, s20, 0x40000
	s_addc_u32 s21, s21, 0
	s_mov_b32 m0, s37
	v_lshl_add_u64 v[134:135], s[20:21], 0, v[176:177]
	ds_read_b128 v[122:125], v232 offset:32768
	ds_read_b128 v[130:133], v232 offset:33792
	ds_read_b128 v[182:185], v232 offset:34816
	ds_read_b128 v[186:189], v232 offset:35840
	ds_read_b128 v[190:193], v232 offset:36864
	ds_read_b128 v[206:209], v232 offset:37888
	ds_read_b128 v[210:213], v232 offset:38912
	ds_read_b128 v[214:217], v232 offset:39936
	global_load_lds_dwordx4 v[134:135], off
	v_lshl_add_u64 v[134:135], s[20:21], 0, v[174:175]
	s_mov_b32 m0, s33
	s_nop 0
	global_load_lds_dwordx4 v[134:135], off
	s_waitcnt vmcnt(8)
	s_waitcnt lgkmcnt(0)
	s_barrier
	s_waitcnt lgkmcnt(0)
	v_mfma_f32_16x16x32_bf16 v[160:163], v[92:95], v[122:125], v[160:163]
	v_mfma_f32_16x16x32_bf16 v[60:63], v[102:105], v[122:125], v[60:63]
	v_mfma_f32_16x16x32_bf16 v[144:147], v[92:95], v[182:185], v[144:147]
	v_mfma_f32_16x16x32_bf16 v[52:55], v[102:105], v[182:185], v[52:55]
	v_mfma_f32_16x16x32_bf16 v[140:143], v[92:95], v[190:193], v[140:143]
	v_mfma_f32_16x16x32_bf16 v[36:39], v[102:105], v[190:193], v[36:39]
	v_mfma_f32_16x16x32_bf16 v[152:155], v[92:95], v[210:213], v[152:155]
	v_mfma_f32_16x16x32_bf16 v[48:51], v[102:105], v[210:213], v[48:51]
	v_mfma_f32_16x16x32_bf16 v[160:163], v[98:101], v[130:133], v[160:163]
	v_mfma_f32_16x16x32_bf16 v[60:63], v[106:109], v[130:133], v[60:63]
	v_mfma_f32_16x16x32_bf16 v[144:147], v[98:101], v[186:189], v[144:147]
	v_mfma_f32_16x16x32_bf16 v[52:55], v[106:109], v[186:189], v[52:55]
	v_mfma_f32_16x16x32_bf16 v[140:143], v[98:101], v[206:209], v[140:143]
	v_mfma_f32_16x16x32_bf16 v[36:39], v[106:109], v[206:209], v[36:39]
	v_mfma_f32_16x16x32_bf16 v[152:155], v[98:101], v[214:217], v[152:155]
	v_mfma_f32_16x16x32_bf16 v[48:51], v[106:109], v[214:217], v[48:51]
	v_mfma_f32_16x16x32_bf16 v[156:159], v[110:113], v[122:125], v[156:159]
	v_mfma_f32_16x16x32_bf16 v[56:59], v[164:167], v[122:125], v[56:59]
	v_mfma_f32_16x16x32_bf16 v[118:121], v[110:113], v[182:185], v[118:121]
	v_mfma_f32_16x16x32_bf16 v[40:43], v[164:167], v[182:185], v[40:43]
	v_mfma_f32_16x16x32_bf16 v[114:117], v[110:113], v[190:193], v[114:117]
	v_mfma_f32_16x16x32_bf16 v[32:35], v[164:167], v[190:193], v[32:35]
	v_mfma_f32_16x16x32_bf16 v[122:125], v[110:113], v[210:213], v[148:151]
	v_mfma_f32_16x16x32_bf16 v[44:47], v[164:167], v[210:213], v[44:47]
	v_mfma_f32_16x16x32_bf16 v[156:159], v[126:129], v[130:133], v[156:159]
	v_mfma_f32_16x16x32_bf16 v[56:59], v[168:171], v[130:133], v[56:59]
	v_mfma_f32_16x16x32_bf16 v[118:121], v[126:129], v[186:189], v[118:121]
	v_mfma_f32_16x16x32_bf16 v[40:43], v[168:171], v[186:189], v[40:43]
	v_mfma_f32_16x16x32_bf16 v[114:117], v[126:129], v[206:209], v[114:117]
	v_mfma_f32_16x16x32_bf16 v[32:35], v[168:171], v[206:209], v[32:35]
	v_mfma_f32_16x16x32_bf16 v[148:151], v[126:129], v[214:217], v[122:125]
	v_mfma_f32_16x16x32_bf16 v[44:47], v[168:171], v[214:217], v[44:47]
	s_barrier
; #define PG8_STAGE(bufoff, gbase, voff) do { _Pragma("unroll") for (int _i = 0; _i < 2; ++_i) \
;         __builtin_amdgcn_global_load_lds((const unsigned*)((const char*)(gbase) + (voff)[_i]), (LAS unsigned*)(lds + (bufoff) + ldsw + _i * 8192), 16, 0, 0); } while (0)
; #define PG8_LDA(dst, b, h) do { _Pragma("unroll") for (int m = 0; m < 4; ++m) _Pragma("unroll") for (int k = 0; k < 2; ++k) dst[m][k] = *(const LAS bf16x8*)(lds + PG8_SA(b, h) + aoff + m * 2048 + k * 1024); } while (0)
; #define PG8_MMA(ai, bj, At, Bt) do { __builtin_amdgcn_s_setprio(1); _Pragma("unroll") for (int m = 0; m < 4; ++m) _Pragma("unroll") for (int n = 0; n < 2; ++n) _Pragma("unroll") for (int k = 0; k < 2; ++k) \
;         acc[ai][bj][m][n] = __builtin_amdgcn_mfma_f32_16x16x32_bf16(Bt[n][k], At[m][k], acc[ai][bj][m][n], 0, 0, 0); __builtin_amdgcn_s_setprio(0); } while (0)
; #define PG8_WAIT_V(n) asm volatile("s_waitcnt vmcnt(" #n ")" ::: "memory")
; #define PG8_WAIT_L(n) asm volatile("s_waitcnt lgkmcnt(" #n ")" ::: "memory")
; #define PG8_BAR __builtin_amdgcn_s_barrier()
; #define PG8_SCHED __builtin_amdgcn_sched_barrier(0)
; template <class Epi, class Sched>
; __device__ __forceinline__ void gemm_phase(LAS unsigned char* lds, const Gemm g, const Sched& S, const Epi& E) {
;     ...
;             PG8_LDA(At, 1, 1); PG8_STAGE(PG8_SB(1, 0), b3, voffB); PG8_STAGE(PG8_SB(1, 1), b3 + hstepB, voffB); PG8_STAGE(PG8_SA(1, 0), a3, voffA);
;             PG8_WAIT_V(8); PG8_WAIT_L(0); PG8_BAR; PG8_MMA(1, 0, At, B0); PG8_MMA(1, 1, At, B1); PG8_BAR; PG8_SCHED;
;         }
;         if (wr == 0) PG8_BAR;
	s_add_i32 s20, s51, s29
	v_lshl_add_u64 v[122:123], v[238:239], 0, s[4:5]
	s_mov_b32 m0, s20
	ds_read_b128 v[182:185], v232 offset:49152
	ds_read_b128 v[186:189], v232 offset:50176
	ds_read_b128 v[190:193], v232 offset:51200
	ds_read_b128 v[206:209], v232 offset:52224
	ds_read_b128 v[210:213], v232 offset:53248
	ds_read_b128 v[214:217], v232 offset:54272
	ds_read_b128 v[218:221], v232 offset:55296
	ds_read_b128 v[234:237], v232 offset:56320
	global_load_lds_dwordx4 v[122:123], off
	s_add_i32 m0, s20, 0x2000
	s_add_u32 s18, s18, 0x40080
	v_lshl_add_u64 v[122:123], v[240:241], 0, s[4:5]
	s_addc_u32 s19, s19, 0
	s_add_i32 s20, s52, s29
	global_load_lds_dwordx4 v[122:123], off
	v_lshl_add_u64 v[122:123], s[18:19], 0, v[96:97]
	s_mov_b32 m0, s20
	s_nop 0
	global_load_lds_dwordx4 v[122:123], off
	v_lshl_add_u64 v[122:123], s[18:19], 0, v[172:173]
	s_add_i32 m0, s20, 0x2000
	s_nop 0
	global_load_lds_dwordx4 v[122:123], off
	v_lshl_add_u64 v[122:123], v[242:243], 0, s[4:5]
	s_mov_b32 m0, s96
	s_nop 0
	global_load_lds_dwordx4 v[122:123], off
	v_lshl_add_u64 v[122:123], v[244:245], 0, s[4:5]
	s_mov_b32 m0, s7
	s_nop 0
	global_load_lds_dwordx4 v[122:123], off
	s_waitcnt vmcnt(8)
	s_waitcnt lgkmcnt(0)
	s_barrier
	s_waitcnt lgkmcnt(0)
	v_mfma_f32_16x16x32_bf16 v[122:125], v[92:95], v[182:185], v[136:139]
	v_mfma_f32_16x16x32_bf16 v[28:31], v[102:105], v[182:185], v[28:31]
	v_mfma_f32_16x16x32_bf16 v[76:79], v[92:95], v[190:193], v[76:79]
	v_mfma_f32_16x16x32_bf16 v[12:15], v[102:105], v[190:193], v[12:15]
	v_mfma_f32_16x16x32_bf16 v[68:71], v[92:95], v[210:213], v[68:71]
	v_mfma_f32_16x16x32_bf16 v[4:7], v[102:105], v[210:213], v[4:7]
	v_mfma_f32_16x16x32_bf16 v[80:83], v[92:95], v[218:221], v[80:83]
	v_mfma_f32_16x16x32_bf16 v[16:19], v[102:105], v[218:221], v[16:19]
	v_mfma_f32_16x16x32_bf16 v[136:139], v[98:101], v[186:189], v[122:125]
	v_mfma_f32_16x16x32_bf16 v[28:31], v[106:109], v[186:189], v[28:31]
	v_mfma_f32_16x16x32_bf16 v[76:79], v[98:101], v[206:209], v[76:79]
	v_mfma_f32_16x16x32_bf16 v[12:15], v[106:109], v[206:209], v[12:15]
	v_mfma_f32_16x16x32_bf16 v[68:71], v[98:101], v[214:217], v[68:71]
	v_mfma_f32_16x16x32_bf16 v[4:7], v[106:109], v[214:217], v[4:7]
	v_mfma_f32_16x16x32_bf16 v[122:125], v[98:101], v[234:237], v[80:83]
	v_mfma_f32_16x16x32_bf16 v[16:19], v[106:109], v[234:237], v[16:19]
	v_mfma_f32_16x16x32_bf16 v[80:83], v[110:113], v[182:185], v[84:87]
	v_mfma_f32_16x16x32_bf16 v[132:135], v[126:129], v[186:189], v[80:83]
	v_mfma_f32_16x16x32_bf16 v[24:27], v[164:167], v[182:185], v[24:27]
	v_mfma_f32_16x16x32_bf16 v[72:75], v[110:113], v[190:193], v[72:75]
	v_mfma_f32_16x16x32_bf16 v[8:11], v[164:167], v[190:193], v[8:11]
	v_mfma_f32_16x16x32_bf16 v[64:67], v[110:113], v[210:213], v[64:67]
	v_mfma_f32_16x16x32_bf16 v[0:3], v[164:167], v[210:213], v[0:3]
	v_mfma_f32_16x16x32_bf16 v[80:83], v[110:113], v[218:221], v[88:91]
	v_mfma_f32_16x16x32_bf16 v[20:23], v[164:167], v[218:221], v[20:23]
	v_mfma_f32_16x16x32_bf16 v[24:27], v[168:171], v[186:189], v[24:27]
	v_mfma_f32_16x16x32_bf16 v[72:75], v[126:129], v[206:209], v[72:75]
	v_mfma_f32_16x16x32_bf16 v[8:11], v[168:171], v[206:209], v[8:11]
	v_mfma_f32_16x16x32_bf16 v[64:67], v[126:129], v[214:217], v[64:67]
	v_mfma_f32_16x16x32_bf16 v[0:3], v[168:171], v[214:217], v[0:3]
	v_mfma_f32_16x16x32_bf16 v[128:131], v[126:129], v[234:237], v[80:83]
	v_mfma_f32_16x16x32_bf16 v[20:23], v[168:171], v[234:237], v[20:23]
	s_barrier
	s_add_i32 s50, s50, 2
	s_add_u32 s48, s48, 0x100
	s_addc_u32 s49, s49, 0
	s_add_u32 s14, s14, 0x100
	s_addc_u32 s15, s15, 0
	s_cmp_gt_u32 s50, 13
	s_cbranch_scc0 .LBB0_1025
	v_readlane_b32 s14, v246, 31
	v_readlane_b32 s15, v246, 32
	s_and_b64 vcc, exec, s[14:15]
	s_cbranch_vccz .LBB0_1028
	s_barrier

; #define PG8_STAGE(bufoff, gbase, voff) do { _Pragma("unroll") for (int _i = 0; _i < 2; ++_i) \
;         __builtin_amdgcn_global_load_lds((const unsigned*)((const char*)(gbase) + (voff)[_i]), (LAS unsigned*)(lds + (bufoff) + ldsw + _i * 8192), 16, 0, 0); } while (0)
; #define PG8_LDA(dst, b, h) do { _Pragma("unroll") for (int m = 0; m < 4; ++m) _Pragma("unroll") for (int k = 0; k < 2; ++k) dst[m][k] = *(const LAS bf16x8*)(lds + PG8_SA(b, h) + aoff + m * 2048 + k * 1024); } while (0)
; #define PG8_LDB(dst, b, h) do { _Pragma("unroll") for (int n = 0; n < 2; ++n) _Pragma("unroll") for (int k = 0; k < 2; ++k) dst[n][k] = *(const LAS bf16x8*)(lds + PG8_SB(b, h) + boff + n * 2048 + k * 1024); } while (0)
; #define PG8_MMA(ai, bj, At, Bt) do { __builtin_amdgcn_s_setprio(1); _Pragma("unroll") for (int m = 0; m < 4; ++m) _Pragma("unroll") for (int n = 0; n < 2; ++n) _Pragma("unroll") for (int k = 0; k < 2; ++k) \
;         acc[ai][bj][m][n] = __builtin_amdgcn_mfma_f32_16x16x32_bf16(Bt[n][k], At[m][k], acc[ai][bj][m][n], 0, 0, 0); __builtin_amdgcn_s_setprio(0); } while (0)
; #define PG8_WAIT_V(n) asm volatile("s_waitcnt vmcnt(" #n ")" ::: "memory")
; #define PG8_WAIT_L(n) asm volatile("s_waitcnt lgkmcnt(" #n ")" ::: "memory")
; #define PG8_BAR __builtin_amdgcn_s_barrier()
; #define PG8_SCHED __builtin_amdgcn_sched_barrier(0)
; template <class Epi, class Sched>
; __device__ __forceinline__ void gemm_phase(LAS unsigned char* lds, const Gemm g, const Sched& S, const Epi& E) {
;     ...
;         for (int t = 0; t < nt; t += 2) {
;             const bool last = (t == nt - 2);
;             const char* a1 = cA + (size_t)(t + 1) * kstep;
;             const char* a2 = last ? nA : cA + (size_t)(t + 2) * kstep; const char* b2 = last ? nB : cB + (size_t)(t + 2) * kstep;
;             const char* a3 = a2 + kstep; const char* b3 = b2 + kstep;
;             PG8_LDB(B0, 0, 0); PG8_LDB(B1, 0, 1); PG8_SCHED; PG8_LDA(At, 0, 0); PG8_STAGE(PG8_SA(1, 1), a1 + hstepA, voffA);
;             PG8_WAIT_V(8); PG8_WAIT_L(0); PG8_BAR; PG8_MMA(0, 0, At, B0); PG8_MMA(0, 1, At, B1); PG8_BAR; PG8_SCHED;
;             PG8_LDA(At, 0, 1); PG8_STAGE(PG8_SB(0, 0), b2, voffB); PG8_STAGE(PG8_SB(0, 1), b2 + hstepB, voffB); PG8_STAGE(PG8_SA(0, 0), a2, voffA);
;             PG8_WAIT_V(8); PG8_WAIT_L(0); PG8_BAR; PG8_MMA(1, 0, At, B0); PG8_MMA(1, 1, At, B1); PG8_BAR; PG8_SCHED;
.LBB0_1242:
	s_add_u32 s14, s12, 0x100
	s_addc_u32 s15, s13, 0
	s_add_i32 s50, 0, 0x10000
	s_cmp_eq_u32 s49, 40
	s_cselect_b32 s19, s1, s15
	s_cselect_b32 s18, s0, s14
	v_add_u32_e32 v96, s50, v231
	s_cselect_b32 s17, s11, s48
	s_cselect_b32 s16, s10, s45
	s_add_i32 s51, 0, 0x14000
	ds_read_b128 v[130:133], v96
	ds_read_b128 v[134:137], v96 offset:1024
	ds_read_b128 v[138:141], v96 offset:2048
	ds_read_b128 v[142:145], v96 offset:3072
	v_add_u32_e32 v96, s51, v231
	ds_read_b128 v[146:149], v96
	ds_read_b128 v[150:153], v96 offset:1024
	ds_read_b128 v[154:157], v96 offset:2048
	ds_read_b128 v[158:161], v96 offset:3072
	v_lshl_add_u64 v[218:219], s[12:13], 0, v[216:217]
	s_add_i32 m0, s20, 0xc000
	ds_read_b128 v[162:165], v232
	ds_read_b128 v[166:169], v232 offset:1024
	ds_read_b128 v[170:173], v232 offset:2048
	ds_read_b128 v[174:177], v232 offset:3072
	ds_read_b128 v[178:181], v232 offset:4096
	ds_read_b128 v[182:185], v232 offset:5120
	ds_read_b128 v[186:189], v232 offset:6144
	ds_read_b128 v[190:193], v232 offset:7168
	global_load_lds_dwordx4 v[218:219], off
	v_lshl_add_u64 v[218:219], s[12:13], 0, v[214:215]
	s_add_i32 m0, s20, 0xe000
	s_nop 0
	global_load_lds_dwordx4 v[218:219], off
	s_waitcnt vmcnt(8)
	s_waitcnt lgkmcnt(0)
	s_barrier
	s_waitcnt lgkmcnt(0)
	v_mfma_f32_16x16x32_bf16 v[126:129], v[130:133], v[162:165], v[126:129]
	v_mfma_f32_16x16x32_bf16 v[122:125], v[138:141], v[162:165], v[122:125]
	v_mfma_f32_16x16x32_bf16 v[114:117], v[130:133], v[170:173], v[114:117]
	v_mfma_f32_16x16x32_bf16 v[106:109], v[138:141], v[170:173], v[106:109]
	v_mfma_f32_16x16x32_bf16 v[98:101], v[130:133], v[178:181], v[98:101]
	v_mfma_f32_16x16x32_bf16 v[88:91], v[138:141], v[178:181], v[88:91]
	v_mfma_f32_16x16x32_bf16 v[80:83], v[130:133], v[186:189], v[80:83]
	v_mfma_f32_16x16x32_bf16 v[72:75], v[138:141], v[186:189], v[72:75]
	v_mfma_f32_16x16x32_bf16 v[126:129], v[134:137], v[166:169], v[126:129]
	v_mfma_f32_16x16x32_bf16 v[122:125], v[142:145], v[166:169], v[122:125]
	v_mfma_f32_16x16x32_bf16 v[114:117], v[134:137], v[174:177], v[114:117]
	v_mfma_f32_16x16x32_bf16 v[106:109], v[142:145], v[174:177], v[106:109]
	v_mfma_f32_16x16x32_bf16 v[98:101], v[134:137], v[182:185], v[98:101]
	v_mfma_f32_16x16x32_bf16 v[88:91], v[142:145], v[182:185], v[88:91]
	v_mfma_f32_16x16x32_bf16 v[80:83], v[134:137], v[190:193], v[80:83]
	v_mfma_f32_16x16x32_bf16 v[72:75], v[142:145], v[190:193], v[72:75]
	v_mfma_f32_16x16x32_bf16 v[118:121], v[146:149], v[162:165], v[118:121]
	v_mfma_f32_16x16x32_bf16 v[110:113], v[154:157], v[162:165], v[110:113]
	v_mfma_f32_16x16x32_bf16 v[102:105], v[146:149], v[170:173], v[102:105]
	v_mfma_f32_16x16x32_bf16 v[92:95], v[154:157], v[170:173], v[92:95]
	v_mfma_f32_16x16x32_bf16 v[84:87], v[146:149], v[178:181], v[84:87]
	v_mfma_f32_16x16x32_bf16 v[76:79], v[154:157], v[178:181], v[76:79]
	v_mfma_f32_16x16x32_bf16 v[68:71], v[146:149], v[186:189], v[68:71]
	v_mfma_f32_16x16x32_bf16 v[64:67], v[154:157], v[186:189], v[64:67]
	v_mfma_f32_16x16x32_bf16 v[118:121], v[150:153], v[166:169], v[118:121]
	v_mfma_f32_16x16x32_bf16 v[110:113], v[158:161], v[166:169], v[110:113]
	v_mfma_f32_16x16x32_bf16 v[102:105], v[150:153], v[174:177], v[102:105]
	v_mfma_f32_16x16x32_bf16 v[92:95], v[158:161], v[174:177], v[92:95]
	v_mfma_f32_16x16x32_bf16 v[84:87], v[150:153], v[182:185], v[84:87]
	v_mfma_f32_16x16x32_bf16 v[76:79], v[158:161], v[182:185], v[76:79]
	v_mfma_f32_16x16x32_bf16 v[68:71], v[150:153], v[190:193], v[68:71]
	v_mfma_f32_16x16x32_bf16 v[64:67], v[158:161], v[190:193], v[64:67]
	s_barrier
	s_add_i32 s12, s50, s7
	v_lshl_add_u64 v[218:219], s[16:17], 0, v[210:211]
	s_mov_b32 m0, s12
	ds_read_b128 v[162:165], v232 offset:16384
	ds_read_b128 v[166:169], v232 offset:17408
	ds_read_b128 v[170:173], v232 offset:18432
	ds_read_b128 v[174:177], v232 offset:19456
	ds_read_b128 v[178:181], v232 offset:20480
	ds_read_b128 v[182:185], v232 offset:21504
	ds_read_b128 v[186:189], v232 offset:22528
	ds_read_b128 v[190:193], v232 offset:23552
	global_load_lds_dwordx4 v[218:219], off
	s_add_i32 m0, s12, 0x2000
	s_add_u32 s12, s16, 0xb0000
	v_lshl_add_u64 v[220:221], s[16:17], 0, v[206:207]
	s_addc_u32 s13, s17, 0
	s_add_i32 s50, s51, s7
	global_load_lds_dwordx4 v[220:221], off
	v_lshl_add_u64 v[234:235], s[12:13], 0, v[210:211]
	s_mov_b32 m0, s50
	v_lshl_add_u64 v[236:237], s[18:19], 0, v[208:209]
	global_load_lds_dwordx4 v[234:235], off
	v_lshl_add_u64 v[234:235], s[12:13], 0, v[206:207]
	s_add_i32 m0, s50, 0x2000
	s_nop 0
	global_load_lds_dwordx4 v[234:235], off
	v_lshl_add_u64 v[234:235], s[18:19], 0, v[212:213]
	s_mov_b32 m0, s20
	s_nop 0
	global_load_lds_dwordx4 v[234:235], off
	s_mov_b32 m0, s21
	s_nop 0
	global_load_lds_dwordx4 v[236:237], off
	s_waitcnt vmcnt(8)
	s_waitcnt lgkmcnt(0)
	s_barrier
; #define PG8_STAGE(bufoff, gbase, voff) do { _Pragma("unroll") for (int _i = 0; _i < 2; ++_i) \
;         __builtin_amdgcn_global_load_lds((const unsigned*)((const char*)(gbase) + (voff)[_i]), (LAS unsigned*)(lds + (bufoff) + ldsw + _i * 8192), 16, 0, 0); } while (0)
; #define PG8_LDA(dst, b, h) do { _Pragma("unroll") for (int m = 0; m < 4; ++m) _Pragma("unroll") for (int k = 0; k < 2; ++k) dst[m][k] = *(const LAS bf16x8*)(lds + PG8_SA(b, h) + aoff + m * 2048 + k * 1024); } while (0)
; #define PG8_LDB(dst, b, h) do { _Pragma("unroll") for (int n = 0; n < 2; ++n) _Pragma("unroll") for (int k = 0; k < 2; ++k) dst[n][k] = *(const LAS bf16x8*)(lds + PG8_SB(b, h) + boff + n * 2048 + k * 1024); } while (0)
; #define PG8_MMA(ai, bj, At, Bt) do { __builtin_amdgcn_s_setprio(1); _Pragma("unroll") for (int m = 0; m < 4; ++m) _Pragma("unroll") for (int n = 0; n < 2; ++n) _Pragma("unroll") for (int k = 0; k < 2; ++k) \
;         acc[ai][bj][m][n] = __builtin_amdgcn_mfma_f32_16x16x32_bf16(Bt[n][k], At[m][k], acc[ai][bj][m][n], 0, 0, 0); __builtin_amdgcn_s_setprio(0); } while (0)
; #define PG8_WAIT_V(n) asm volatile("s_waitcnt vmcnt(" #n ")" ::: "memory")
; #define PG8_WAIT_L(n) asm volatile("s_waitcnt lgkmcnt(" #n ")" ::: "memory")
; #define PG8_BAR __builtin_amdgcn_s_barrier()
; #define PG8_SCHED __builtin_amdgcn_sched_barrier(0)
; template <class Epi, class Sched>
; __device__ __forceinline__ void gemm_phase(LAS unsigned char* lds, const Gemm g, const Sched& S, const Epi& E) {
;     ...
;             PG8_LDA(At, 0, 1); PG8_STAGE(PG8_SB(0, 0), b2, voffB); PG8_STAGE(PG8_SB(0, 1), b2 + hstepB, voffB); PG8_STAGE(PG8_SA(0, 0), a2, voffA);
;             PG8_WAIT_V(8); PG8_WAIT_L(0); PG8_BAR; PG8_MMA(1, 0, At, B0); PG8_MMA(1, 1, At, B1); PG8_BAR; PG8_SCHED;
;             PG8_LDB(B0, 1, 0); PG8_LDB(B1, 1, 1); PG8_SCHED; PG8_LDA(At, 1, 0); PG8_STAGE(PG8_SA(0, 1), a2 + hstepA, voffA);
;             PG8_WAIT_V(8); PG8_WAIT_L(0); PG8_BAR; PG8_MMA(0, 0, At, B0); PG8_MMA(0, 1, At, B1); PG8_BAR; PG8_SCHED;
;             PG8_LDA(At, 1, 1); PG8_STAGE(PG8_SB(1, 0), b3, voffB); PG8_STAGE(PG8_SB(1, 1), b3 + hstepB, voffB); PG8_STAGE(PG8_SA(1, 0), a3, voffA);
	s_waitcnt lgkmcnt(0)
	v_mfma_f32_16x16x32_bf16 v[60:63], v[130:133], v[162:165], v[60:63]
	v_mfma_f32_16x16x32_bf16 v[56:59], v[138:141], v[162:165], v[56:59]
	v_mfma_f32_16x16x32_bf16 v[48:51], v[130:133], v[170:173], v[48:51]
	v_mfma_f32_16x16x32_bf16 v[40:43], v[138:141], v[170:173], v[40:43]
	v_mfma_f32_16x16x32_bf16 v[32:35], v[130:133], v[178:181], v[32:35]
	v_mfma_f32_16x16x32_bf16 v[24:27], v[138:141], v[178:181], v[24:27]
	v_mfma_f32_16x16x32_bf16 v[16:19], v[130:133], v[186:189], v[16:19]
	v_mfma_f32_16x16x32_bf16 v[8:11], v[138:141], v[186:189], v[8:11]
	v_mfma_f32_16x16x32_bf16 v[60:63], v[134:137], v[166:169], v[60:63]
	v_mfma_f32_16x16x32_bf16 v[56:59], v[142:145], v[166:169], v[56:59]
	v_mfma_f32_16x16x32_bf16 v[48:51], v[134:137], v[174:177], v[48:51]
	v_mfma_f32_16x16x32_bf16 v[40:43], v[142:145], v[174:177], v[40:43]
	v_mfma_f32_16x16x32_bf16 v[32:35], v[134:137], v[182:185], v[32:35]
	v_mfma_f32_16x16x32_bf16 v[24:27], v[142:145], v[182:185], v[24:27]
	v_mfma_f32_16x16x32_bf16 v[16:19], v[134:137], v[190:193], v[16:19]
	v_mfma_f32_16x16x32_bf16 v[8:11], v[142:145], v[190:193], v[8:11]
	v_mfma_f32_16x16x32_bf16 v[52:55], v[146:149], v[162:165], v[52:55]
	v_mfma_f32_16x16x32_bf16 v[44:47], v[154:157], v[162:165], v[44:47]
	v_mfma_f32_16x16x32_bf16 v[36:39], v[146:149], v[170:173], v[36:39]
	v_mfma_f32_16x16x32_bf16 v[28:31], v[154:157], v[170:173], v[28:31]
	v_mfma_f32_16x16x32_bf16 v[20:23], v[146:149], v[178:181], v[20:23]
	v_mfma_f32_16x16x32_bf16 v[12:15], v[154:157], v[178:181], v[12:15]
	v_mfma_f32_16x16x32_bf16 v[4:7], v[146:149], v[186:189], v[4:7]
	v_mfma_f32_16x16x32_bf16 v[0:3], v[154:157], v[186:189], v[0:3]
	v_mfma_f32_16x16x32_bf16 v[52:55], v[150:153], v[166:169], v[52:55]
	v_mfma_f32_16x16x32_bf16 v[44:47], v[158:161], v[166:169], v[44:47]
	v_mfma_f32_16x16x32_bf16 v[36:39], v[150:153], v[174:177], v[36:39]
	v_mfma_f32_16x16x32_bf16 v[28:31], v[158:161], v[174:177], v[28:31]
	v_mfma_f32_16x16x32_bf16 v[20:23], v[150:153], v[182:185], v[20:23]
	v_mfma_f32_16x16x32_bf16 v[12:15], v[158:161], v[182:185], v[12:15]
	v_mfma_f32_16x16x32_bf16 v[4:7], v[150:153], v[190:193], v[4:7]
	v_mfma_f32_16x16x32_bf16 v[0:3], v[158:161], v[190:193], v[0:3]
	s_barrier
	s_add_i32 s50, 0, 0x18000
	v_add_u32_e32 v96, s50, v231
	s_add_i32 s51, 0, 0x1c000
	ds_read_b128 v[130:133], v96
	ds_read_b128 v[134:137], v96 offset:1024
	ds_read_b128 v[138:141], v96 offset:2048
	ds_read_b128 v[142:145], v96 offset:3072
	v_add_u32_e32 v96, s51, v231
	ds_read_b128 v[146:149], v96
	ds_read_b128 v[150:153], v96 offset:1024
	ds_read_b128 v[154:157], v96 offset:2048
	ds_read_b128 v[158:161], v96 offset:3072
	s_add_u32 s12, s18, 0xb0000
	s_addc_u32 s13, s19, 0
	s_mov_b32 m0, s25
	v_lshl_add_u64 v[238:239], s[12:13], 0, v[212:213]
	ds_read_b128 v[162:165], v232 offset:32768
	ds_read_b128 v[166:169], v232 offset:33792
	ds_read_b128 v[170:173], v232 offset:34816
	ds_read_b128 v[174:177], v232 offset:35840
	ds_read_b128 v[178:181], v232 offset:36864
	ds_read_b128 v[182:185], v232 offset:37888
	ds_read_b128 v[186:189], v232 offset:38912
	ds_read_b128 v[190:193], v232 offset:39936
	global_load_lds_dwordx4 v[238:239], off
	v_lshl_add_u64 v[238:239], s[12:13], 0, v[208:209]
	s_mov_b32 m0, s27
	s_nop 0
	global_load_lds_dwordx4 v[238:239], off
	s_waitcnt vmcnt(8)
	s_waitcnt lgkmcnt(0)
	s_barrier
	s_waitcnt lgkmcnt(0)
	v_mfma_f32_16x16x32_bf16 v[126:129], v[130:133], v[162:165], v[126:129]
	v_mfma_f32_16x16x32_bf16 v[122:125], v[138:141], v[162:165], v[122:125]
	v_mfma_f32_16x16x32_bf16 v[114:117], v[130:133], v[170:173], v[114:117]
	v_mfma_f32_16x16x32_bf16 v[106:109], v[138:141], v[170:173], v[106:109]
	v_mfma_f32_16x16x32_bf16 v[98:101], v[130:133], v[178:181], v[98:101]
	v_mfma_f32_16x16x32_bf16 v[88:91], v[138:141], v[178:181], v[88:91]
	v_mfma_f32_16x16x32_bf16 v[80:83], v[130:133], v[186:189], v[80:83]
	v_mfma_f32_16x16x32_bf16 v[72:75], v[138:141], v[186:189], v[72:75]
	v_mfma_f32_16x16x32_bf16 v[126:129], v[134:137], v[166:169], v[126:129]
	v_mfma_f32_16x16x32_bf16 v[122:125], v[142:145], v[166:169], v[122:125]
	v_mfma_f32_16x16x32_bf16 v[114:117], v[134:137], v[174:177], v[114:117]
	v_mfma_f32_16x16x32_bf16 v[106:109], v[142:145], v[174:177], v[106:109]
	v_mfma_f32_16x16x32_bf16 v[98:101], v[134:137], v[182:185], v[98:101]
	v_mfma_f32_16x16x32_bf16 v[88:91], v[142:145], v[182:185], v[88:91]
	v_mfma_f32_16x16x32_bf16 v[80:83], v[134:137], v[190:193], v[80:83]
	v_mfma_f32_16x16x32_bf16 v[72:75], v[142:145], v[190:193], v[72:75]
	v_mfma_f32_16x16x32_bf16 v[118:121], v[146:149], v[162:165], v[118:121]
	v_mfma_f32_16x16x32_bf16 v[110:113], v[154:157], v[162:165], v[110:113]
	v_mfma_f32_16x16x32_bf16 v[102:105], v[146:149], v[170:173], v[102:105]
	v_mfma_f32_16x16x32_bf16 v[92:95], v[154:157], v[170:173], v[92:95]
	v_mfma_f32_16x16x32_bf16 v[84:87], v[146:149], v[178:181], v[84:87]
	v_mfma_f32_16x16x32_bf16 v[76:79], v[154:157], v[178:181], v[76:79]
	v_mfma_f32_16x16x32_bf16 v[68:71], v[146:149], v[186:189], v[68:71]
	v_mfma_f32_16x16x32_bf16 v[64:67], v[154:157], v[186:189], v[64:67]
	v_mfma_f32_16x16x32_bf16 v[118:121], v[150:153], v[166:169], v[118:121]
	v_mfma_f32_16x16x32_bf16 v[110:113], v[158:161], v[166:169], v[110:113]
	v_mfma_f32_16x16x32_bf16 v[102:105], v[150:153], v[174:177], v[102:105]
	v_mfma_f32_16x16x32_bf16 v[92:95], v[158:161], v[174:177], v[92:95]
	v_mfma_f32_16x16x32_bf16 v[84:87], v[150:153], v[182:185], v[84:87]
	v_mfma_f32_16x16x32_bf16 v[76:79], v[158:161], v[182:185], v[76:79]
	v_mfma_f32_16x16x32_bf16 v[68:71], v[150:153], v[190:193], v[68:71]
	v_mfma_f32_16x16x32_bf16 v[64:67], v[158:161], v[190:193], v[64:67]
	s_barrier
; #define PG8_STAGE(bufoff, gbase, voff) do { _Pragma("unroll") for (int _i = 0; _i < 2; ++_i) \
;         __builtin_amdgcn_global_load_lds((const unsigned*)((const char*)(gbase) + (voff)[_i]), (LAS unsigned*)(lds + (bufoff) + ldsw + _i * 8192), 16, 0, 0); } while (0)
; #define PG8_LDA(dst, b, h) do { _Pragma("unroll") for (int m = 0; m < 4; ++m) _Pragma("unroll") for (int k = 0; k < 2; ++k) dst[m][k] = *(const LAS bf16x8*)(lds + PG8_SA(b, h) + aoff + m * 2048 + k * 1024); } while (0)
; #define PG8_MMA(ai, bj, At, Bt) do { __builtin_amdgcn_s_setprio(1); _Pragma("unroll") for (int m = 0; m < 4; ++m) _Pragma("unroll") for (int n = 0; n < 2; ++n) _Pragma("unroll") for (int k = 0; k < 2; ++k) \
;         acc[ai][bj][m][n] = __builtin_amdgcn_mfma_f32_16x16x32_bf16(Bt[n][k], At[m][k], acc[ai][bj][m][n], 0, 0, 0); __builtin_amdgcn_s_setprio(0); } while (0)
; #define PG8_WAIT_V(n) asm volatile("s_waitcnt vmcnt(" #n ")" ::: "memory")
; #define PG8_WAIT_L(n) asm volatile("s_waitcnt lgkmcnt(" #n ")" ::: "memory")
; #define PG8_BAR __builtin_amdgcn_s_barrier()
; #define PG8_SCHED __builtin_amdgcn_sched_barrier(0)
; template <class Epi, class Sched>
; __device__ __forceinline__ void gemm_phase(LAS unsigned char* lds, const Gemm g, const Sched& S, const Epi& E) {
;     ...
;             PG8_LDA(At, 1, 1); PG8_STAGE(PG8_SB(1, 0), b3, voffB); PG8_STAGE(PG8_SB(1, 1), b3 + hstepB, voffB); PG8_STAGE(PG8_SA(1, 0), a3, voffA);
;             PG8_WAIT_V(8); PG8_WAIT_L(0); PG8_BAR; PG8_MMA(1, 0, At, B0); PG8_MMA(1, 1, At, B1); PG8_BAR; PG8_SCHED;
;         }
;         if (wr == 0) PG8_BAR;
	s_add_i32 s12, s50, s7
	v_lshl_add_u64 v[218:219], v[218:219], 0, s[4:5]
	s_mov_b32 m0, s12
	ds_read_b128 v[162:165], v232 offset:49152
	ds_read_b128 v[166:169], v232 offset:50176
	ds_read_b128 v[170:173], v232 offset:51200
	ds_read_b128 v[174:177], v232 offset:52224
	ds_read_b128 v[178:181], v232 offset:53248
	ds_read_b128 v[182:185], v232 offset:54272
	ds_read_b128 v[186:189], v232 offset:55296
	ds_read_b128 v[190:193], v232 offset:56320
	global_load_lds_dwordx4 v[218:219], off
	s_add_i32 m0, s12, 0x2000
	s_add_u32 s12, s16, 0xb0080
	v_lshl_add_u64 v[218:219], v[220:221], 0, s[4:5]
	s_addc_u32 s13, s17, 0
	s_add_i32 s16, s51, s7
	global_load_lds_dwordx4 v[218:219], off
	v_lshl_add_u64 v[218:219], s[12:13], 0, v[210:211]
	s_mov_b32 m0, s16
	s_nop 0
	global_load_lds_dwordx4 v[218:219], off
	v_lshl_add_u64 v[218:219], s[12:13], 0, v[206:207]
	s_add_i32 m0, s16, 0x2000
	s_nop 0
	global_load_lds_dwordx4 v[218:219], off
	v_lshl_add_u64 v[218:219], v[234:235], 0, s[4:5]
	s_mov_b32 m0, s33
	s_nop 0
	global_load_lds_dwordx4 v[218:219], off
	v_lshl_add_u64 v[218:219], v[236:237], 0, s[4:5]
	s_mov_b32 m0, s37
	s_nop 0
	global_load_lds_dwordx4 v[218:219], off
	s_waitcnt vmcnt(8)
	s_waitcnt lgkmcnt(0)
	s_barrier
	s_waitcnt lgkmcnt(0)
	v_mfma_f32_16x16x32_bf16 v[60:63], v[130:133], v[162:165], v[60:63]
	v_mfma_f32_16x16x32_bf16 v[56:59], v[138:141], v[162:165], v[56:59]
	v_mfma_f32_16x16x32_bf16 v[48:51], v[130:133], v[170:173], v[48:51]
	v_mfma_f32_16x16x32_bf16 v[40:43], v[138:141], v[170:173], v[40:43]
	v_mfma_f32_16x16x32_bf16 v[32:35], v[130:133], v[178:181], v[32:35]
	v_mfma_f32_16x16x32_bf16 v[24:27], v[138:141], v[178:181], v[24:27]
	v_mfma_f32_16x16x32_bf16 v[16:19], v[130:133], v[186:189], v[16:19]
	v_mfma_f32_16x16x32_bf16 v[8:11], v[138:141], v[186:189], v[8:11]
	v_mfma_f32_16x16x32_bf16 v[60:63], v[134:137], v[166:169], v[60:63]
	v_mfma_f32_16x16x32_bf16 v[56:59], v[142:145], v[166:169], v[56:59]
	v_mfma_f32_16x16x32_bf16 v[48:51], v[134:137], v[174:177], v[48:51]
	v_mfma_f32_16x16x32_bf16 v[40:43], v[142:145], v[174:177], v[40:43]
	v_mfma_f32_16x16x32_bf16 v[32:35], v[134:137], v[182:185], v[32:35]
	v_mfma_f32_16x16x32_bf16 v[24:27], v[142:145], v[182:185], v[24:27]
	v_mfma_f32_16x16x32_bf16 v[16:19], v[134:137], v[190:193], v[16:19]
	v_mfma_f32_16x16x32_bf16 v[8:11], v[142:145], v[190:193], v[8:11]
	v_mfma_f32_16x16x32_bf16 v[52:55], v[146:149], v[162:165], v[52:55]
	v_mfma_f32_16x16x32_bf16 v[44:47], v[154:157], v[162:165], v[44:47]
	v_mfma_f32_16x16x32_bf16 v[36:39], v[146:149], v[170:173], v[36:39]
	v_mfma_f32_16x16x32_bf16 v[28:31], v[154:157], v[170:173], v[28:31]
	v_mfma_f32_16x16x32_bf16 v[20:23], v[146:149], v[178:181], v[20:23]
	v_mfma_f32_16x16x32_bf16 v[12:15], v[154:157], v[178:181], v[12:15]
	v_mfma_f32_16x16x32_bf16 v[4:7], v[146:149], v[186:189], v[4:7]
	v_mfma_f32_16x16x32_bf16 v[0:3], v[154:157], v[186:189], v[0:3]
	v_mfma_f32_16x16x32_bf16 v[52:55], v[150:153], v[166:169], v[52:55]
	v_mfma_f32_16x16x32_bf16 v[44:47], v[158:161], v[166:169], v[44:47]
	v_mfma_f32_16x16x32_bf16 v[36:39], v[150:153], v[174:177], v[36:39]
	v_mfma_f32_16x16x32_bf16 v[28:31], v[158:161], v[174:177], v[28:31]
	v_mfma_f32_16x16x32_bf16 v[20:23], v[150:153], v[182:185], v[20:23]
	v_mfma_f32_16x16x32_bf16 v[12:15], v[158:161], v[182:185], v[12:15]
	v_mfma_f32_16x16x32_bf16 v[4:7], v[150:153], v[190:193], v[4:7]
	v_mfma_f32_16x16x32_bf16 v[0:3], v[158:161], v[190:193], v[0:3]
	s_barrier
	s_add_i32 s49, s49, 2
	s_add_u32 s45, s45, 0x100
	s_addc_u32 s48, s48, 0
	s_cmp_gt_u32 s49, 41
	s_mov_b64 s[12:13], s[14:15]
	s_cbranch_scc0 .LBB0_1242
	s_and_b64 vcc, exec, s[8:9]
	s_cbranch_vccz .LBB0_1245
	s_barrier

; #define PG8_STAGE(bufoff, gbase, voff) do { _Pragma("unroll") for (int _i = 0; _i < 2; ++_i) \
;         __builtin_amdgcn_global_load_lds((const unsigned*)((const char*)(gbase) + (voff)[_i]), (LAS unsigned*)(lds + (bufoff) + ldsw + _i * 8192), 16, 0, 0); } while (0)
; #define PG8_LDA(dst, b, h) do { _Pragma("unroll") for (int m = 0; m < 4; ++m) _Pragma("unroll") for (int k = 0; k < 2; ++k) dst[m][k] = *(const LAS bf16x8*)(lds + PG8_SA(b, h) + aoff + m * 2048 + k * 1024); } while (0)
; #define PG8_LDB(dst, b, h) do { _Pragma("unroll") for (int n = 0; n < 2; ++n) _Pragma("unroll") for (int k = 0; k < 2; ++k) dst[n][k] = *(const LAS bf16x8*)(lds + PG8_SB(b, h) + boff + n * 2048 + k * 1024); } while (0)
; #define PG8_MMA(ai, bj, At, Bt) do { __builtin_amdgcn_s_setprio(1); _Pragma("unroll") for (int m = 0; m < 4; ++m) _Pragma("unroll") for (int n = 0; n < 2; ++n) _Pragma("unroll") for (int k = 0; k < 2; ++k) \
;         acc[ai][bj][m][n] = __builtin_amdgcn_mfma_f32_16x16x32_bf16(Bt[n][k], At[m][k], acc[ai][bj][m][n], 0, 0, 0); __builtin_amdgcn_s_setprio(0); } while (0)
; #define PG8_WAIT_V(n) asm volatile("s_waitcnt vmcnt(" #n ")" ::: "memory")
; #define PG8_WAIT_L(n) asm volatile("s_waitcnt lgkmcnt(" #n ")" ::: "memory")
; #define PG8_BAR __builtin_amdgcn_s_barrier()
; #define PG8_SCHED __builtin_amdgcn_sched_barrier(0)
; template <class Epi, class Sched>
; __device__ __forceinline__ void gemm_phase(LAS unsigned char* lds, const Gemm g, const Sched& S, const Epi& E) {
;     ...
;         for (int t = 0; t < nt; t += 2) {
;             const bool last = (t == nt - 2);
;             const char* a1 = cA + (size_t)(t + 1) * kstep;
;             const char* a2 = last ? nA : cA + (size_t)(t + 2) * kstep; const char* b2 = last ? nB : cB + (size_t)(t + 2) * kstep;
;             const char* a3 = a2 + kstep; const char* b3 = b2 + kstep;
;             PG8_LDB(B0, 0, 0); PG8_LDB(B1, 0, 1); PG8_SCHED; PG8_LDA(At, 0, 0); PG8_STAGE(PG8_SA(1, 1), a1 + hstepA, voffA);
;             PG8_WAIT_V(8); PG8_WAIT_L(0); PG8_BAR; PG8_MMA(0, 0, At, B0); PG8_MMA(0, 1, At, B1); PG8_BAR; PG8_SCHED;
;             PG8_LDA(At, 0, 1); PG8_STAGE(PG8_SB(0, 0), b2, voffB); PG8_STAGE(PG8_SB(0, 1), b2 + hstepB, voffB); PG8_STAGE(PG8_SA(0, 0), a2, voffA);
;             PG8_WAIT_V(8); PG8_WAIT_L(0); PG8_BAR; PG8_MMA(1, 0, At, B0); PG8_MMA(1, 1, At, B1); PG8_BAR; PG8_SCHED;
.LBB0_1275:
	s_add_u32 s0, s16, 0x100
	s_addc_u32 s1, s17, 0
	s_add_i32 s52, 0, 0x10000
	s_cmp_eq_u32 s51, 40
	s_cselect_b32 s21, s13, s1
	s_cselect_b32 s20, s12, s0
	v_add_u32_e32 v96, s52, v231
	s_cselect_b32 s19, s15, s50
	s_cselect_b32 s18, s14, s49
	s_add_i32 s53, 0, 0x14000
	ds_read_b128 v[118:121], v96
	ds_read_b128 v[126:129], v96 offset:1024
	ds_read_b128 v[134:137], v96 offset:2048
	ds_read_b128 v[138:141], v96 offset:3072
	v_add_u32_e32 v96, s53, v231
	ds_read_b128 v[146:149], v96
	ds_read_b128 v[150:153], v96 offset:1024
	ds_read_b128 v[154:157], v96 offset:2048
	ds_read_b128 v[158:161], v96 offset:3072
	v_lshl_add_u64 v[218:219], s[16:17], 0, v[216:217]
	s_add_i32 m0, s25, 0xc000
	ds_read_b128 v[162:165], v232
	ds_read_b128 v[166:169], v232 offset:1024
	ds_read_b128 v[170:173], v232 offset:2048
	ds_read_b128 v[174:177], v232 offset:3072
	ds_read_b128 v[178:181], v232 offset:4096
	ds_read_b128 v[182:185], v232 offset:5120
	ds_read_b128 v[186:189], v232 offset:6144
	ds_read_b128 v[190:193], v232 offset:7168
	global_load_lds_dwordx4 v[218:219], off
	v_lshl_add_u64 v[218:219], s[16:17], 0, v[214:215]
	s_add_i32 m0, s25, 0xe000
	s_nop 0
	global_load_lds_dwordx4 v[218:219], off
	s_waitcnt vmcnt(8)
	s_waitcnt lgkmcnt(0)
	s_barrier
	s_waitcnt lgkmcnt(0)
	v_mfma_f32_16x16x32_bf16 v[142:145], v[118:121], v[162:165], v[142:145]
	v_mfma_f32_16x16x32_bf16 v[130:133], v[134:137], v[162:165], v[130:133]
	v_mfma_f32_16x16x32_bf16 v[110:113], v[118:121], v[170:173], v[110:113]
	v_mfma_f32_16x16x32_bf16 v[106:109], v[134:137], v[170:173], v[106:109]
	v_mfma_f32_16x16x32_bf16 v[92:95], v[118:121], v[178:181], v[92:95]
	v_mfma_f32_16x16x32_bf16 v[88:91], v[134:137], v[178:181], v[88:91]
	v_mfma_f32_16x16x32_bf16 v[76:79], v[118:121], v[186:189], v[76:79]
	v_mfma_f32_16x16x32_bf16 v[72:75], v[134:137], v[186:189], v[72:75]
	v_mfma_f32_16x16x32_bf16 v[142:145], v[126:129], v[166:169], v[142:145]
	v_mfma_f32_16x16x32_bf16 v[130:133], v[138:141], v[166:169], v[130:133]
	v_mfma_f32_16x16x32_bf16 v[110:113], v[126:129], v[174:177], v[110:113]
	v_mfma_f32_16x16x32_bf16 v[106:109], v[138:141], v[174:177], v[106:109]
	v_mfma_f32_16x16x32_bf16 v[92:95], v[126:129], v[182:185], v[92:95]
	v_mfma_f32_16x16x32_bf16 v[88:91], v[138:141], v[182:185], v[88:91]
	v_mfma_f32_16x16x32_bf16 v[76:79], v[126:129], v[190:193], v[76:79]
	v_mfma_f32_16x16x32_bf16 v[72:75], v[138:141], v[190:193], v[72:75]
	v_mfma_f32_16x16x32_bf16 v[122:125], v[146:149], v[162:165], v[122:125]
	v_mfma_f32_16x16x32_bf16 v[114:117], v[154:157], v[162:165], v[114:117]
	v_mfma_f32_16x16x32_bf16 v[102:105], v[146:149], v[170:173], v[102:105]
	v_mfma_f32_16x16x32_bf16 v[98:101], v[154:157], v[170:173], v[98:101]
	v_mfma_f32_16x16x32_bf16 v[84:87], v[146:149], v[178:181], v[84:87]
	v_mfma_f32_16x16x32_bf16 v[80:83], v[154:157], v[178:181], v[80:83]
	v_mfma_f32_16x16x32_bf16 v[68:71], v[146:149], v[186:189], v[68:71]
	v_mfma_f32_16x16x32_bf16 v[64:67], v[154:157], v[186:189], v[64:67]
	v_mfma_f32_16x16x32_bf16 v[122:125], v[150:153], v[166:169], v[122:125]
	v_mfma_f32_16x16x32_bf16 v[114:117], v[158:161], v[166:169], v[114:117]
	v_mfma_f32_16x16x32_bf16 v[102:105], v[150:153], v[174:177], v[102:105]
	v_mfma_f32_16x16x32_bf16 v[98:101], v[158:161], v[174:177], v[98:101]
	v_mfma_f32_16x16x32_bf16 v[84:87], v[150:153], v[182:185], v[84:87]
	v_mfma_f32_16x16x32_bf16 v[80:83], v[158:161], v[182:185], v[80:83]
	v_mfma_f32_16x16x32_bf16 v[68:71], v[150:153], v[190:193], v[68:71]
	v_mfma_f32_16x16x32_bf16 v[64:67], v[158:161], v[190:193], v[64:67]
	s_barrier
	s_add_i32 s16, s52, s7
	v_lshl_add_u64 v[218:219], s[18:19], 0, v[210:211]
	s_mov_b32 m0, s16
	ds_read_b128 v[162:165], v232 offset:16384
	ds_read_b128 v[166:169], v232 offset:17408
	ds_read_b128 v[170:173], v232 offset:18432
	ds_read_b128 v[174:177], v232 offset:19456
	ds_read_b128 v[178:181], v232 offset:20480
	ds_read_b128 v[182:185], v232 offset:21504
	ds_read_b128 v[186:189], v232 offset:22528
	ds_read_b128 v[190:193], v232 offset:23552
	global_load_lds_dwordx4 v[218:219], off
	s_add_i32 m0, s16, 0x2000
	s_add_u32 s16, s18, 0xb0000
	v_lshl_add_u64 v[220:221], s[18:19], 0, v[206:207]
	s_addc_u32 s17, s19, 0
	s_add_i32 s52, s53, s7
	global_load_lds_dwordx4 v[220:221], off
	v_lshl_add_u64 v[234:235], s[16:17], 0, v[210:211]
	s_mov_b32 m0, s52
	v_lshl_add_u64 v[236:237], s[20:21], 0, v[208:209]
	global_load_lds_dwordx4 v[234:235], off
	v_lshl_add_u64 v[234:235], s[16:17], 0, v[206:207]
	s_add_i32 m0, s52, 0x2000
	s_nop 0
	global_load_lds_dwordx4 v[234:235], off
	v_lshl_add_u64 v[234:235], s[20:21], 0, v[212:213]
	s_mov_b32 m0, s25
	s_nop 0
	global_load_lds_dwordx4 v[234:235], off
	s_mov_b32 m0, s27
	s_nop 0
	global_load_lds_dwordx4 v[236:237], off
	s_waitcnt vmcnt(8)
	s_waitcnt lgkmcnt(0)
	s_barrier
; #define PG8_STAGE(bufoff, gbase, voff) do { _Pragma("unroll") for (int _i = 0; _i < 2; ++_i) \
;         __builtin_amdgcn_global_load_lds((const unsigned*)((const char*)(gbase) + (voff)[_i]), (LAS unsigned*)(lds + (bufoff) + ldsw + _i * 8192), 16, 0, 0); } while (0)
; #define PG8_LDA(dst, b, h) do { _Pragma("unroll") for (int m = 0; m < 4; ++m) _Pragma("unroll") for (int k = 0; k < 2; ++k) dst[m][k] = *(const LAS bf16x8*)(lds + PG8_SA(b, h) + aoff + m * 2048 + k * 1024); } while (0)
; #define PG8_LDB(dst, b, h) do { _Pragma("unroll") for (int n = 0; n < 2; ++n) _Pragma("unroll") for (int k = 0; k < 2; ++k) dst[n][k] = *(const LAS bf16x8*)(lds + PG8_SB(b, h) + boff + n * 2048 + k * 1024); } while (0)
; #define PG8_MMA(ai, bj, At, Bt) do { __builtin_amdgcn_s_setprio(1); _Pragma("unroll") for (int m = 0; m < 4; ++m) _Pragma("unroll") for (int n = 0; n < 2; ++n) _Pragma("unroll") for (int k = 0; k < 2; ++k) \
;         acc[ai][bj][m][n] = __builtin_amdgcn_mfma_f32_16x16x32_bf16(Bt[n][k], At[m][k], acc[ai][bj][m][n], 0, 0, 0); __builtin_amdgcn_s_setprio(0); } while (0)
; #define PG8_WAIT_V(n) asm volatile("s_waitcnt vmcnt(" #n ")" ::: "memory")
; #define PG8_WAIT_L(n) asm volatile("s_waitcnt lgkmcnt(" #n ")" ::: "memory")
; #define PG8_BAR __builtin_amdgcn_s_barrier()
; #define PG8_SCHED __builtin_amdgcn_sched_barrier(0)
; template <class Epi, class Sched>
; __device__ __forceinline__ void gemm_phase(LAS unsigned char* lds, const Gemm g, const Sched& S, const Epi& E) {
;     ...
;             PG8_LDA(At, 0, 1); PG8_STAGE(PG8_SB(0, 0), b2, voffB); PG8_STAGE(PG8_SB(0, 1), b2 + hstepB, voffB); PG8_STAGE(PG8_SA(0, 0), a2, voffA);
;             PG8_WAIT_V(8); PG8_WAIT_L(0); PG8_BAR; PG8_MMA(1, 0, At, B0); PG8_MMA(1, 1, At, B1); PG8_BAR; PG8_SCHED;
;             PG8_LDB(B0, 1, 0); PG8_LDB(B1, 1, 1); PG8_SCHED; PG8_LDA(At, 1, 0); PG8_STAGE(PG8_SA(0, 1), a2 + hstepA, voffA);
;             PG8_WAIT_V(8); PG8_WAIT_L(0); PG8_BAR; PG8_MMA(0, 0, At, B0); PG8_MMA(0, 1, At, B1); PG8_BAR; PG8_SCHED;
;             PG8_LDA(At, 1, 1); PG8_STAGE(PG8_SB(1, 0), b3, voffB); PG8_STAGE(PG8_SB(1, 1), b3 + hstepB, voffB); PG8_STAGE(PG8_SA(1, 0), a3, voffA);
	s_waitcnt lgkmcnt(0)
	v_mfma_f32_16x16x32_bf16 v[60:63], v[118:121], v[162:165], v[60:63]
	v_mfma_f32_16x16x32_bf16 v[56:59], v[134:137], v[162:165], v[56:59]
	v_mfma_f32_16x16x32_bf16 v[44:47], v[118:121], v[170:173], v[44:47]
	v_mfma_f32_16x16x32_bf16 v[40:43], v[134:137], v[170:173], v[40:43]
	v_mfma_f32_16x16x32_bf16 v[28:31], v[118:121], v[178:181], v[28:31]
	v_mfma_f32_16x16x32_bf16 v[24:27], v[134:137], v[178:181], v[24:27]
	v_mfma_f32_16x16x32_bf16 v[12:15], v[118:121], v[186:189], v[12:15]
	v_mfma_f32_16x16x32_bf16 v[8:11], v[134:137], v[186:189], v[8:11]
	v_mfma_f32_16x16x32_bf16 v[60:63], v[126:129], v[166:169], v[60:63]
	v_mfma_f32_16x16x32_bf16 v[56:59], v[138:141], v[166:169], v[56:59]
	v_mfma_f32_16x16x32_bf16 v[44:47], v[126:129], v[174:177], v[44:47]
	v_mfma_f32_16x16x32_bf16 v[40:43], v[138:141], v[174:177], v[40:43]
	v_mfma_f32_16x16x32_bf16 v[28:31], v[126:129], v[182:185], v[28:31]
	v_mfma_f32_16x16x32_bf16 v[24:27], v[138:141], v[182:185], v[24:27]
	v_mfma_f32_16x16x32_bf16 v[12:15], v[126:129], v[190:193], v[12:15]
	v_mfma_f32_16x16x32_bf16 v[8:11], v[138:141], v[190:193], v[8:11]
	v_mfma_f32_16x16x32_bf16 v[52:55], v[146:149], v[162:165], v[52:55]
	v_mfma_f32_16x16x32_bf16 v[48:51], v[154:157], v[162:165], v[48:51]
	v_mfma_f32_16x16x32_bf16 v[36:39], v[146:149], v[170:173], v[36:39]
	v_mfma_f32_16x16x32_bf16 v[32:35], v[154:157], v[170:173], v[32:35]
	v_mfma_f32_16x16x32_bf16 v[20:23], v[146:149], v[178:181], v[20:23]
	v_mfma_f32_16x16x32_bf16 v[16:19], v[154:157], v[178:181], v[16:19]
	v_mfma_f32_16x16x32_bf16 v[4:7], v[146:149], v[186:189], v[4:7]
	v_mfma_f32_16x16x32_bf16 v[0:3], v[154:157], v[186:189], v[0:3]
	v_mfma_f32_16x16x32_bf16 v[52:55], v[150:153], v[166:169], v[52:55]
	v_mfma_f32_16x16x32_bf16 v[48:51], v[158:161], v[166:169], v[48:51]
	v_mfma_f32_16x16x32_bf16 v[36:39], v[150:153], v[174:177], v[36:39]
	v_mfma_f32_16x16x32_bf16 v[32:35], v[158:161], v[174:177], v[32:35]
	v_mfma_f32_16x16x32_bf16 v[20:23], v[150:153], v[182:185], v[20:23]
	v_mfma_f32_16x16x32_bf16 v[16:19], v[158:161], v[182:185], v[16:19]
	v_mfma_f32_16x16x32_bf16 v[4:7], v[150:153], v[190:193], v[4:7]
	v_mfma_f32_16x16x32_bf16 v[0:3], v[158:161], v[190:193], v[0:3]
	s_barrier
	s_add_i32 s52, 0, 0x18000
	v_add_u32_e32 v96, s52, v231
	s_add_i32 s53, 0, 0x1c000
	ds_read_b128 v[118:121], v96
	ds_read_b128 v[126:129], v96 offset:1024
	ds_read_b128 v[134:137], v96 offset:2048
	ds_read_b128 v[138:141], v96 offset:3072
	v_add_u32_e32 v96, s53, v231
	ds_read_b128 v[146:149], v96
	ds_read_b128 v[150:153], v96 offset:1024
	ds_read_b128 v[154:157], v96 offset:2048
	ds_read_b128 v[158:161], v96 offset:3072
	s_add_u32 s16, s20, 0xb0000
	s_addc_u32 s17, s21, 0
	s_mov_b32 m0, s29
	v_lshl_add_u64 v[238:239], s[16:17], 0, v[212:213]
	ds_read_b128 v[162:165], v232 offset:32768
	ds_read_b128 v[166:169], v232 offset:33792
	ds_read_b128 v[170:173], v232 offset:34816
	ds_read_b128 v[174:177], v232 offset:35840
	ds_read_b128 v[178:181], v232 offset:36864
	ds_read_b128 v[182:185], v232 offset:37888
	ds_read_b128 v[186:189], v232 offset:38912
	ds_read_b128 v[190:193], v232 offset:39936
	global_load_lds_dwordx4 v[238:239], off
	v_lshl_add_u64 v[238:239], s[16:17], 0, v[208:209]
	s_mov_b32 m0, s31
	s_nop 0
	global_load_lds_dwordx4 v[238:239], off
	s_waitcnt vmcnt(8)
	s_waitcnt lgkmcnt(0)
	s_barrier
	s_waitcnt lgkmcnt(0)
	v_mfma_f32_16x16x32_bf16 v[142:145], v[118:121], v[162:165], v[142:145]
	v_mfma_f32_16x16x32_bf16 v[130:133], v[134:137], v[162:165], v[130:133]
	v_mfma_f32_16x16x32_bf16 v[110:113], v[118:121], v[170:173], v[110:113]
	v_mfma_f32_16x16x32_bf16 v[106:109], v[134:137], v[170:173], v[106:109]
	v_mfma_f32_16x16x32_bf16 v[92:95], v[118:121], v[178:181], v[92:95]
	v_mfma_f32_16x16x32_bf16 v[88:91], v[134:137], v[178:181], v[88:91]
	v_mfma_f32_16x16x32_bf16 v[76:79], v[118:121], v[186:189], v[76:79]
	v_mfma_f32_16x16x32_bf16 v[72:75], v[134:137], v[186:189], v[72:75]
	v_mfma_f32_16x16x32_bf16 v[142:145], v[126:129], v[166:169], v[142:145]
	v_mfma_f32_16x16x32_bf16 v[130:133], v[138:141], v[166:169], v[130:133]
	v_mfma_f32_16x16x32_bf16 v[110:113], v[126:129], v[174:177], v[110:113]
	v_mfma_f32_16x16x32_bf16 v[106:109], v[138:141], v[174:177], v[106:109]
	v_mfma_f32_16x16x32_bf16 v[92:95], v[126:129], v[182:185], v[92:95]
	v_mfma_f32_16x16x32_bf16 v[88:91], v[138:141], v[182:185], v[88:91]
	v_mfma_f32_16x16x32_bf16 v[76:79], v[126:129], v[190:193], v[76:79]
	v_mfma_f32_16x16x32_bf16 v[72:75], v[138:141], v[190:193], v[72:75]
	v_mfma_f32_16x16x32_bf16 v[122:125], v[146:149], v[162:165], v[122:125]
	v_mfma_f32_16x16x32_bf16 v[114:117], v[154:157], v[162:165], v[114:117]
	v_mfma_f32_16x16x32_bf16 v[102:105], v[146:149], v[170:173], v[102:105]
	v_mfma_f32_16x16x32_bf16 v[98:101], v[154:157], v[170:173], v[98:101]
	v_mfma_f32_16x16x32_bf16 v[84:87], v[146:149], v[178:181], v[84:87]
	v_mfma_f32_16x16x32_bf16 v[80:83], v[154:157], v[178:181], v[80:83]
	v_mfma_f32_16x16x32_bf16 v[68:71], v[146:149], v[186:189], v[68:71]
	v_mfma_f32_16x16x32_bf16 v[64:67], v[154:157], v[186:189], v[64:67]
	v_mfma_f32_16x16x32_bf16 v[122:125], v[150:153], v[166:169], v[122:125]
	v_mfma_f32_16x16x32_bf16 v[114:117], v[158:161], v[166:169], v[114:117]
	v_mfma_f32_16x16x32_bf16 v[102:105], v[150:153], v[174:177], v[102:105]
	v_mfma_f32_16x16x32_bf16 v[98:101], v[158:161], v[174:177], v[98:101]
	v_mfma_f32_16x16x32_bf16 v[84:87], v[150:153], v[182:185], v[84:87]
	v_mfma_f32_16x16x32_bf16 v[80:83], v[158:161], v[182:185], v[80:83]
	v_mfma_f32_16x16x32_bf16 v[68:71], v[150:153], v[190:193], v[68:71]
	v_mfma_f32_16x16x32_bf16 v[64:67], v[158:161], v[190:193], v[64:67]
	s_barrier
; #define PG8_STAGE(bufoff, gbase, voff) do { _Pragma("unroll") for (int _i = 0; _i < 2; ++_i) \
;         __builtin_amdgcn_global_load_lds((const unsigned*)((const char*)(gbase) + (voff)[_i]), (LAS unsigned*)(lds + (bufoff) + ldsw + _i * 8192), 16, 0, 0); } while (0)
; #define PG8_LDA(dst, b, h) do { _Pragma("unroll") for (int m = 0; m < 4; ++m) _Pragma("unroll") for (int k = 0; k < 2; ++k) dst[m][k] = *(const LAS bf16x8*)(lds + PG8_SA(b, h) + aoff + m * 2048 + k * 1024); } while (0)
; #define PG8_MMA(ai, bj, At, Bt) do { __builtin_amdgcn_s_setprio(1); _Pragma("unroll") for (int m = 0; m < 4; ++m) _Pragma("unroll") for (int n = 0; n < 2; ++n) _Pragma("unroll") for (int k = 0; k < 2; ++k) \
;         acc[ai][bj][m][n] = __builtin_amdgcn_mfma_f32_16x16x32_bf16(Bt[n][k], At[m][k], acc[ai][bj][m][n], 0, 0, 0); __builtin_amdgcn_s_setprio(0); } while (0)
; #define PG8_WAIT_V(n) asm volatile("s_waitcnt vmcnt(" #n ")" ::: "memory")
; #define PG8_WAIT_L(n) asm volatile("s_waitcnt lgkmcnt(" #n ")" ::: "memory")
; #define PG8_BAR __builtin_amdgcn_s_barrier()
; #define PG8_SCHED __builtin_amdgcn_sched_barrier(0)
; template <class Epi, class Sched>
; __device__ __forceinline__ void gemm_phase(LAS unsigned char* lds, const Gemm g, const Sched& S, const Epi& E) {
;     ...
;             PG8_LDA(At, 1, 1); PG8_STAGE(PG8_SB(1, 0), b3, voffB); PG8_STAGE(PG8_SB(1, 1), b3 + hstepB, voffB); PG8_STAGE(PG8_SA(1, 0), a3, voffA);
;             PG8_WAIT_V(8); PG8_WAIT_L(0); PG8_BAR; PG8_MMA(1, 0, At, B0); PG8_MMA(1, 1, At, B1); PG8_BAR; PG8_SCHED;
;         }
;         if (wr == 0) PG8_BAR;
	s_add_i32 s16, s52, s7
	v_lshl_add_u64 v[218:219], v[218:219], 0, s[4:5]
	s_mov_b32 m0, s16
	ds_read_b128 v[162:165], v232 offset:49152
	ds_read_b128 v[166:169], v232 offset:50176
	ds_read_b128 v[170:173], v232 offset:51200
	ds_read_b128 v[174:177], v232 offset:52224
	ds_read_b128 v[178:181], v232 offset:53248
	ds_read_b128 v[182:185], v232 offset:54272
	ds_read_b128 v[186:189], v232 offset:55296
	ds_read_b128 v[190:193], v232 offset:56320
	global_load_lds_dwordx4 v[218:219], off
	s_add_i32 m0, s16, 0x2000
	s_add_u32 s16, s18, 0xb0080
	v_lshl_add_u64 v[218:219], v[220:221], 0, s[4:5]
	s_addc_u32 s17, s19, 0
	s_add_i32 s18, s53, s7
	global_load_lds_dwordx4 v[218:219], off
	v_lshl_add_u64 v[218:219], s[16:17], 0, v[210:211]
	s_mov_b32 m0, s18
	s_nop 0
	global_load_lds_dwordx4 v[218:219], off
	v_lshl_add_u64 v[218:219], s[16:17], 0, v[206:207]
	s_add_i32 m0, s18, 0x2000
	s_nop 0
	global_load_lds_dwordx4 v[218:219], off
	v_lshl_add_u64 v[218:219], v[234:235], 0, s[4:5]
	s_mov_b32 m0, s40
	s_nop 0
	global_load_lds_dwordx4 v[218:219], off
	v_lshl_add_u64 v[218:219], v[236:237], 0, s[4:5]
	s_mov_b32 m0, s41
	s_nop 0
	global_load_lds_dwordx4 v[218:219], off
	s_waitcnt vmcnt(8)
	s_waitcnt lgkmcnt(0)
	s_barrier
	s_waitcnt lgkmcnt(0)
	v_mfma_f32_16x16x32_bf16 v[60:63], v[118:121], v[162:165], v[60:63]
	v_mfma_f32_16x16x32_bf16 v[56:59], v[134:137], v[162:165], v[56:59]
	v_mfma_f32_16x16x32_bf16 v[44:47], v[118:121], v[170:173], v[44:47]
	v_mfma_f32_16x16x32_bf16 v[40:43], v[134:137], v[170:173], v[40:43]
	v_mfma_f32_16x16x32_bf16 v[28:31], v[118:121], v[178:181], v[28:31]
	v_mfma_f32_16x16x32_bf16 v[24:27], v[134:137], v[178:181], v[24:27]
	v_mfma_f32_16x16x32_bf16 v[12:15], v[118:121], v[186:189], v[12:15]
	v_mfma_f32_16x16x32_bf16 v[8:11], v[134:137], v[186:189], v[8:11]
	v_mfma_f32_16x16x32_bf16 v[60:63], v[126:129], v[166:169], v[60:63]
	v_mfma_f32_16x16x32_bf16 v[56:59], v[138:141], v[166:169], v[56:59]
	v_mfma_f32_16x16x32_bf16 v[44:47], v[126:129], v[174:177], v[44:47]
	v_mfma_f32_16x16x32_bf16 v[40:43], v[138:141], v[174:177], v[40:43]
	v_mfma_f32_16x16x32_bf16 v[28:31], v[126:129], v[182:185], v[28:31]
	v_mfma_f32_16x16x32_bf16 v[24:27], v[138:141], v[182:185], v[24:27]
	v_mfma_f32_16x16x32_bf16 v[12:15], v[126:129], v[190:193], v[12:15]
	v_mfma_f32_16x16x32_bf16 v[8:11], v[138:141], v[190:193], v[8:11]
	v_mfma_f32_16x16x32_bf16 v[52:55], v[146:149], v[162:165], v[52:55]
	v_mfma_f32_16x16x32_bf16 v[48:51], v[154:157], v[162:165], v[48:51]
	v_mfma_f32_16x16x32_bf16 v[36:39], v[146:149], v[170:173], v[36:39]
	v_mfma_f32_16x16x32_bf16 v[32:35], v[154:157], v[170:173], v[32:35]
	v_mfma_f32_16x16x32_bf16 v[20:23], v[146:149], v[178:181], v[20:23]
	v_mfma_f32_16x16x32_bf16 v[16:19], v[154:157], v[178:181], v[16:19]
	v_mfma_f32_16x16x32_bf16 v[4:7], v[146:149], v[186:189], v[4:7]
	v_mfma_f32_16x16x32_bf16 v[0:3], v[154:157], v[186:189], v[0:3]
	v_mfma_f32_16x16x32_bf16 v[52:55], v[150:153], v[166:169], v[52:55]
	v_mfma_f32_16x16x32_bf16 v[48:51], v[158:161], v[166:169], v[48:51]
	v_mfma_f32_16x16x32_bf16 v[36:39], v[150:153], v[174:177], v[36:39]
	v_mfma_f32_16x16x32_bf16 v[32:35], v[158:161], v[174:177], v[32:35]
	v_mfma_f32_16x16x32_bf16 v[20:23], v[150:153], v[182:185], v[20:23]
	v_mfma_f32_16x16x32_bf16 v[16:19], v[158:161], v[182:185], v[16:19]
	v_mfma_f32_16x16x32_bf16 v[4:7], v[150:153], v[190:193], v[4:7]
	v_mfma_f32_16x16x32_bf16 v[0:3], v[158:161], v[190:193], v[0:3]
	s_barrier
	s_add_i32 s51, s51, 2
	s_add_u32 s49, s49, 0x100
	s_addc_u32 s50, s50, 0
	s_cmp_gt_u32 s51, 41
	s_mov_b64 s[16:17], s[0:1]
	s_cbranch_scc0 .LBB0_1275
	s_and_b64 vcc, exec, s[10:11]
	s_cbranch_vccz .LBB0_1278
	s_barrier
